# v21 + K-loop back-edge rotation (guide 7.11): loop-counter / address-increment / exit-compare SALU moved from behind the last closing barrier to the tail of the last load segment; only the branch stay
# speedup vs baseline: 1.0096x; 1.0096x over previous
; #define PG8_STAGE(bufoff, gbase, voff) do { _Pragma("unroll") for (int _i = 0; _i < 2; ++_i) \
;         __builtin_amdgcn_global_load_lds((const unsigned*)((const char*)(gbase) + (voff)[_i]), (PG8_LAS unsigned*)(lds + (bufoff) + ldsw + _i * 8192), 16, 0, 0); } while (0)
; #define PG8_WAIT_V(n) asm volatile("s_waitcnt vmcnt(" #n ")" ::: "memory")
; #define PG8_WAIT_L(n) asm volatile("s_waitcnt lgkmcnt(" #n ")" ::: "memory")
; #define PG8_BAR __builtin_amdgcn_s_barrier()
; #define PG8_SCHED __builtin_amdgcn_sched_barrier(0)
;     __device__ __forceinline__ int nt(const pg8::Unit& u) const { return u.kind == 0 ? ntiles : q_nt(u.kind - 1); }
; template <class Epi, class Sched, bool ALIGN_EPI = true, bool SP2 = true>
; __device__ __forceinline__ void gemm_phase(PG8_LAS unsigned char* lds, const int K  , const Sched& S, const Epi& E) {
;     ...
;             const bool last = (t == nt - 2);
;             const char* a1 = cA + (size_t)(t + 1) * kstep;
;             const char* a2 = last ? nA : cA + (size_t)(t + 2) * kstep; const char* b2 = last ? nB : cB + (size_t)(t + 2) * kstep;
;             const char* a3 = a2 + kstep; const char* b3 = b2 + kstep;
;             if constexpr (SP2) {
;             PG8_LDB(B0, 0, 0); PG8_LDB(B1, 0, 1); PG8_SCHED; PG8_LDA(At, 0, 0); PG8_STAGE(PG8_SA(1, 1), a1 + hstep, voffA);
;             PG8_WAIT_V(8); PG8_WAIT_L(0); PG8_BAR; PG8_MMA(0, 0, At, B0); PG8_MMA(0, 1, At, B1); PG8_BAR; PG8_SCHED;
;             PG8_LDA(At, 0, 1); PG8_STAGE(PG8_SB(0, 0), b2, voffB); PG8_STAGE(PG8_SB(0, 1), b2 + hstep, voffB); PG8_STAGE(PG8_SA(0, 0), a2, voffA);
;             PG8_WAIT_V(8); PG8_WAIT_L(0); PG8_BAR; PG8_MMA(1, 0, At, B0); PG8_MMA(1, 1, At, B1); PG8_BAR; PG8_SCHED;
.LBB0_219:
	ds_read_b128 v[148:151], v154
	ds_read_b128 v[160:163], v154 offset:1024
	ds_read_b128 v[164:167], v154 offset:2048
	ds_read_b128 v[168:171], v154 offset:3072
	ds_read_b128 v[172:175], v155
	ds_read_b128 v[176:179], v155 offset:1024
	ds_read_b128 v[180:183], v155 offset:2048
	ds_read_b128 v[184:187], v155 offset:3072
	s_add_u32 s22, s20, 0xfff80080
	s_addc_u32 s23, s21, -1
	s_cmp_eq_u32 s48, 28
	s_cselect_b32 s25, s13, s23
	s_cselect_b32 s24, s44, s22
	s_cselect_b32 s23, s11, s47
	s_cselect_b32 s22, s45, s46
	v_lshl_add_u64 v[220:221], s[20:21], 0, v[140:141]
	s_add_i32 m0, s19, 0xc000
	ds_read_b128 v[188:191], v156
	ds_read_b128 v[192:195], v156 offset:1024
	ds_read_b128 v[196:199], v156 offset:2048
	ds_read_b128 v[200:203], v156 offset:3072
	ds_read_b128 v[204:207], v156 offset:4096
	ds_read_b128 v[208:211], v156 offset:5120
	ds_read_b128 v[212:215], v156 offset:6144
	ds_read_b128 v[216:219], v156 offset:7168
	global_load_lds_dwordx4 v[220:221], off
	v_lshl_add_u64 v[220:221], s[20:21], 0, v[142:143]
	s_add_i32 m0, s19, 0xe000
	s_nop 0
	global_load_lds_dwordx4 v[220:221], off
	s_waitcnt vmcnt(8)
	s_waitcnt lgkmcnt(0)
	s_setprio 1
	s_barrier
	v_mfma_f32_16x16x32_bf16 v[126:129], v[148:151], v[188:191], v[126:129]
	v_mfma_f32_16x16x32_bf16 v[118:121], v[164:167], v[188:191], v[118:121]
	v_mfma_f32_16x16x32_bf16 v[110:113], v[148:151], v[196:199], v[110:113]
	v_mfma_f32_16x16x32_bf16 v[102:105], v[164:167], v[196:199], v[102:105]
	v_mfma_f32_16x16x32_bf16 v[94:97], v[148:151], v[204:207], v[94:97]
	v_mfma_f32_16x16x32_bf16 v[86:89], v[164:167], v[204:207], v[86:89]
	v_mfma_f32_16x16x32_bf16 v[78:81], v[148:151], v[212:215], v[78:81]
	v_mfma_f32_16x16x32_bf16 v[70:73], v[164:167], v[212:215], v[70:73]
	v_mfma_f32_16x16x32_bf16 v[126:129], v[160:163], v[192:195], v[126:129]
	v_mfma_f32_16x16x32_bf16 v[118:121], v[168:171], v[192:195], v[118:121]
	v_mfma_f32_16x16x32_bf16 v[110:113], v[160:163], v[200:203], v[110:113]
	v_mfma_f32_16x16x32_bf16 v[102:105], v[168:171], v[200:203], v[102:105]
	v_mfma_f32_16x16x32_bf16 v[94:97], v[160:163], v[208:211], v[94:97]
	v_mfma_f32_16x16x32_bf16 v[86:89], v[168:171], v[208:211], v[86:89]
	v_mfma_f32_16x16x32_bf16 v[78:81], v[160:163], v[216:219], v[78:81]
	v_mfma_f32_16x16x32_bf16 v[70:73], v[168:171], v[216:219], v[70:73]
	s_setprio 0
	s_setprio 1
	v_mfma_f32_16x16x32_bf16 v[122:125], v[172:175], v[188:191], v[122:125]
	v_mfma_f32_16x16x32_bf16 v[114:117], v[180:183], v[188:191], v[114:117]
	v_mfma_f32_16x16x32_bf16 v[106:109], v[172:175], v[196:199], v[106:109]
	v_mfma_f32_16x16x32_bf16 v[98:101], v[180:183], v[196:199], v[98:101]
	v_mfma_f32_16x16x32_bf16 v[90:93], v[172:175], v[204:207], v[90:93]
	v_mfma_f32_16x16x32_bf16 v[82:85], v[180:183], v[204:207], v[82:85]
	v_mfma_f32_16x16x32_bf16 v[74:77], v[172:175], v[212:215], v[74:77]
	v_mfma_f32_16x16x32_bf16 v[66:69], v[180:183], v[212:215], v[66:69]
	v_mfma_f32_16x16x32_bf16 v[122:125], v[176:179], v[192:195], v[122:125]
	v_mfma_f32_16x16x32_bf16 v[114:117], v[184:187], v[192:195], v[114:117]
	v_mfma_f32_16x16x32_bf16 v[106:109], v[176:179], v[200:203], v[106:109]
	v_mfma_f32_16x16x32_bf16 v[98:101], v[184:187], v[200:203], v[98:101]
	v_mfma_f32_16x16x32_bf16 v[90:93], v[176:179], v[208:211], v[90:93]
	v_mfma_f32_16x16x32_bf16 v[82:85], v[184:187], v[208:211], v[82:85]
	v_mfma_f32_16x16x32_bf16 v[74:77], v[176:179], v[216:219], v[74:77]
	v_mfma_f32_16x16x32_bf16 v[66:69], v[184:187], v[216:219], v[66:69]
	s_barrier
	s_setprio 0
	s_add_i32 s49, s39, s29
	v_lshl_add_u64 v[220:221], s[22:23], 0, v[136:137]
	s_mov_b32 m0, s49
	ds_read_b128 v[188:191], v156 offset:16384
	ds_read_b128 v[192:195], v156 offset:17408
	ds_read_b128 v[196:199], v156 offset:18432
	ds_read_b128 v[200:203], v156 offset:19456
	ds_read_b128 v[204:207], v156 offset:20480
	ds_read_b128 v[208:211], v156 offset:21504
	ds_read_b128 v[212:215], v156 offset:22528
	ds_read_b128 v[216:219], v156 offset:23552
	global_load_lds_dwordx4 v[220:221], off
	s_add_i32 m0, s49, 0x2000
	s_add_u32 s50, s22, 0x80000
	v_lshl_add_u64 v[222:223], s[22:23], 0, v[132:133]
	s_addc_u32 s51, s23, 0
	s_add_i32 s49, s40, s29
	global_load_lds_dwordx4 v[222:223], off
	v_lshl_add_u64 v[224:225], s[50:51], 0, v[136:137]
	s_mov_b32 m0, s49
	v_lshl_add_u64 v[226:227], s[24:25], 0, v[134:135]
	global_load_lds_dwordx4 v[224:225], off
	v_lshl_add_u64 v[224:225], s[50:51], 0, v[132:133]
	s_add_i32 m0, s49, 0x2000
	s_nop 0
	global_load_lds_dwordx4 v[224:225], off
	v_lshl_add_u64 v[224:225], s[24:25], 0, v[138:139]
	s_mov_b32 m0, s19
	s_nop 0
	global_load_lds_dwordx4 v[224:225], off
	s_mov_b32 m0, s31
	s_nop 0
	global_load_lds_dwordx4 v[226:227], off
	s_waitcnt vmcnt(8)
	s_waitcnt lgkmcnt(0)
	s_setprio 1
	s_barrier
; #define PG8_STAGE(bufoff, gbase, voff) do { _Pragma("unroll") for (int _i = 0; _i < 2; ++_i) \
;         __builtin_amdgcn_global_load_lds((const unsigned*)((const char*)(gbase) + (voff)[_i]), (PG8_LAS unsigned*)(lds + (bufoff) + ldsw + _i * 8192), 16, 0, 0); } while (0)
; #define PG8_WAIT_V(n) asm volatile("s_waitcnt vmcnt(" #n ")" ::: "memory")
; #define PG8_WAIT_L(n) asm volatile("s_waitcnt lgkmcnt(" #n ")" ::: "memory")
; #define PG8_BAR __builtin_amdgcn_s_barrier()
; #define PG8_SCHED __builtin_amdgcn_sched_barrier(0)
; template <class Epi, class Sched, bool ALIGN_EPI = true, bool SP2 = true>
; __device__ __forceinline__ void gemm_phase(PG8_LAS unsigned char* lds, const int K  , const Sched& S, const Epi& E) {
;     ...
;             PG8_WAIT_V(8); PG8_WAIT_L(0); PG8_BAR; PG8_MMA(1, 0, At, B0); PG8_MMA(1, 1, At, B1); PG8_BAR; PG8_SCHED;
;             PG8_LDB(B0, 1, 0); PG8_LDB(B1, 1, 1); PG8_SCHED; PG8_LDA(At, 1, 0); PG8_STAGE(PG8_SA(0, 1), a2 + hstep, voffA);
;             PG8_WAIT_V(8); PG8_WAIT_L(0); PG8_BAR; PG8_MMA(0, 0, At, B0); PG8_MMA(0, 1, At, B1); PG8_BAR; PG8_SCHED;
	v_mfma_f32_16x16x32_bf16 v[62:65], v[148:151], v[188:191], v[62:65]
	v_mfma_f32_16x16x32_bf16 v[54:57], v[164:167], v[188:191], v[54:57]
	v_mfma_f32_16x16x32_bf16 v[46:49], v[148:151], v[196:199], v[46:49]
	v_mfma_f32_16x16x32_bf16 v[38:41], v[164:167], v[196:199], v[38:41]
	v_mfma_f32_16x16x32_bf16 v[30:33], v[148:151], v[204:207], v[30:33]
	v_mfma_f32_16x16x32_bf16 v[22:25], v[164:167], v[204:207], v[22:25]
	v_mfma_f32_16x16x32_bf16 v[14:17], v[148:151], v[212:215], v[14:17]
	v_mfma_f32_16x16x32_bf16 v[6:9], v[164:167], v[212:215], v[6:9]
	v_mfma_f32_16x16x32_bf16 v[62:65], v[160:163], v[192:195], v[62:65]
	v_mfma_f32_16x16x32_bf16 v[54:57], v[168:171], v[192:195], v[54:57]
	v_mfma_f32_16x16x32_bf16 v[46:49], v[160:163], v[200:203], v[46:49]
	v_mfma_f32_16x16x32_bf16 v[38:41], v[168:171], v[200:203], v[38:41]
	v_mfma_f32_16x16x32_bf16 v[30:33], v[160:163], v[208:211], v[30:33]
	v_mfma_f32_16x16x32_bf16 v[22:25], v[168:171], v[208:211], v[22:25]
	v_mfma_f32_16x16x32_bf16 v[14:17], v[160:163], v[216:219], v[14:17]
	v_mfma_f32_16x16x32_bf16 v[6:9], v[168:171], v[216:219], v[6:9]
	s_setprio 0
	s_setprio 1
	v_mfma_f32_16x16x32_bf16 v[58:61], v[172:175], v[188:191], v[58:61]
	v_mfma_f32_16x16x32_bf16 v[50:53], v[180:183], v[188:191], v[50:53]
	v_mfma_f32_16x16x32_bf16 v[42:45], v[172:175], v[196:199], v[42:45]
	v_mfma_f32_16x16x32_bf16 v[34:37], v[180:183], v[196:199], v[34:37]
	v_mfma_f32_16x16x32_bf16 v[26:29], v[172:175], v[204:207], v[26:29]
	v_mfma_f32_16x16x32_bf16 v[18:21], v[180:183], v[204:207], v[18:21]
	v_mfma_f32_16x16x32_bf16 v[10:13], v[172:175], v[212:215], v[10:13]
	v_mfma_f32_16x16x32_bf16 v[2:5], v[180:183], v[212:215], v[2:5]
	v_mfma_f32_16x16x32_bf16 v[58:61], v[176:179], v[192:195], v[58:61]
	v_mfma_f32_16x16x32_bf16 v[50:53], v[184:187], v[192:195], v[50:53]
	v_mfma_f32_16x16x32_bf16 v[42:45], v[176:179], v[200:203], v[42:45]
	v_mfma_f32_16x16x32_bf16 v[34:37], v[184:187], v[200:203], v[34:37]
	v_mfma_f32_16x16x32_bf16 v[26:29], v[176:179], v[208:211], v[26:29]
	v_mfma_f32_16x16x32_bf16 v[18:21], v[184:187], v[208:211], v[18:21]
	v_mfma_f32_16x16x32_bf16 v[10:13], v[176:179], v[216:219], v[10:13]
	v_mfma_f32_16x16x32_bf16 v[2:5], v[184:187], v[216:219], v[2:5]
	s_barrier
	s_setprio 0
	s_add_i32 s49, 0, 0x18000
	v_add_u32_e32 v159, s49, v152
	s_add_i32 s50, 0, 0x1c000
	ds_read_b128 v[148:151], v159
	ds_read_b128 v[160:163], v159 offset:1024
	ds_read_b128 v[164:167], v159 offset:2048
	ds_read_b128 v[168:171], v159 offset:3072
	v_add_u32_e32 v159, s50, v152
	ds_read_b128 v[172:175], v159
	ds_read_b128 v[176:179], v159 offset:1024
	ds_read_b128 v[180:183], v159 offset:2048
	ds_read_b128 v[184:187], v159 offset:3072
	s_add_u32 s24, s24, 0x80000
	s_addc_u32 s25, s25, 0
	s_mov_b32 m0, s33
	v_lshl_add_u64 v[230:231], s[24:25], 0, v[138:139]
	ds_read_b128 v[188:191], v156 offset:32768
	ds_read_b128 v[192:195], v156 offset:33792
	ds_read_b128 v[196:199], v156 offset:34816
	ds_read_b128 v[200:203], v156 offset:35840
	ds_read_b128 v[204:207], v156 offset:36864
	ds_read_b128 v[208:211], v156 offset:37888
	ds_read_b128 v[212:215], v156 offset:38912
	ds_read_b128 v[216:219], v156 offset:39936
	global_load_lds_dwordx4 v[230:231], off
	v_lshl_add_u64 v[230:231], s[24:25], 0, v[134:135]
	s_mov_b32 m0, s34
	s_nop 0
	global_load_lds_dwordx4 v[230:231], off
	s_waitcnt vmcnt(8)
	s_waitcnt lgkmcnt(0)
	s_setprio 1
	s_barrier
	v_mfma_f32_16x16x32_bf16 v[126:129], v[148:151], v[188:191], v[126:129]
	v_mfma_f32_16x16x32_bf16 v[118:121], v[164:167], v[188:191], v[118:121]
	v_mfma_f32_16x16x32_bf16 v[110:113], v[148:151], v[196:199], v[110:113]
	v_mfma_f32_16x16x32_bf16 v[102:105], v[164:167], v[196:199], v[102:105]
	v_mfma_f32_16x16x32_bf16 v[94:97], v[148:151], v[204:207], v[94:97]
	v_mfma_f32_16x16x32_bf16 v[86:89], v[164:167], v[204:207], v[86:89]
	v_mfma_f32_16x16x32_bf16 v[78:81], v[148:151], v[212:215], v[78:81]
	v_mfma_f32_16x16x32_bf16 v[70:73], v[164:167], v[212:215], v[70:73]
	v_mfma_f32_16x16x32_bf16 v[126:129], v[160:163], v[192:195], v[126:129]
	v_mfma_f32_16x16x32_bf16 v[118:121], v[168:171], v[192:195], v[118:121]
	v_mfma_f32_16x16x32_bf16 v[110:113], v[160:163], v[200:203], v[110:113]
	v_mfma_f32_16x16x32_bf16 v[102:105], v[168:171], v[200:203], v[102:105]
	v_mfma_f32_16x16x32_bf16 v[94:97], v[160:163], v[208:211], v[94:97]
	v_mfma_f32_16x16x32_bf16 v[86:89], v[168:171], v[208:211], v[86:89]
	v_mfma_f32_16x16x32_bf16 v[78:81], v[160:163], v[216:219], v[78:81]
	v_mfma_f32_16x16x32_bf16 v[70:73], v[168:171], v[216:219], v[70:73]
	s_setprio 0
	s_setprio 1
	v_mfma_f32_16x16x32_bf16 v[122:125], v[172:175], v[188:191], v[122:125]
	v_mfma_f32_16x16x32_bf16 v[114:117], v[180:183], v[188:191], v[114:117]
	v_mfma_f32_16x16x32_bf16 v[106:109], v[172:175], v[196:199], v[106:109]
	v_mfma_f32_16x16x32_bf16 v[98:101], v[180:183], v[196:199], v[98:101]
	v_mfma_f32_16x16x32_bf16 v[90:93], v[172:175], v[204:207], v[90:93]
	v_mfma_f32_16x16x32_bf16 v[82:85], v[180:183], v[204:207], v[82:85]
	v_mfma_f32_16x16x32_bf16 v[74:77], v[172:175], v[212:215], v[74:77]
	v_mfma_f32_16x16x32_bf16 v[66:69], v[180:183], v[212:215], v[66:69]
	v_mfma_f32_16x16x32_bf16 v[122:125], v[176:179], v[192:195], v[122:125]
	v_mfma_f32_16x16x32_bf16 v[114:117], v[184:187], v[192:195], v[114:117]
	v_mfma_f32_16x16x32_bf16 v[106:109], v[176:179], v[200:203], v[106:109]
	v_mfma_f32_16x16x32_bf16 v[98:101], v[184:187], v[200:203], v[98:101]
	v_mfma_f32_16x16x32_bf16 v[90:93], v[176:179], v[208:211], v[90:93]
	v_mfma_f32_16x16x32_bf16 v[82:85], v[184:187], v[208:211], v[82:85]
	v_mfma_f32_16x16x32_bf16 v[74:77], v[176:179], v[216:219], v[74:77]
	v_mfma_f32_16x16x32_bf16 v[66:69], v[184:187], v[216:219], v[66:69]
	s_barrier
; #define PG8_STAGE(bufoff, gbase, voff) do { _Pragma("unroll") for (int _i = 0; _i < 2; ++_i) \
;         __builtin_amdgcn_global_load_lds((const unsigned*)((const char*)(gbase) + (voff)[_i]), (PG8_LAS unsigned*)(lds + (bufoff) + ldsw + _i * 8192), 16, 0, 0); } while (0)
; #define PG8_WAIT_V(n) asm volatile("s_waitcnt vmcnt(" #n ")" ::: "memory")
; #define PG8_WAIT_L(n) asm volatile("s_waitcnt lgkmcnt(" #n ")" ::: "memory")
; #define PG8_BAR __builtin_amdgcn_s_barrier()
; #define PG8_SCHED __builtin_amdgcn_sched_barrier(0)
;     __device__ __forceinline__ int nt(const pg8::Unit& u) const { return u.kind == 0 ? ntiles : q_nt(u.kind - 1); }
; template <class Epi, class Sched, bool ALIGN_EPI = true, bool SP2 = true>
; __device__ __forceinline__ void gemm_phase(PG8_LAS unsigned char* lds, const int K  , const Sched& S, const Epi& E) {
;     ...
;         for (int t = 0; t < nt; t += 2) {
;     ...
;             PG8_LDA(At, 1, 1); PG8_STAGE(PG8_SB(1, 0), b3, voffB); PG8_STAGE(PG8_SB(1, 1), b3 + hstep, voffB); PG8_STAGE(PG8_SA(1, 0), a3, voffA);
;             PG8_WAIT_V(8); PG8_WAIT_L(0); PG8_BAR; PG8_MMA(1, 0, At, B0); PG8_MMA(1, 1, At, B1); PG8_BAR; PG8_SCHED;
	s_setprio 0
	s_add_i32 s24, s49, s29
	v_lshl_add_u64 v[220:221], v[220:221], 0, s[6:7]
	s_mov_b32 m0, s24
	ds_read_b128 v[188:191], v156 offset:49152
	ds_read_b128 v[192:195], v156 offset:50176
	ds_read_b128 v[196:199], v156 offset:51200
	ds_read_b128 v[200:203], v156 offset:52224
	ds_read_b128 v[204:207], v156 offset:53248
	ds_read_b128 v[208:211], v156 offset:54272
	ds_read_b128 v[212:215], v156 offset:55296
	ds_read_b128 v[216:219], v156 offset:56320
	global_load_lds_dwordx4 v[220:221], off
	s_add_i32 m0, s24, 0x2000
	s_add_u32 s22, s22, 0x80080
	v_lshl_add_u64 v[220:221], v[222:223], 0, s[6:7]
	s_addc_u32 s23, s23, 0
	s_add_i32 s24, s50, s29
	global_load_lds_dwordx4 v[220:221], off
	v_lshl_add_u64 v[220:221], s[22:23], 0, v[136:137]
	s_mov_b32 m0, s24
	s_nop 0
	global_load_lds_dwordx4 v[220:221], off
	v_lshl_add_u64 v[220:221], s[22:23], 0, v[132:133]
	s_add_i32 m0, s24, 0x2000
	s_nop 0
	global_load_lds_dwordx4 v[220:221], off
	v_lshl_add_u64 v[220:221], v[224:225], 0, s[6:7]
	s_mov_b32 m0, s36
	s_nop 0
	global_load_lds_dwordx4 v[220:221], off
	v_lshl_add_u64 v[220:221], v[226:227], 0, s[6:7]
	s_mov_b32 m0, s37
	s_nop 0
	global_load_lds_dwordx4 v[220:221], off
	s_add_i32 s48, s48, 2
	s_add_u32 s20, s20, 0x100
	s_addc_u32 s21, s21, 0
	s_add_u32 s46, s46, 0x100
	s_addc_u32 s47, s47, 0
	s_cmp_gt_u32 s48, 29
	s_waitcnt vmcnt(8)
	s_waitcnt lgkmcnt(0)
	s_setprio 1
	s_barrier
	v_mfma_f32_16x16x32_bf16 v[62:65], v[148:151], v[188:191], v[62:65]
	v_mfma_f32_16x16x32_bf16 v[54:57], v[164:167], v[188:191], v[54:57]
	v_mfma_f32_16x16x32_bf16 v[46:49], v[148:151], v[196:199], v[46:49]
	v_mfma_f32_16x16x32_bf16 v[38:41], v[164:167], v[196:199], v[38:41]
	v_mfma_f32_16x16x32_bf16 v[30:33], v[148:151], v[204:207], v[30:33]
	v_mfma_f32_16x16x32_bf16 v[22:25], v[164:167], v[204:207], v[22:25]
	v_mfma_f32_16x16x32_bf16 v[14:17], v[148:151], v[212:215], v[14:17]
	v_mfma_f32_16x16x32_bf16 v[6:9], v[164:167], v[212:215], v[6:9]
	v_mfma_f32_16x16x32_bf16 v[62:65], v[160:163], v[192:195], v[62:65]
	v_mfma_f32_16x16x32_bf16 v[54:57], v[168:171], v[192:195], v[54:57]
	v_mfma_f32_16x16x32_bf16 v[46:49], v[160:163], v[200:203], v[46:49]
	v_mfma_f32_16x16x32_bf16 v[38:41], v[168:171], v[200:203], v[38:41]
	v_mfma_f32_16x16x32_bf16 v[30:33], v[160:163], v[208:211], v[30:33]
	v_mfma_f32_16x16x32_bf16 v[22:25], v[168:171], v[208:211], v[22:25]
	v_mfma_f32_16x16x32_bf16 v[14:17], v[160:163], v[216:219], v[14:17]
	v_mfma_f32_16x16x32_bf16 v[6:9], v[168:171], v[216:219], v[6:9]
	s_setprio 0
	s_setprio 1
	v_mfma_f32_16x16x32_bf16 v[58:61], v[172:175], v[188:191], v[58:61]
	v_mfma_f32_16x16x32_bf16 v[50:53], v[180:183], v[188:191], v[50:53]
	v_mfma_f32_16x16x32_bf16 v[42:45], v[172:175], v[196:199], v[42:45]
	v_mfma_f32_16x16x32_bf16 v[34:37], v[180:183], v[196:199], v[34:37]
	v_mfma_f32_16x16x32_bf16 v[26:29], v[172:175], v[204:207], v[26:29]
	v_mfma_f32_16x16x32_bf16 v[18:21], v[180:183], v[204:207], v[18:21]
	v_mfma_f32_16x16x32_bf16 v[10:13], v[172:175], v[212:215], v[10:13]
	v_mfma_f32_16x16x32_bf16 v[2:5], v[180:183], v[212:215], v[2:5]
	v_mfma_f32_16x16x32_bf16 v[58:61], v[176:179], v[192:195], v[58:61]
	v_mfma_f32_16x16x32_bf16 v[50:53], v[184:187], v[192:195], v[50:53]
	v_mfma_f32_16x16x32_bf16 v[42:45], v[176:179], v[200:203], v[42:45]
	v_mfma_f32_16x16x32_bf16 v[34:37], v[184:187], v[200:203], v[34:37]
	v_mfma_f32_16x16x32_bf16 v[26:29], v[176:179], v[208:211], v[26:29]
	v_mfma_f32_16x16x32_bf16 v[18:21], v[184:187], v[208:211], v[18:21]
	v_mfma_f32_16x16x32_bf16 v[10:13], v[176:179], v[216:219], v[10:13]
	v_mfma_f32_16x16x32_bf16 v[2:5], v[184:187], v[216:219], v[2:5]
	s_barrier
	s_setprio 0
	s_cbranch_scc0 .LBB0_219
	s_and_b64 vcc, exec, s[8:9]
	s_cbranch_vccz .LBB0_222
	s_barrier

; #define PG8_STAGE(bufoff, gbase, voff) do { _Pragma("unroll") for (int _i = 0; _i < 2; ++_i) \
;         __builtin_amdgcn_global_load_lds((const unsigned*)((const char*)(gbase) + (voff)[_i]), (PG8_LAS unsigned*)(lds + (bufoff) + ldsw + _i * 8192), 16, 0, 0); } while (0)
; #define PG8_WAIT_V(n) asm volatile("s_waitcnt vmcnt(" #n ")" ::: "memory")
; #define PG8_WAIT_L(n) asm volatile("s_waitcnt lgkmcnt(" #n ")" ::: "memory")
; #define PG8_BAR __builtin_amdgcn_s_barrier()
; #define PG8_SCHED __builtin_amdgcn_sched_barrier(0)
;     __device__ __forceinline__ int nt(const pg8::Unit& u) const { return u.kind == 0 ? ntiles : q_nt(u.kind - 1); }
; template <class Epi, class Sched, bool ALIGN_EPI = true, bool SP2 = true>
; __device__ __forceinline__ void gemm_phase(PG8_LAS unsigned char* lds, const int K  , const Sched& S, const Epi& E) {
;     ...
;             const bool last = (t == nt - 2);
;             const char* a1 = cA + (size_t)(t + 1) * kstep;
;             const char* a2 = last ? nA : cA + (size_t)(t + 2) * kstep; const char* b2 = last ? nB : cB + (size_t)(t + 2) * kstep;
;             const char* a3 = a2 + kstep; const char* b3 = b2 + kstep;
;             if constexpr (SP2) {
;             PG8_LDB(B0, 0, 0); PG8_LDB(B1, 0, 1); PG8_SCHED; PG8_LDA(At, 0, 0); PG8_STAGE(PG8_SA(1, 1), a1 + hstep, voffA);
;             PG8_WAIT_V(8); PG8_WAIT_L(0); PG8_BAR; PG8_MMA(0, 0, At, B0); PG8_MMA(0, 1, At, B1); PG8_BAR; PG8_SCHED;
;             PG8_LDA(At, 0, 1); PG8_STAGE(PG8_SB(0, 0), b2, voffB); PG8_STAGE(PG8_SB(0, 1), b2 + hstep, voffB); PG8_STAGE(PG8_SA(0, 0), a2, voffA);
;             PG8_WAIT_V(8); PG8_WAIT_L(0); PG8_BAR; PG8_MMA(1, 0, At, B0); PG8_MMA(1, 1, At, B1); PG8_BAR; PG8_SCHED;
.LBB0_393:
	ds_read_b128 v[18:21], v190
	ds_read_b128 v[22:25], v190 offset:1024
	ds_read_b128 v[26:29], v190 offset:2048
	ds_read_b128 v[30:33], v190 offset:3072
	ds_read_b128 v[2:5], v191
	ds_read_b128 v[6:9], v191 offset:1024
	ds_read_b128 v[10:13], v191 offset:2048
	ds_read_b128 v[14:17], v191 offset:3072
	s_add_i32 s50, s22, 2
	s_add_u32 s20, s18, 0xfff50080
	s_addc_u32 s21, s19, -1
	s_cmp_eq_u32 s47, s22
	s_cselect_b32 s22, s14, s20
	s_cselect_b32 s23, s15, s21
	s_cselect_b32 s21, s17, s49
	s_cselect_b32 s20, s16, s48
	v_lshl_add_u64 v[218:219], s[18:19], 0, v[170:171]
	s_add_i32 m0, s26, 0xc000
	ds_read_b128 v[178:181], v192
	ds_read_b128 v[182:185], v192 offset:1024
	ds_read_b128 v[194:197], v192 offset:2048
	ds_read_b128 v[198:201], v192 offset:3072
	ds_read_b128 v[202:205], v192 offset:4096
	ds_read_b128 v[206:209], v192 offset:5120
	ds_read_b128 v[210:213], v192 offset:6144
	ds_read_b128 v[214:217], v192 offset:7168
	global_load_lds_dwordx4 v[218:219], off
	v_lshl_add_u64 v[218:219], s[18:19], 0, v[172:173]
	s_add_i32 m0, s26, 0xe000
	s_nop 0
	global_load_lds_dwordx4 v[218:219], off
	s_waitcnt vmcnt(8)
	s_waitcnt lgkmcnt(0)
	s_setprio 1
	s_barrier
	v_mfma_scale_f32_16x16x128_f8f6f4 v[158:161], v[18:25], v[178:185], v[158:161], v186, v186 op_sel_hi:[0,0,0]
	v_mfma_scale_f32_16x16x128_f8f6f4 v[154:157], v[26:33], v[178:185], v[154:157], v186, v186 op_sel_hi:[0,0,0]
	v_mfma_scale_f32_16x16x128_f8f6f4 v[150:153], v[18:25], v[194:201], v[150:153], v186, v186 op_sel_hi:[0,0,0]
	v_mfma_scale_f32_16x16x128_f8f6f4 v[142:145], v[26:33], v[194:201], v[142:145], v186, v186 op_sel_hi:[0,0,0]
	v_mfma_scale_f32_16x16x128_f8f6f4 v[134:137], v[18:25], v[202:209], v[134:137], v186, v186 op_sel_hi:[0,0,0]
	v_mfma_scale_f32_16x16x128_f8f6f4 v[126:129], v[26:33], v[202:209], v[126:129], v186, v186 op_sel_hi:[0,0,0]
	v_mfma_scale_f32_16x16x128_f8f6f4 v[118:121], v[18:25], v[210:217], v[118:121], v186, v186 op_sel_hi:[0,0,0]
	v_mfma_scale_f32_16x16x128_f8f6f4 v[110:113], v[26:33], v[210:217], v[110:113], v186, v186 op_sel_hi:[0,0,0]
	s_setprio 0
	s_setprio 1
	v_mfma_scale_f32_16x16x128_f8f6f4 v[146:149], v[2:9], v[178:185], v[146:149], v186, v186 op_sel_hi:[0,0,0]
	v_mfma_scale_f32_16x16x128_f8f6f4 v[138:141], v[10:17], v[178:185], v[138:141], v186, v186 op_sel_hi:[0,0,0]
	v_mfma_scale_f32_16x16x128_f8f6f4 v[130:133], v[2:9], v[194:201], v[130:133], v186, v186 op_sel_hi:[0,0,0]
	v_mfma_scale_f32_16x16x128_f8f6f4 v[122:125], v[10:17], v[194:201], v[122:125], v186, v186 op_sel_hi:[0,0,0]
	v_mfma_scale_f32_16x16x128_f8f6f4 v[114:117], v[2:9], v[202:209], v[114:117], v186, v186 op_sel_hi:[0,0,0]
	v_mfma_scale_f32_16x16x128_f8f6f4 v[106:109], v[10:17], v[202:209], v[106:109], v186, v186 op_sel_hi:[0,0,0]
	v_mfma_scale_f32_16x16x128_f8f6f4 v[102:105], v[2:9], v[210:217], v[102:105], v186, v186 op_sel_hi:[0,0,0]
	v_mfma_scale_f32_16x16x128_f8f6f4 v[98:101], v[10:17], v[210:217], v[98:101], v186, v186 op_sel_hi:[0,0,0]
	s_barrier
	s_setprio 0
	s_add_i32 s51, s37, s25
	v_lshl_add_u64 v[178:179], s[20:21], 0, v[164:165]
	s_mov_b32 m0, s51
	ds_read_b128 v[194:197], v192 offset:16384
	ds_read_b128 v[198:201], v192 offset:17408
	ds_read_b128 v[202:205], v192 offset:18432
	ds_read_b128 v[206:209], v192 offset:19456
	ds_read_b128 v[210:213], v192 offset:20480
	ds_read_b128 v[214:217], v192 offset:21504
	ds_read_b128 v[218:221], v192 offset:22528
	ds_read_b128 v[222:225], v192 offset:23552
	global_load_lds_dwordx4 v[178:179], off
	s_add_i32 m0, s51, 0x2000
	s_add_u32 s68, s20, 0xb0000
	v_lshl_add_u64 v[180:181], s[20:21], 0, v[168:169]
	s_addc_u32 s69, s21, 0
	s_add_i32 s51, s38, s25
	global_load_lds_dwordx4 v[180:181], off
	v_lshl_add_u64 v[182:183], s[68:69], 0, v[164:165]
	s_mov_b32 m0, s51
	v_lshl_add_u64 v[184:185], s[22:23], 0, v[166:167]
	global_load_lds_dwordx4 v[182:183], off
	v_lshl_add_u64 v[182:183], s[68:69], 0, v[168:169]
	s_add_i32 m0, s51, 0x2000
	s_nop 0
	global_load_lds_dwordx4 v[182:183], off
	v_lshl_add_u64 v[182:183], s[22:23], 0, v[162:163]
	s_mov_b32 m0, s26
	s_nop 0
	global_load_lds_dwordx4 v[182:183], off
	s_mov_b32 m0, s27
	s_nop 0
	global_load_lds_dwordx4 v[184:185], off
	s_waitcnt vmcnt(8)
	s_waitcnt lgkmcnt(0)
	s_setprio 1
	s_barrier
	v_mfma_scale_f32_16x16x128_f8f6f4 v[94:97], v[18:25], v[194:201], v[94:97], v186, v186 op_sel_hi:[0,0,0]
	v_mfma_scale_f32_16x16x128_f8f6f4 v[90:93], v[26:33], v[194:201], v[90:93], v186, v186 op_sel_hi:[0,0,0]
	v_mfma_scale_f32_16x16x128_f8f6f4 v[86:89], v[18:25], v[202:209], v[86:89], v186, v186 op_sel_hi:[0,0,0]
	v_mfma_scale_f32_16x16x128_f8f6f4 v[78:81], v[26:33], v[202:209], v[78:81], v186, v186 op_sel_hi:[0,0,0]
	v_mfma_scale_f32_16x16x128_f8f6f4 v[70:73], v[18:25], v[210:217], v[70:73], v186, v186 op_sel_hi:[0,0,0]
	v_mfma_scale_f32_16x16x128_f8f6f4 v[62:65], v[26:33], v[210:217], v[62:65], v186, v186 op_sel_hi:[0,0,0]
	v_mfma_scale_f32_16x16x128_f8f6f4 v[54:57], v[18:25], v[218:225], v[54:57], v186, v186 op_sel_hi:[0,0,0]
	v_mfma_scale_f32_16x16x128_f8f6f4 v[46:49], v[26:33], v[218:225], v[46:49], v186, v186 op_sel_hi:[0,0,0]
	s_setprio 0
	s_setprio 1
	v_mfma_scale_f32_16x16x128_f8f6f4 v[82:85], v[2:9], v[194:201], v[82:85], v186, v186 op_sel_hi:[0,0,0]
	v_mfma_scale_f32_16x16x128_f8f6f4 v[74:77], v[10:17], v[194:201], v[74:77], v186, v186 op_sel_hi:[0,0,0]
	v_mfma_scale_f32_16x16x128_f8f6f4 v[66:69], v[2:9], v[202:209], v[66:69], v186, v186 op_sel_hi:[0,0,0]
	v_mfma_scale_f32_16x16x128_f8f6f4 v[58:61], v[10:17], v[202:209], v[58:61], v186, v186 op_sel_hi:[0,0,0]
	v_mfma_scale_f32_16x16x128_f8f6f4 v[50:53], v[2:9], v[210:217], v[50:53], v186, v186 op_sel_hi:[0,0,0]
	v_mfma_scale_f32_16x16x128_f8f6f4 v[42:45], v[10:17], v[210:217], v[42:45], v186, v186 op_sel_hi:[0,0,0]
	v_mfma_scale_f32_16x16x128_f8f6f4 v[38:41], v[2:9], v[218:225], v[38:41], v186, v186 op_sel_hi:[0,0,0]
	v_mfma_scale_f32_16x16x128_f8f6f4 v[34:37], v[10:17], v[218:225], v[34:37], v186, v186 op_sel_hi:[0,0,0]
	s_barrier
; #define PG8_STAGE(bufoff, gbase, voff) do { _Pragma("unroll") for (int _i = 0; _i < 2; ++_i) \
;         __builtin_amdgcn_global_load_lds((const unsigned*)((const char*)(gbase) + (voff)[_i]), (PG8_LAS unsigned*)(lds + (bufoff) + ldsw + _i * 8192), 16, 0, 0); } while (0)
; #define PG8_WAIT_V(n) asm volatile("s_waitcnt vmcnt(" #n ")" ::: "memory")
; #define PG8_WAIT_L(n) asm volatile("s_waitcnt lgkmcnt(" #n ")" ::: "memory")
; #define PG8_BAR __builtin_amdgcn_s_barrier()
; #define PG8_SCHED __builtin_amdgcn_sched_barrier(0)
;     __device__ __forceinline__ int nt(const pg8::Unit& u) const { return u.kind == 0 ? ntiles : q_nt(u.kind - 1); }
; template <class Epi, class Sched, bool ALIGN_EPI = true, bool SP2 = true>
; __device__ __forceinline__ void gemm_phase(PG8_LAS unsigned char* lds, const int K  , const Sched& S, const Epi& E) {
;     ...
;         for (int t = 0; t < nt; t += 2) {
;     ...
;             PG8_LDB(B0, 1, 0); PG8_LDB(B1, 1, 1); PG8_SCHED; PG8_LDA(At, 1, 0); PG8_STAGE(PG8_SA(0, 1), a2 + hstep, voffA);
;             PG8_WAIT_V(8); PG8_WAIT_L(0); PG8_BAR; PG8_MMA(0, 0, At, B0); PG8_MMA(0, 1, At, B1); PG8_BAR; PG8_SCHED;
;             PG8_LDA(At, 1, 1); PG8_STAGE(PG8_SB(1, 0), b3, voffB); PG8_STAGE(PG8_SB(1, 1), b3 + hstep, voffB); PG8_STAGE(PG8_SA(1, 0), a3, voffA);
;             PG8_WAIT_V(8); PG8_WAIT_L(0); PG8_BAR; PG8_MMA(1, 0, At, B0); PG8_MMA(1, 1, At, B1); PG8_BAR; PG8_SCHED;
;     ...
;         if constexpr (Epi::FP8) asm volatile("s_nop 15\n\ts_nop 15\n\ts_nop 15\n\ts_nop 15\n\ts_nop 15" ::: "memory");
;         if constexpr (ALIGN_EPI) { if (wr == 0) PG8_BAR; }
	s_setprio 0
	s_add_i32 s51, 0, 0x18000
	s_add_i32 s68, 0, 0x1c000
	v_add_u32_e32 v14, s51, v188
	v_add_u32_e32 v30, s68, v188
	ds_read_b128 v[2:5], v14
	ds_read_b128 v[6:9], v14 offset:1024
	ds_read_b128 v[10:13], v14 offset:2048
	ds_read_b128 v[14:17], v14 offset:3072
	ds_read_b128 v[18:21], v30
	ds_read_b128 v[22:25], v30 offset:1024
	ds_read_b128 v[26:29], v30 offset:2048
	ds_read_b128 v[30:33], v30 offset:3072
	s_add_u32 s22, s22, 0xb0000
	s_addc_u32 s23, s23, 0
	s_mov_b32 m0, s28
	v_lshl_add_u64 v[226:227], s[22:23], 0, v[162:163]
	ds_read_b128 v[194:197], v192 offset:32768
	ds_read_b128 v[198:201], v192 offset:33792
	ds_read_b128 v[202:205], v192 offset:34816
	ds_read_b128 v[206:209], v192 offset:35840
	ds_read_b128 v[210:213], v192 offset:36864
	ds_read_b128 v[214:217], v192 offset:37888
	ds_read_b128 v[218:221], v192 offset:38912
	ds_read_b128 v[222:225], v192 offset:39936
	global_load_lds_dwordx4 v[226:227], off
	v_lshl_add_u64 v[226:227], s[22:23], 0, v[166:167]
	s_mov_b32 m0, s29
	s_nop 0
	global_load_lds_dwordx4 v[226:227], off
	s_waitcnt vmcnt(8)
	s_waitcnt lgkmcnt(0)
	s_setprio 1
	s_barrier
	v_mfma_scale_f32_16x16x128_f8f6f4 v[158:161], v[2:9], v[194:201], v[158:161], v186, v186 op_sel_hi:[0,0,0]
	v_mfma_scale_f32_16x16x128_f8f6f4 v[154:157], v[10:17], v[194:201], v[154:157], v186, v186 op_sel_hi:[0,0,0]
	v_mfma_scale_f32_16x16x128_f8f6f4 v[150:153], v[2:9], v[202:209], v[150:153], v186, v186 op_sel_hi:[0,0,0]
	v_mfma_scale_f32_16x16x128_f8f6f4 v[142:145], v[10:17], v[202:209], v[142:145], v186, v186 op_sel_hi:[0,0,0]
	v_mfma_scale_f32_16x16x128_f8f6f4 v[134:137], v[2:9], v[210:217], v[134:137], v186, v186 op_sel_hi:[0,0,0]
	v_mfma_scale_f32_16x16x128_f8f6f4 v[126:129], v[10:17], v[210:217], v[126:129], v186, v186 op_sel_hi:[0,0,0]
	v_mfma_scale_f32_16x16x128_f8f6f4 v[118:121], v[2:9], v[218:225], v[118:121], v186, v186 op_sel_hi:[0,0,0]
	v_mfma_scale_f32_16x16x128_f8f6f4 v[110:113], v[10:17], v[218:225], v[110:113], v186, v186 op_sel_hi:[0,0,0]
	s_setprio 0
	s_setprio 1
	v_mfma_scale_f32_16x16x128_f8f6f4 v[146:149], v[18:25], v[194:201], v[146:149], v186, v186 op_sel_hi:[0,0,0]
	v_mfma_scale_f32_16x16x128_f8f6f4 v[138:141], v[26:33], v[194:201], v[138:141], v186, v186 op_sel_hi:[0,0,0]
	v_mfma_scale_f32_16x16x128_f8f6f4 v[130:133], v[18:25], v[202:209], v[130:133], v186, v186 op_sel_hi:[0,0,0]
	v_mfma_scale_f32_16x16x128_f8f6f4 v[122:125], v[26:33], v[202:209], v[122:125], v186, v186 op_sel_hi:[0,0,0]
	v_mfma_scale_f32_16x16x128_f8f6f4 v[114:117], v[18:25], v[210:217], v[114:117], v186, v186 op_sel_hi:[0,0,0]
	v_mfma_scale_f32_16x16x128_f8f6f4 v[106:109], v[26:33], v[210:217], v[106:109], v186, v186 op_sel_hi:[0,0,0]
	v_mfma_scale_f32_16x16x128_f8f6f4 v[102:105], v[18:25], v[218:225], v[102:105], v186, v186 op_sel_hi:[0,0,0]
	v_mfma_scale_f32_16x16x128_f8f6f4 v[98:101], v[26:33], v[218:225], v[98:101], v186, v186 op_sel_hi:[0,0,0]
	s_barrier
	s_setprio 0
	s_add_i32 s22, s51, s25
	v_lshl_add_u64 v[178:179], v[178:179], 0, s[8:9]
	s_mov_b32 m0, s22
	ds_read_b128 v[194:197], v192 offset:49152
	ds_read_b128 v[198:201], v192 offset:50176
	ds_read_b128 v[202:205], v192 offset:51200
	ds_read_b128 v[206:209], v192 offset:52224
	ds_read_b128 v[210:213], v192 offset:53248
	ds_read_b128 v[214:217], v192 offset:54272
	ds_read_b128 v[218:221], v192 offset:55296
	ds_read_b128 v[222:225], v192 offset:56320
	global_load_lds_dwordx4 v[178:179], off
	s_add_i32 m0, s22, 0x2000
	s_add_u32 s20, s20, 0xb0080
	v_lshl_add_u64 v[178:179], v[180:181], 0, s[8:9]
	s_addc_u32 s21, s21, 0
	s_add_i32 s22, s68, s25
	global_load_lds_dwordx4 v[178:179], off
	v_lshl_add_u64 v[178:179], s[20:21], 0, v[164:165]
	s_mov_b32 m0, s22
	s_nop 0
	global_load_lds_dwordx4 v[178:179], off
	v_lshl_add_u64 v[178:179], s[20:21], 0, v[168:169]
	s_add_i32 m0, s22, 0x2000
	s_nop 0
	global_load_lds_dwordx4 v[178:179], off
	v_lshl_add_u64 v[178:179], v[182:183], 0, s[8:9]
	s_mov_b32 m0, s33
	s_nop 0
	global_load_lds_dwordx4 v[178:179], off
	v_lshl_add_u64 v[178:179], v[184:185], 0, s[8:9]
	s_mov_b32 m0, s34
	s_nop 0
	global_load_lds_dwordx4 v[178:179], off
	s_add_u32 s18, s18, 0x100
	s_addc_u32 s19, s19, 0
	s_add_u32 s48, s48, 0x100
	s_addc_u32 s49, s49, 0
	s_cmp_ge_u32 s50, s4
	s_mov_b32 s22, s50
	s_waitcnt vmcnt(8)
	s_waitcnt lgkmcnt(0)
	s_setprio 1
	s_barrier
	v_mfma_scale_f32_16x16x128_f8f6f4 v[94:97], v[2:9], v[194:201], v[94:97], v186, v186 op_sel_hi:[0,0,0]
	v_mfma_scale_f32_16x16x128_f8f6f4 v[90:93], v[10:17], v[194:201], v[90:93], v186, v186 op_sel_hi:[0,0,0]
	v_mfma_scale_f32_16x16x128_f8f6f4 v[86:89], v[2:9], v[202:209], v[86:89], v186, v186 op_sel_hi:[0,0,0]
	v_mfma_scale_f32_16x16x128_f8f6f4 v[78:81], v[10:17], v[202:209], v[78:81], v186, v186 op_sel_hi:[0,0,0]
	v_mfma_scale_f32_16x16x128_f8f6f4 v[70:73], v[2:9], v[210:217], v[70:73], v186, v186 op_sel_hi:[0,0,0]
	v_mfma_scale_f32_16x16x128_f8f6f4 v[62:65], v[10:17], v[210:217], v[62:65], v186, v186 op_sel_hi:[0,0,0]
	v_mfma_scale_f32_16x16x128_f8f6f4 v[54:57], v[2:9], v[218:225], v[54:57], v186, v186 op_sel_hi:[0,0,0]
	v_mfma_scale_f32_16x16x128_f8f6f4 v[46:49], v[10:17], v[218:225], v[46:49], v186, v186 op_sel_hi:[0,0,0]
	s_setprio 0
	s_setprio 1
	v_mfma_scale_f32_16x16x128_f8f6f4 v[82:85], v[18:25], v[194:201], v[82:85], v186, v186 op_sel_hi:[0,0,0]
	v_mfma_scale_f32_16x16x128_f8f6f4 v[74:77], v[26:33], v[194:201], v[74:77], v186, v186 op_sel_hi:[0,0,0]
	v_mfma_scale_f32_16x16x128_f8f6f4 v[66:69], v[18:25], v[202:209], v[66:69], v186, v186 op_sel_hi:[0,0,0]
	v_mfma_scale_f32_16x16x128_f8f6f4 v[58:61], v[26:33], v[202:209], v[58:61], v186, v186 op_sel_hi:[0,0,0]
	v_mfma_scale_f32_16x16x128_f8f6f4 v[50:53], v[18:25], v[210:217], v[50:53], v186, v186 op_sel_hi:[0,0,0]
	v_mfma_scale_f32_16x16x128_f8f6f4 v[42:45], v[26:33], v[210:217], v[42:45], v186, v186 op_sel_hi:[0,0,0]
	v_mfma_scale_f32_16x16x128_f8f6f4 v[38:41], v[18:25], v[218:225], v[38:41], v186, v186 op_sel_hi:[0,0,0]
	v_mfma_scale_f32_16x16x128_f8f6f4 v[34:37], v[26:33], v[218:225], v[34:37], v186, v186 op_sel_hi:[0,0,0]
	s_barrier
	s_setprio 0
	s_cbranch_scc0 .LBB0_393
	s_nop 15
	s_nop 15
	s_nop 15
	s_nop 15
	s_nop 15
	s_and_b64 vcc, exec, s[10:11]
	s_cbranch_vccz .LBB0_396
	s_barrier

; #define PG8_STAGE(bufoff, gbase, voff) do { _Pragma("unroll") for (int _i = 0; _i < 2; ++_i) \
;         __builtin_amdgcn_global_load_lds((const unsigned*)((const char*)(gbase) + (voff)[_i]), (PG8_LAS unsigned*)(lds + (bufoff) + ldsw + _i * 8192), 16, 0, 0); } while (0)
; #define PG8_WAIT_V(n) asm volatile("s_waitcnt vmcnt(" #n ")" ::: "memory")
; #define PG8_WAIT_L(n) asm volatile("s_waitcnt lgkmcnt(" #n ")" ::: "memory")
; #define PG8_BAR __builtin_amdgcn_s_barrier()
; #define PG8_SCHED __builtin_amdgcn_sched_barrier(0)
;     __device__ __forceinline__ int nt(const pg8::Unit& u) const { return u.kind == 0 ? ntiles : q_nt(u.kind - 1); }
; template <class Epi, class Sched, bool ALIGN_EPI = true, bool SP2 = true>
; __device__ __forceinline__ void gemm_phase(PG8_LAS unsigned char* lds, const int K  , const Sched& S, const Epi& E) {
;     ...
;             const bool last = (t == nt - 2);
;             const char* a1 = cA + (size_t)(t + 1) * kstep;
;             const char* a2 = last ? nA : cA + (size_t)(t + 2) * kstep; const char* b2 = last ? nB : cB + (size_t)(t + 2) * kstep;
;             const char* a3 = a2 + kstep; const char* b3 = b2 + kstep;
;             if constexpr (SP2) {
;             PG8_LDB(B0, 0, 0); PG8_LDB(B1, 0, 1); PG8_SCHED; PG8_LDA(At, 0, 0); PG8_STAGE(PG8_SA(1, 1), a1 + hstep, voffA);
;             PG8_WAIT_V(8); PG8_WAIT_L(0); PG8_BAR; PG8_MMA(0, 0, At, B0); PG8_MMA(0, 1, At, B1); PG8_BAR; PG8_SCHED;
;             PG8_LDA(At, 0, 1); PG8_STAGE(PG8_SB(0, 0), b2, voffB); PG8_STAGE(PG8_SB(0, 1), b2 + hstep, voffB); PG8_STAGE(PG8_SA(0, 0), a2, voffA);
;             PG8_WAIT_V(8); PG8_WAIT_L(0); PG8_BAR; PG8_MMA(1, 0, At, B0); PG8_MMA(1, 1, At, B1); PG8_BAR; PG8_SCHED;
.LBB0_537:
	ds_read_b128 v[150:153], v156
	ds_read_b128 v[160:163], v156 offset:1024
	ds_read_b128 v[164:167], v156 offset:2048
	ds_read_b128 v[168:171], v156 offset:3072
	ds_read_b128 v[172:175], v157
	ds_read_b128 v[176:179], v157 offset:1024
	ds_read_b128 v[180:183], v157 offset:2048
	ds_read_b128 v[184:187], v157 offset:3072
	s_add_u32 s22, s20, 0xfff80080
	s_addc_u32 s23, s21, -1
	s_cmp_eq_u32 s47, 28
	s_cselect_b32 s25, s13, s23
	s_cselect_b32 s24, s19, s22
	s_cselect_b32 s23, s11, s46
	s_cselect_b32 s22, s44, s45
	v_lshl_add_u64 v[220:221], s[20:21], 0, v[142:143]
	s_add_i32 m0, s31, 0xc000
	ds_read_b128 v[188:191], v158
	ds_read_b128 v[192:195], v158 offset:1024
	ds_read_b128 v[196:199], v158 offset:2048
	ds_read_b128 v[200:203], v158 offset:3072
	ds_read_b128 v[204:207], v158 offset:4096
	ds_read_b128 v[208:211], v158 offset:5120
	ds_read_b128 v[212:215], v158 offset:6144
	ds_read_b128 v[216:219], v158 offset:7168
	global_load_lds_dwordx4 v[220:221], off
	v_lshl_add_u64 v[220:221], s[20:21], 0, v[144:145]
	s_add_i32 m0, s31, 0xe000
	s_nop 0
	global_load_lds_dwordx4 v[220:221], off
	s_waitcnt vmcnt(8)
	s_waitcnt lgkmcnt(0)
	s_setprio 1
	s_barrier
	v_mfma_f32_16x16x32_bf16 v[126:129], v[150:153], v[188:191], v[126:129]
	v_mfma_f32_16x16x32_bf16 v[122:125], v[164:167], v[188:191], v[122:125]
	v_mfma_f32_16x16x32_bf16 v[118:121], v[150:153], v[196:199], v[118:121]
	v_mfma_f32_16x16x32_bf16 v[110:113], v[164:167], v[196:199], v[110:113]
	v_mfma_f32_16x16x32_bf16 v[102:105], v[150:153], v[204:207], v[102:105]
	v_mfma_f32_16x16x32_bf16 v[94:97], v[164:167], v[204:207], v[94:97]
	v_mfma_f32_16x16x32_bf16 v[86:89], v[150:153], v[212:215], v[86:89]
	v_mfma_f32_16x16x32_bf16 v[78:81], v[164:167], v[212:215], v[78:81]
	v_mfma_f32_16x16x32_bf16 v[126:129], v[160:163], v[192:195], v[126:129]
	v_mfma_f32_16x16x32_bf16 v[122:125], v[168:171], v[192:195], v[122:125]
	v_mfma_f32_16x16x32_bf16 v[118:121], v[160:163], v[200:203], v[118:121]
	v_mfma_f32_16x16x32_bf16 v[110:113], v[168:171], v[200:203], v[110:113]
	v_mfma_f32_16x16x32_bf16 v[102:105], v[160:163], v[208:211], v[102:105]
	v_mfma_f32_16x16x32_bf16 v[94:97], v[168:171], v[208:211], v[94:97]
	v_mfma_f32_16x16x32_bf16 v[86:89], v[160:163], v[216:219], v[86:89]
	v_mfma_f32_16x16x32_bf16 v[78:81], v[168:171], v[216:219], v[78:81]
	s_setprio 0
	s_setprio 1
	v_mfma_f32_16x16x32_bf16 v[114:117], v[172:175], v[188:191], v[114:117]
	v_mfma_f32_16x16x32_bf16 v[106:109], v[180:183], v[188:191], v[106:109]
	v_mfma_f32_16x16x32_bf16 v[98:101], v[172:175], v[196:199], v[98:101]
	v_mfma_f32_16x16x32_bf16 v[90:93], v[180:183], v[196:199], v[90:93]
	v_mfma_f32_16x16x32_bf16 v[82:85], v[172:175], v[204:207], v[82:85]
	v_mfma_f32_16x16x32_bf16 v[74:77], v[180:183], v[204:207], v[74:77]
	v_mfma_f32_16x16x32_bf16 v[70:73], v[172:175], v[212:215], v[70:73]
	v_mfma_f32_16x16x32_bf16 v[66:69], v[180:183], v[212:215], v[66:69]
	v_mfma_f32_16x16x32_bf16 v[114:117], v[176:179], v[192:195], v[114:117]
	v_mfma_f32_16x16x32_bf16 v[106:109], v[184:187], v[192:195], v[106:109]
	v_mfma_f32_16x16x32_bf16 v[98:101], v[176:179], v[200:203], v[98:101]
	v_mfma_f32_16x16x32_bf16 v[90:93], v[184:187], v[200:203], v[90:93]
	v_mfma_f32_16x16x32_bf16 v[82:85], v[176:179], v[208:211], v[82:85]
	v_mfma_f32_16x16x32_bf16 v[74:77], v[184:187], v[208:211], v[74:77]
	v_mfma_f32_16x16x32_bf16 v[70:73], v[176:179], v[216:219], v[70:73]
	v_mfma_f32_16x16x32_bf16 v[66:69], v[184:187], v[216:219], v[66:69]
	s_barrier
	s_setprio 0
	s_add_i32 s48, s40, s29
	v_lshl_add_u64 v[220:221], s[22:23], 0, v[136:137]
	s_mov_b32 m0, s48
	ds_read_b128 v[188:191], v158 offset:16384
	ds_read_b128 v[192:195], v158 offset:17408
	ds_read_b128 v[196:199], v158 offset:18432
	ds_read_b128 v[200:203], v158 offset:19456
	ds_read_b128 v[204:207], v158 offset:20480
	ds_read_b128 v[208:211], v158 offset:21504
	ds_read_b128 v[212:215], v158 offset:22528
	ds_read_b128 v[216:219], v158 offset:23552
	global_load_lds_dwordx4 v[220:221], off
	s_add_i32 m0, s48, 0x2000
	s_add_u32 s48, s22, 0x80000
	v_lshl_add_u64 v[222:223], s[22:23], 0, v[132:133]
	s_addc_u32 s49, s23, 0
	s_add_i32 s50, s41, s29
	global_load_lds_dwordx4 v[222:223], off
	v_lshl_add_u64 v[224:225], s[48:49], 0, v[136:137]
	s_mov_b32 m0, s50
	v_lshl_add_u64 v[226:227], s[24:25], 0, v[134:135]
	global_load_lds_dwordx4 v[224:225], off
	v_lshl_add_u64 v[224:225], s[48:49], 0, v[132:133]
	s_add_i32 m0, s50, 0x2000
	s_nop 0
	global_load_lds_dwordx4 v[224:225], off
	v_lshl_add_u64 v[224:225], s[24:25], 0, v[138:139]
	s_mov_b32 m0, s31
	s_nop 0
	global_load_lds_dwordx4 v[224:225], off
	s_mov_b32 m0, s33
	s_nop 0
	global_load_lds_dwordx4 v[226:227], off
	s_waitcnt vmcnt(8)
	s_waitcnt lgkmcnt(0)
	s_setprio 1
	s_barrier
; #define PG8_STAGE(bufoff, gbase, voff) do { _Pragma("unroll") for (int _i = 0; _i < 2; ++_i) \
;         __builtin_amdgcn_global_load_lds((const unsigned*)((const char*)(gbase) + (voff)[_i]), (PG8_LAS unsigned*)(lds + (bufoff) + ldsw + _i * 8192), 16, 0, 0); } while (0)
; #define PG8_WAIT_V(n) asm volatile("s_waitcnt vmcnt(" #n ")" ::: "memory")
; #define PG8_WAIT_L(n) asm volatile("s_waitcnt lgkmcnt(" #n ")" ::: "memory")
; #define PG8_BAR __builtin_amdgcn_s_barrier()
; #define PG8_SCHED __builtin_amdgcn_sched_barrier(0)
; template <class Epi, class Sched, bool ALIGN_EPI = true, bool SP2 = true>
; __device__ __forceinline__ void gemm_phase(PG8_LAS unsigned char* lds, const int K  , const Sched& S, const Epi& E) {
;     ...
;             PG8_WAIT_V(8); PG8_WAIT_L(0); PG8_BAR; PG8_MMA(1, 0, At, B0); PG8_MMA(1, 1, At, B1); PG8_BAR; PG8_SCHED;
;             PG8_LDB(B0, 1, 0); PG8_LDB(B1, 1, 1); PG8_SCHED; PG8_LDA(At, 1, 0); PG8_STAGE(PG8_SA(0, 1), a2 + hstep, voffA);
;             PG8_WAIT_V(8); PG8_WAIT_L(0); PG8_BAR; PG8_MMA(0, 0, At, B0); PG8_MMA(0, 1, At, B1); PG8_BAR; PG8_SCHED;
	v_mfma_f32_16x16x32_bf16 v[62:65], v[150:153], v[188:191], v[62:65]
	v_mfma_f32_16x16x32_bf16 v[58:61], v[164:167], v[188:191], v[58:61]
	v_mfma_f32_16x16x32_bf16 v[54:57], v[150:153], v[196:199], v[54:57]
	v_mfma_f32_16x16x32_bf16 v[46:49], v[164:167], v[196:199], v[46:49]
	v_mfma_f32_16x16x32_bf16 v[38:41], v[150:153], v[204:207], v[38:41]
	v_mfma_f32_16x16x32_bf16 v[30:33], v[164:167], v[204:207], v[30:33]
	v_mfma_f32_16x16x32_bf16 v[22:25], v[150:153], v[212:215], v[22:25]
	v_mfma_f32_16x16x32_bf16 v[14:17], v[164:167], v[212:215], v[14:17]
	v_mfma_f32_16x16x32_bf16 v[62:65], v[160:163], v[192:195], v[62:65]
	v_mfma_f32_16x16x32_bf16 v[58:61], v[168:171], v[192:195], v[58:61]
	v_mfma_f32_16x16x32_bf16 v[54:57], v[160:163], v[200:203], v[54:57]
	v_mfma_f32_16x16x32_bf16 v[46:49], v[168:171], v[200:203], v[46:49]
	v_mfma_f32_16x16x32_bf16 v[38:41], v[160:163], v[208:211], v[38:41]
	v_mfma_f32_16x16x32_bf16 v[30:33], v[168:171], v[208:211], v[30:33]
	v_mfma_f32_16x16x32_bf16 v[22:25], v[160:163], v[216:219], v[22:25]
	v_mfma_f32_16x16x32_bf16 v[14:17], v[168:171], v[216:219], v[14:17]
	s_setprio 0
	s_setprio 1
	v_mfma_f32_16x16x32_bf16 v[50:53], v[172:175], v[188:191], v[50:53]
	v_mfma_f32_16x16x32_bf16 v[42:45], v[180:183], v[188:191], v[42:45]
	v_mfma_f32_16x16x32_bf16 v[34:37], v[172:175], v[196:199], v[34:37]
	v_mfma_f32_16x16x32_bf16 v[26:29], v[180:183], v[196:199], v[26:29]
	v_mfma_f32_16x16x32_bf16 v[18:21], v[172:175], v[204:207], v[18:21]
	v_mfma_f32_16x16x32_bf16 v[10:13], v[180:183], v[204:207], v[10:13]
	v_mfma_f32_16x16x32_bf16 v[6:9], v[172:175], v[212:215], v[6:9]
	v_mfma_f32_16x16x32_bf16 v[2:5], v[180:183], v[212:215], v[2:5]
	v_mfma_f32_16x16x32_bf16 v[50:53], v[176:179], v[192:195], v[50:53]
	v_mfma_f32_16x16x32_bf16 v[42:45], v[184:187], v[192:195], v[42:45]
	v_mfma_f32_16x16x32_bf16 v[34:37], v[176:179], v[200:203], v[34:37]
	v_mfma_f32_16x16x32_bf16 v[26:29], v[184:187], v[200:203], v[26:29]
	v_mfma_f32_16x16x32_bf16 v[18:21], v[176:179], v[208:211], v[18:21]
	v_mfma_f32_16x16x32_bf16 v[10:13], v[184:187], v[208:211], v[10:13]
	v_mfma_f32_16x16x32_bf16 v[6:9], v[176:179], v[216:219], v[6:9]
	v_mfma_f32_16x16x32_bf16 v[2:5], v[184:187], v[216:219], v[2:5]
	s_barrier
	s_setprio 0
	s_add_i32 s48, 0, 0x18000
	v_add_u32_e32 v140, s48, v154
	s_add_i32 s49, 0, 0x1c000
	ds_read_b128 v[150:153], v140
	ds_read_b128 v[160:163], v140 offset:1024
	ds_read_b128 v[164:167], v140 offset:2048
	ds_read_b128 v[168:171], v140 offset:3072
	v_add_u32_e32 v140, s49, v154
	ds_read_b128 v[172:175], v140
	ds_read_b128 v[176:179], v140 offset:1024
	ds_read_b128 v[180:183], v140 offset:2048
	ds_read_b128 v[184:187], v140 offset:3072
	s_add_u32 s24, s24, 0x80000
	s_addc_u32 s25, s25, 0
	s_mov_b32 m0, s34
	v_lshl_add_u64 v[230:231], s[24:25], 0, v[138:139]
	ds_read_b128 v[188:191], v158 offset:32768
	ds_read_b128 v[192:195], v158 offset:33792
	ds_read_b128 v[196:199], v158 offset:34816
	ds_read_b128 v[200:203], v158 offset:35840
	ds_read_b128 v[204:207], v158 offset:36864
	ds_read_b128 v[208:211], v158 offset:37888
	ds_read_b128 v[212:215], v158 offset:38912
	ds_read_b128 v[216:219], v158 offset:39936
	global_load_lds_dwordx4 v[230:231], off
	v_lshl_add_u64 v[230:231], s[24:25], 0, v[134:135]
	s_mov_b32 m0, s35
	s_nop 0
	global_load_lds_dwordx4 v[230:231], off
	s_waitcnt vmcnt(8)
	s_waitcnt lgkmcnt(0)
	s_setprio 1
	s_barrier
	v_mfma_f32_16x16x32_bf16 v[126:129], v[150:153], v[188:191], v[126:129]
	v_mfma_f32_16x16x32_bf16 v[122:125], v[164:167], v[188:191], v[122:125]
	v_mfma_f32_16x16x32_bf16 v[118:121], v[150:153], v[196:199], v[118:121]
	v_mfma_f32_16x16x32_bf16 v[110:113], v[164:167], v[196:199], v[110:113]
	v_mfma_f32_16x16x32_bf16 v[102:105], v[150:153], v[204:207], v[102:105]
	v_mfma_f32_16x16x32_bf16 v[94:97], v[164:167], v[204:207], v[94:97]
	v_mfma_f32_16x16x32_bf16 v[86:89], v[150:153], v[212:215], v[86:89]
	v_mfma_f32_16x16x32_bf16 v[78:81], v[164:167], v[212:215], v[78:81]
	v_mfma_f32_16x16x32_bf16 v[126:129], v[160:163], v[192:195], v[126:129]
	v_mfma_f32_16x16x32_bf16 v[122:125], v[168:171], v[192:195], v[122:125]
	v_mfma_f32_16x16x32_bf16 v[118:121], v[160:163], v[200:203], v[118:121]
	v_mfma_f32_16x16x32_bf16 v[110:113], v[168:171], v[200:203], v[110:113]
	v_mfma_f32_16x16x32_bf16 v[102:105], v[160:163], v[208:211], v[102:105]
	v_mfma_f32_16x16x32_bf16 v[94:97], v[168:171], v[208:211], v[94:97]
	v_mfma_f32_16x16x32_bf16 v[86:89], v[160:163], v[216:219], v[86:89]
	v_mfma_f32_16x16x32_bf16 v[78:81], v[168:171], v[216:219], v[78:81]
	s_setprio 0
	s_setprio 1
	v_mfma_f32_16x16x32_bf16 v[114:117], v[172:175], v[188:191], v[114:117]
	v_mfma_f32_16x16x32_bf16 v[106:109], v[180:183], v[188:191], v[106:109]
	v_mfma_f32_16x16x32_bf16 v[98:101], v[172:175], v[196:199], v[98:101]
	v_mfma_f32_16x16x32_bf16 v[90:93], v[180:183], v[196:199], v[90:93]
	v_mfma_f32_16x16x32_bf16 v[82:85], v[172:175], v[204:207], v[82:85]
	v_mfma_f32_16x16x32_bf16 v[74:77], v[180:183], v[204:207], v[74:77]
	v_mfma_f32_16x16x32_bf16 v[70:73], v[172:175], v[212:215], v[70:73]
	v_mfma_f32_16x16x32_bf16 v[66:69], v[180:183], v[212:215], v[66:69]
	v_mfma_f32_16x16x32_bf16 v[114:117], v[176:179], v[192:195], v[114:117]
	v_mfma_f32_16x16x32_bf16 v[106:109], v[184:187], v[192:195], v[106:109]
	v_mfma_f32_16x16x32_bf16 v[98:101], v[176:179], v[200:203], v[98:101]
	v_mfma_f32_16x16x32_bf16 v[90:93], v[184:187], v[200:203], v[90:93]
	v_mfma_f32_16x16x32_bf16 v[82:85], v[176:179], v[208:211], v[82:85]
	v_mfma_f32_16x16x32_bf16 v[74:77], v[184:187], v[208:211], v[74:77]
	v_mfma_f32_16x16x32_bf16 v[70:73], v[176:179], v[216:219], v[70:73]
	v_mfma_f32_16x16x32_bf16 v[66:69], v[184:187], v[216:219], v[66:69]
	s_barrier
; #define PG8_STAGE(bufoff, gbase, voff) do { _Pragma("unroll") for (int _i = 0; _i < 2; ++_i) \
;         __builtin_amdgcn_global_load_lds((const unsigned*)((const char*)(gbase) + (voff)[_i]), (PG8_LAS unsigned*)(lds + (bufoff) + ldsw + _i * 8192), 16, 0, 0); } while (0)
; #define PG8_WAIT_V(n) asm volatile("s_waitcnt vmcnt(" #n ")" ::: "memory")
; #define PG8_WAIT_L(n) asm volatile("s_waitcnt lgkmcnt(" #n ")" ::: "memory")
; #define PG8_BAR __builtin_amdgcn_s_barrier()
; #define PG8_SCHED __builtin_amdgcn_sched_barrier(0)
;     __device__ __forceinline__ int nt(const pg8::Unit& u) const { return u.kind == 0 ? ntiles : q_nt(u.kind - 1); }
; template <class Epi, class Sched, bool ALIGN_EPI = true, bool SP2 = true>
; __device__ __forceinline__ void gemm_phase(PG8_LAS unsigned char* lds, const int K  , const Sched& S, const Epi& E) {
;     ...
;         for (int t = 0; t < nt; t += 2) {
;     ...
;             PG8_LDA(At, 1, 1); PG8_STAGE(PG8_SB(1, 0), b3, voffB); PG8_STAGE(PG8_SB(1, 1), b3 + hstep, voffB); PG8_STAGE(PG8_SA(1, 0), a3, voffA);
;             PG8_WAIT_V(8); PG8_WAIT_L(0); PG8_BAR; PG8_MMA(1, 0, At, B0); PG8_MMA(1, 1, At, B1); PG8_BAR; PG8_SCHED;
	s_setprio 0
	s_add_i32 s24, s48, s29
	v_lshl_add_u64 v[220:221], v[220:221], 0, s[6:7]
	s_mov_b32 m0, s24
	ds_read_b128 v[188:191], v158 offset:49152
	ds_read_b128 v[192:195], v158 offset:50176
	ds_read_b128 v[196:199], v158 offset:51200
	ds_read_b128 v[200:203], v158 offset:52224
	ds_read_b128 v[204:207], v158 offset:53248
	ds_read_b128 v[208:211], v158 offset:54272
	ds_read_b128 v[212:215], v158 offset:55296
	ds_read_b128 v[216:219], v158 offset:56320
	global_load_lds_dwordx4 v[220:221], off
	s_add_i32 m0, s24, 0x2000
	s_add_u32 s22, s22, 0x80080
	v_lshl_add_u64 v[220:221], v[222:223], 0, s[6:7]
	s_addc_u32 s23, s23, 0
	s_add_i32 s24, s49, s29
	global_load_lds_dwordx4 v[220:221], off
	v_lshl_add_u64 v[220:221], s[22:23], 0, v[136:137]
	s_mov_b32 m0, s24
	s_nop 0
	global_load_lds_dwordx4 v[220:221], off
	v_lshl_add_u64 v[220:221], s[22:23], 0, v[132:133]
	s_add_i32 m0, s24, 0x2000
	s_nop 0
	global_load_lds_dwordx4 v[220:221], off
	v_lshl_add_u64 v[220:221], v[224:225], 0, s[6:7]
	s_mov_b32 m0, s37
	s_nop 0
	global_load_lds_dwordx4 v[220:221], off
	v_lshl_add_u64 v[220:221], v[226:227], 0, s[6:7]
	s_mov_b32 m0, s38
	s_nop 0
	global_load_lds_dwordx4 v[220:221], off
	s_add_i32 s47, s47, 2
	s_add_u32 s20, s20, 0x100
	s_addc_u32 s21, s21, 0
	s_add_u32 s45, s45, 0x100
	s_addc_u32 s46, s46, 0
	s_cmp_gt_u32 s47, 29
	s_waitcnt vmcnt(8)
	s_waitcnt lgkmcnt(0)
	s_setprio 1
	s_barrier
	v_mfma_f32_16x16x32_bf16 v[62:65], v[150:153], v[188:191], v[62:65]
	v_mfma_f32_16x16x32_bf16 v[58:61], v[164:167], v[188:191], v[58:61]
	v_mfma_f32_16x16x32_bf16 v[54:57], v[150:153], v[196:199], v[54:57]
	v_mfma_f32_16x16x32_bf16 v[46:49], v[164:167], v[196:199], v[46:49]
	v_mfma_f32_16x16x32_bf16 v[38:41], v[150:153], v[204:207], v[38:41]
	v_mfma_f32_16x16x32_bf16 v[30:33], v[164:167], v[204:207], v[30:33]
	v_mfma_f32_16x16x32_bf16 v[22:25], v[150:153], v[212:215], v[22:25]
	v_mfma_f32_16x16x32_bf16 v[14:17], v[164:167], v[212:215], v[14:17]
	v_mfma_f32_16x16x32_bf16 v[62:65], v[160:163], v[192:195], v[62:65]
	v_mfma_f32_16x16x32_bf16 v[58:61], v[168:171], v[192:195], v[58:61]
	v_mfma_f32_16x16x32_bf16 v[54:57], v[160:163], v[200:203], v[54:57]
	v_mfma_f32_16x16x32_bf16 v[46:49], v[168:171], v[200:203], v[46:49]
	v_mfma_f32_16x16x32_bf16 v[38:41], v[160:163], v[208:211], v[38:41]
	v_mfma_f32_16x16x32_bf16 v[30:33], v[168:171], v[208:211], v[30:33]
	v_mfma_f32_16x16x32_bf16 v[22:25], v[160:163], v[216:219], v[22:25]
	v_mfma_f32_16x16x32_bf16 v[14:17], v[168:171], v[216:219], v[14:17]
	s_setprio 0
	s_setprio 1
	v_mfma_f32_16x16x32_bf16 v[50:53], v[172:175], v[188:191], v[50:53]
	v_mfma_f32_16x16x32_bf16 v[42:45], v[180:183], v[188:191], v[42:45]
	v_mfma_f32_16x16x32_bf16 v[34:37], v[172:175], v[196:199], v[34:37]
	v_mfma_f32_16x16x32_bf16 v[26:29], v[180:183], v[196:199], v[26:29]
	v_mfma_f32_16x16x32_bf16 v[18:21], v[172:175], v[204:207], v[18:21]
	v_mfma_f32_16x16x32_bf16 v[10:13], v[180:183], v[204:207], v[10:13]
	v_mfma_f32_16x16x32_bf16 v[6:9], v[172:175], v[212:215], v[6:9]
	v_mfma_f32_16x16x32_bf16 v[2:5], v[180:183], v[212:215], v[2:5]
	v_mfma_f32_16x16x32_bf16 v[50:53], v[176:179], v[192:195], v[50:53]
	v_mfma_f32_16x16x32_bf16 v[42:45], v[184:187], v[192:195], v[42:45]
	v_mfma_f32_16x16x32_bf16 v[34:37], v[176:179], v[200:203], v[34:37]
	v_mfma_f32_16x16x32_bf16 v[26:29], v[184:187], v[200:203], v[26:29]
	v_mfma_f32_16x16x32_bf16 v[18:21], v[176:179], v[208:211], v[18:21]
	v_mfma_f32_16x16x32_bf16 v[10:13], v[184:187], v[208:211], v[10:13]
	v_mfma_f32_16x16x32_bf16 v[6:9], v[176:179], v[216:219], v[6:9]
	v_mfma_f32_16x16x32_bf16 v[2:5], v[184:187], v[216:219], v[2:5]
	s_barrier
	s_setprio 0
	s_cbranch_scc0 .LBB0_537
	s_and_b64 vcc, exec, s[8:9]
	s_cbranch_vccz .LBB0_540
	s_barrier

; #define PG8_STAGE(bufoff, gbase, voff) do { _Pragma("unroll") for (int _i = 0; _i < 2; ++_i) \
;         __builtin_amdgcn_global_load_lds((const unsigned*)((const char*)(gbase) + (voff)[_i]), (PG8_LAS unsigned*)(lds + (bufoff) + ldsw + _i * 8192), 16, 0, 0); } while (0)
; #define PG8_WAIT_V(n) asm volatile("s_waitcnt vmcnt(" #n ")" ::: "memory")
; #define PG8_WAIT_L(n) asm volatile("s_waitcnt lgkmcnt(" #n ")" ::: "memory")
; #define PG8_BAR __builtin_amdgcn_s_barrier()
; #define PG8_SCHED __builtin_amdgcn_sched_barrier(0)
;     __device__ __forceinline__ int nt(const pg8::Unit& u) const { return u.kind == 0 ? ntiles : q_nt(u.kind - 1); }
; template <class Epi, class Sched, bool ALIGN_EPI = true, bool SP2 = true>
; __device__ __forceinline__ void gemm_phase(PG8_LAS unsigned char* lds, const int K  , const Sched& S, const Epi& E) {
;     ...
;             const bool last = (t == nt - 2);
;             const char* a1 = cA + (size_t)(t + 1) * kstep;
;             const char* a2 = last ? nA : cA + (size_t)(t + 2) * kstep; const char* b2 = last ? nB : cB + (size_t)(t + 2) * kstep;
;             const char* a3 = a2 + kstep; const char* b3 = b2 + kstep;
;             if constexpr (SP2) {
;             PG8_LDB(B0, 0, 0); PG8_LDB(B1, 0, 1); PG8_SCHED; PG8_LDA(At, 0, 0); PG8_STAGE(PG8_SA(1, 1), a1 + hstep, voffA);
;             PG8_WAIT_V(8); PG8_WAIT_L(0); PG8_BAR; PG8_MMA(0, 0, At, B0); PG8_MMA(0, 1, At, B1); PG8_BAR; PG8_SCHED;
;             PG8_LDA(At, 0, 1); PG8_STAGE(PG8_SB(0, 0), b2, voffB); PG8_STAGE(PG8_SB(0, 1), b2 + hstep, voffB); PG8_STAGE(PG8_SA(0, 0), a2, voffA);
;             PG8_WAIT_V(8); PG8_WAIT_L(0); PG8_BAR; PG8_MMA(1, 0, At, B0); PG8_MMA(1, 1, At, B1); PG8_BAR; PG8_SCHED;
.LBB0_955:
	s_waitcnt vmcnt(0)
	ds_read_b128 v[130:133], v232
	ds_read_b128 v[134:137], v232 offset:1024
	ds_read_b128 v[138:141], v232 offset:2048
	ds_read_b128 v[142:145], v232 offset:3072
	ds_read_b128 v[146:149], v233
	ds_read_b128 v[150:153], v233 offset:1024
	ds_read_b128 v[154:157], v233 offset:2048
	ds_read_b128 v[158:161], v233 offset:3072
	s_add_i32 s73, s28, 2
	s_add_u32 s26, s24, 0xfff80080
	s_addc_u32 s27, s25, -1
	s_cmp_eq_u32 s13, s28
	s_cselect_b32 s28, s16, s26
	s_cselect_b32 s29, s17, s27
	s_cselect_b32 s27, s19, s21
	s_cselect_b32 s26, s18, s15
	v_lshl_add_u64 v[194:195], s[24:25], 0, v[214:215]
	s_add_i32 m0, s23, 0xc000
	ds_read_b128 v[162:165], v234
	ds_read_b128 v[166:169], v234 offset:1024
	ds_read_b128 v[170:173], v234 offset:2048
	ds_read_b128 v[174:177], v234 offset:3072
	ds_read_b128 v[178:181], v234 offset:4096
	ds_read_b128 v[182:185], v234 offset:5120
	ds_read_b128 v[186:189], v234 offset:6144
	ds_read_b128 v[190:193], v234 offset:7168
	global_load_lds_dwordx4 v[194:195], off
	v_lshl_add_u64 v[194:195], s[24:25], 0, v[216:217]
	s_add_i32 m0, s23, 0xe000
	s_nop 0
	global_load_lds_dwordx4 v[194:195], off
	s_waitcnt vmcnt(8)
	s_waitcnt lgkmcnt(0)
	s_setprio 1
	s_barrier
	v_mfma_f32_16x16x32_bf16 v[126:129], v[130:133], v[162:165], v[126:129]
	v_mfma_f32_16x16x32_bf16 v[122:125], v[138:141], v[162:165], v[122:125]
	v_mfma_f32_16x16x32_bf16 v[118:121], v[130:133], v[170:173], v[118:121]
	v_mfma_f32_16x16x32_bf16 v[110:113], v[138:141], v[170:173], v[110:113]
	v_mfma_f32_16x16x32_bf16 v[102:105], v[130:133], v[178:181], v[102:105]
	v_mfma_f32_16x16x32_bf16 v[94:97], v[138:141], v[178:181], v[94:97]
	v_mfma_f32_16x16x32_bf16 v[86:89], v[130:133], v[186:189], v[86:89]
	v_mfma_f32_16x16x32_bf16 v[78:81], v[138:141], v[186:189], v[78:81]
	v_mfma_f32_16x16x32_bf16 v[126:129], v[134:137], v[166:169], v[126:129]
	v_mfma_f32_16x16x32_bf16 v[122:125], v[142:145], v[166:169], v[122:125]
	v_mfma_f32_16x16x32_bf16 v[118:121], v[134:137], v[174:177], v[118:121]
	v_mfma_f32_16x16x32_bf16 v[110:113], v[142:145], v[174:177], v[110:113]
	v_mfma_f32_16x16x32_bf16 v[102:105], v[134:137], v[182:185], v[102:105]
	v_mfma_f32_16x16x32_bf16 v[94:97], v[142:145], v[182:185], v[94:97]
	v_mfma_f32_16x16x32_bf16 v[86:89], v[134:137], v[190:193], v[86:89]
	v_mfma_f32_16x16x32_bf16 v[78:81], v[142:145], v[190:193], v[78:81]
	s_setprio 0
	s_setprio 1
	v_mfma_f32_16x16x32_bf16 v[114:117], v[146:149], v[162:165], v[114:117]
	v_mfma_f32_16x16x32_bf16 v[106:109], v[154:157], v[162:165], v[106:109]
	v_mfma_f32_16x16x32_bf16 v[98:101], v[146:149], v[170:173], v[98:101]
	v_mfma_f32_16x16x32_bf16 v[90:93], v[154:157], v[170:173], v[90:93]
	v_mfma_f32_16x16x32_bf16 v[82:85], v[146:149], v[178:181], v[82:85]
	v_mfma_f32_16x16x32_bf16 v[74:77], v[154:157], v[178:181], v[74:77]
	v_mfma_f32_16x16x32_bf16 v[70:73], v[146:149], v[186:189], v[70:73]
	v_mfma_f32_16x16x32_bf16 v[66:69], v[154:157], v[186:189], v[66:69]
	v_mfma_f32_16x16x32_bf16 v[114:117], v[150:153], v[166:169], v[114:117]
	v_mfma_f32_16x16x32_bf16 v[106:109], v[158:161], v[166:169], v[106:109]
	v_mfma_f32_16x16x32_bf16 v[98:101], v[150:153], v[174:177], v[98:101]
	v_mfma_f32_16x16x32_bf16 v[90:93], v[158:161], v[174:177], v[90:93]
	v_mfma_f32_16x16x32_bf16 v[82:85], v[150:153], v[182:185], v[82:85]
	v_mfma_f32_16x16x32_bf16 v[74:77], v[158:161], v[182:185], v[74:77]
	v_mfma_f32_16x16x32_bf16 v[70:73], v[150:153], v[190:193], v[70:73]
	v_mfma_f32_16x16x32_bf16 v[66:69], v[158:161], v[190:193], v[66:69]
	s_barrier
	s_setprio 0
	s_add_i32 s74, s47, s33
	v_lshl_add_u64 v[194:195], s[26:27], 0, v[208:209]
	s_mov_b32 m0, s74
	ds_read_b128 v[162:165], v234 offset:16384
	ds_read_b128 v[166:169], v234 offset:17408
	ds_read_b128 v[170:173], v234 offset:18432
	ds_read_b128 v[174:177], v234 offset:19456
	ds_read_b128 v[178:181], v234 offset:20480
	ds_read_b128 v[182:185], v234 offset:21504
	ds_read_b128 v[186:189], v234 offset:22528
	ds_read_b128 v[190:193], v234 offset:23552
	global_load_lds_dwordx4 v[194:195], off
	s_add_i32 m0, s74, 0x2000
	s_add_u32 s74, s26, 0x80000
	v_lshl_add_u64 v[196:197], s[26:27], 0, v[212:213]
	s_addc_u32 s75, s27, 0
	s_add_i32 s76, s48, s33
	global_load_lds_dwordx4 v[196:197], off
	v_lshl_add_u64 v[198:199], s[74:75], 0, v[208:209]
	s_mov_b32 m0, s76
	v_lshl_add_u64 v[200:201], s[28:29], 0, v[210:211]
	global_load_lds_dwordx4 v[198:199], off
	v_lshl_add_u64 v[198:199], s[74:75], 0, v[212:213]
	s_add_i32 m0, s76, 0x2000
	s_nop 0
	global_load_lds_dwordx4 v[198:199], off
	v_lshl_add_u64 v[198:199], s[28:29], 0, v[206:207]
	s_mov_b32 m0, s23
	s_nop 0
	global_load_lds_dwordx4 v[198:199], off
	s_mov_b32 m0, s34
	s_nop 0
	global_load_lds_dwordx4 v[200:201], off
	s_waitcnt vmcnt(8)
	s_waitcnt lgkmcnt(0)
	s_setprio 1
	s_barrier
; #define PG8_STAGE(bufoff, gbase, voff) do { _Pragma("unroll") for (int _i = 0; _i < 2; ++_i) \
;         __builtin_amdgcn_global_load_lds((const unsigned*)((const char*)(gbase) + (voff)[_i]), (PG8_LAS unsigned*)(lds + (bufoff) + ldsw + _i * 8192), 16, 0, 0); } while (0)
; #define PG8_WAIT_V(n) asm volatile("s_waitcnt vmcnt(" #n ")" ::: "memory")
; #define PG8_WAIT_L(n) asm volatile("s_waitcnt lgkmcnt(" #n ")" ::: "memory")
; #define PG8_BAR __builtin_amdgcn_s_barrier()
; #define PG8_SCHED __builtin_amdgcn_sched_barrier(0)
; template <class Epi, class Sched, bool ALIGN_EPI = true, bool SP2 = true>
; __device__ __forceinline__ void gemm_phase(PG8_LAS unsigned char* lds, const int K  , const Sched& S, const Epi& E) {
;     ...
;             PG8_WAIT_V(8); PG8_WAIT_L(0); PG8_BAR; PG8_MMA(1, 0, At, B0); PG8_MMA(1, 1, At, B1); PG8_BAR; PG8_SCHED;
;             PG8_LDB(B0, 1, 0); PG8_LDB(B1, 1, 1); PG8_SCHED; PG8_LDA(At, 1, 0); PG8_STAGE(PG8_SA(0, 1), a2 + hstep, voffA);
;             PG8_WAIT_V(8); PG8_WAIT_L(0); PG8_BAR; PG8_MMA(0, 0, At, B0); PG8_MMA(0, 1, At, B1); PG8_BAR; PG8_SCHED;
	v_mfma_f32_16x16x32_bf16 v[62:65], v[130:133], v[162:165], v[62:65]
	v_mfma_f32_16x16x32_bf16 v[58:61], v[138:141], v[162:165], v[58:61]
	v_mfma_f32_16x16x32_bf16 v[54:57], v[130:133], v[170:173], v[54:57]
	v_mfma_f32_16x16x32_bf16 v[46:49], v[138:141], v[170:173], v[46:49]
	v_mfma_f32_16x16x32_bf16 v[38:41], v[130:133], v[178:181], v[38:41]
	v_mfma_f32_16x16x32_bf16 v[30:33], v[138:141], v[178:181], v[30:33]
	v_mfma_f32_16x16x32_bf16 v[22:25], v[130:133], v[186:189], v[22:25]
	v_mfma_f32_16x16x32_bf16 v[14:17], v[138:141], v[186:189], v[14:17]
	v_mfma_f32_16x16x32_bf16 v[62:65], v[134:137], v[166:169], v[62:65]
	v_mfma_f32_16x16x32_bf16 v[58:61], v[142:145], v[166:169], v[58:61]
	v_mfma_f32_16x16x32_bf16 v[54:57], v[134:137], v[174:177], v[54:57]
	v_mfma_f32_16x16x32_bf16 v[46:49], v[142:145], v[174:177], v[46:49]
	v_mfma_f32_16x16x32_bf16 v[38:41], v[134:137], v[182:185], v[38:41]
	v_mfma_f32_16x16x32_bf16 v[30:33], v[142:145], v[182:185], v[30:33]
	v_mfma_f32_16x16x32_bf16 v[22:25], v[134:137], v[190:193], v[22:25]
	v_mfma_f32_16x16x32_bf16 v[14:17], v[142:145], v[190:193], v[14:17]
	s_setprio 0
	s_setprio 1
	v_mfma_f32_16x16x32_bf16 v[50:53], v[146:149], v[162:165], v[50:53]
	v_mfma_f32_16x16x32_bf16 v[42:45], v[154:157], v[162:165], v[42:45]
	v_mfma_f32_16x16x32_bf16 v[34:37], v[146:149], v[170:173], v[34:37]
	v_mfma_f32_16x16x32_bf16 v[26:29], v[154:157], v[170:173], v[26:29]
	v_mfma_f32_16x16x32_bf16 v[18:21], v[146:149], v[178:181], v[18:21]
	v_mfma_f32_16x16x32_bf16 v[10:13], v[154:157], v[178:181], v[10:13]
	v_mfma_f32_16x16x32_bf16 v[6:9], v[146:149], v[186:189], v[6:9]
	v_mfma_f32_16x16x32_bf16 v[2:5], v[154:157], v[186:189], v[2:5]
	v_mfma_f32_16x16x32_bf16 v[50:53], v[150:153], v[166:169], v[50:53]
	v_mfma_f32_16x16x32_bf16 v[42:45], v[158:161], v[166:169], v[42:45]
	v_mfma_f32_16x16x32_bf16 v[34:37], v[150:153], v[174:177], v[34:37]
	v_mfma_f32_16x16x32_bf16 v[26:29], v[158:161], v[174:177], v[26:29]
	v_mfma_f32_16x16x32_bf16 v[18:21], v[150:153], v[182:185], v[18:21]
	v_mfma_f32_16x16x32_bf16 v[10:13], v[158:161], v[182:185], v[10:13]
	v_mfma_f32_16x16x32_bf16 v[6:9], v[150:153], v[190:193], v[6:9]
	v_mfma_f32_16x16x32_bf16 v[2:5], v[158:161], v[190:193], v[2:5]
	s_barrier
	s_setprio 0
	s_add_i32 s74, 0, 0x18000
	s_add_i32 s75, 0, 0x1c000
	v_add_u32_e32 v142, s74, v230
	v_add_u32_e32 v158, s75, v230
	ds_read_b128 v[130:133], v142
	ds_read_b128 v[134:137], v142 offset:1024
	ds_read_b128 v[138:141], v142 offset:2048
	ds_read_b128 v[142:145], v142 offset:3072
	ds_read_b128 v[146:149], v158
	ds_read_b128 v[150:153], v158 offset:1024
	ds_read_b128 v[154:157], v158 offset:2048
	ds_read_b128 v[158:161], v158 offset:3072
	s_add_u32 s28, s28, 0x80000
	s_addc_u32 s29, s29, 0
	s_mov_b32 m0, s35
	v_lshl_add_u64 v[202:203], s[28:29], 0, v[206:207]
	ds_read_b128 v[162:165], v234 offset:32768
	ds_read_b128 v[166:169], v234 offset:33792
	ds_read_b128 v[170:173], v234 offset:34816
	ds_read_b128 v[174:177], v234 offset:35840
	ds_read_b128 v[178:181], v234 offset:36864
	ds_read_b128 v[182:185], v234 offset:37888
	ds_read_b128 v[186:189], v234 offset:38912
	ds_read_b128 v[190:193], v234 offset:39936
	global_load_lds_dwordx4 v[202:203], off
	v_lshl_add_u64 v[202:203], s[28:29], 0, v[210:211]
	s_mov_b32 m0, s36
	s_nop 0
	global_load_lds_dwordx4 v[202:203], off
	s_waitcnt vmcnt(8)
	s_waitcnt lgkmcnt(0)
	s_setprio 1
	s_barrier
	v_mfma_f32_16x16x32_bf16 v[126:129], v[130:133], v[162:165], v[126:129]
	v_mfma_f32_16x16x32_bf16 v[122:125], v[138:141], v[162:165], v[122:125]
	v_mfma_f32_16x16x32_bf16 v[118:121], v[130:133], v[170:173], v[118:121]
	v_mfma_f32_16x16x32_bf16 v[110:113], v[138:141], v[170:173], v[110:113]
	v_mfma_f32_16x16x32_bf16 v[102:105], v[130:133], v[178:181], v[102:105]
	v_mfma_f32_16x16x32_bf16 v[94:97], v[138:141], v[178:181], v[94:97]
	v_mfma_f32_16x16x32_bf16 v[86:89], v[130:133], v[186:189], v[86:89]
	v_mfma_f32_16x16x32_bf16 v[78:81], v[138:141], v[186:189], v[78:81]
	v_mfma_f32_16x16x32_bf16 v[126:129], v[134:137], v[166:169], v[126:129]
	v_mfma_f32_16x16x32_bf16 v[122:125], v[142:145], v[166:169], v[122:125]
	v_mfma_f32_16x16x32_bf16 v[118:121], v[134:137], v[174:177], v[118:121]
	v_mfma_f32_16x16x32_bf16 v[110:113], v[142:145], v[174:177], v[110:113]
	v_mfma_f32_16x16x32_bf16 v[102:105], v[134:137], v[182:185], v[102:105]
	v_mfma_f32_16x16x32_bf16 v[94:97], v[142:145], v[182:185], v[94:97]
	v_mfma_f32_16x16x32_bf16 v[86:89], v[134:137], v[190:193], v[86:89]
	v_mfma_f32_16x16x32_bf16 v[78:81], v[142:145], v[190:193], v[78:81]
	s_setprio 0
	s_setprio 1
	v_mfma_f32_16x16x32_bf16 v[114:117], v[146:149], v[162:165], v[114:117]
	v_mfma_f32_16x16x32_bf16 v[106:109], v[154:157], v[162:165], v[106:109]
	v_mfma_f32_16x16x32_bf16 v[98:101], v[146:149], v[170:173], v[98:101]
	v_mfma_f32_16x16x32_bf16 v[90:93], v[154:157], v[170:173], v[90:93]
	v_mfma_f32_16x16x32_bf16 v[82:85], v[146:149], v[178:181], v[82:85]
	v_mfma_f32_16x16x32_bf16 v[74:77], v[154:157], v[178:181], v[74:77]
	v_mfma_f32_16x16x32_bf16 v[70:73], v[146:149], v[186:189], v[70:73]
	v_mfma_f32_16x16x32_bf16 v[66:69], v[154:157], v[186:189], v[66:69]
	v_mfma_f32_16x16x32_bf16 v[114:117], v[150:153], v[166:169], v[114:117]
	v_mfma_f32_16x16x32_bf16 v[106:109], v[158:161], v[166:169], v[106:109]
	v_mfma_f32_16x16x32_bf16 v[98:101], v[150:153], v[174:177], v[98:101]
	v_mfma_f32_16x16x32_bf16 v[90:93], v[158:161], v[174:177], v[90:93]
	v_mfma_f32_16x16x32_bf16 v[82:85], v[150:153], v[182:185], v[82:85]
	v_mfma_f32_16x16x32_bf16 v[74:77], v[158:161], v[182:185], v[74:77]
	v_mfma_f32_16x16x32_bf16 v[70:73], v[150:153], v[190:193], v[70:73]
	v_mfma_f32_16x16x32_bf16 v[66:69], v[158:161], v[190:193], v[66:69]
	s_barrier
; #define PG8_STAGE(bufoff, gbase, voff) do { _Pragma("unroll") for (int _i = 0; _i < 2; ++_i) \
;         __builtin_amdgcn_global_load_lds((const unsigned*)((const char*)(gbase) + (voff)[_i]), (PG8_LAS unsigned*)(lds + (bufoff) + ldsw + _i * 8192), 16, 0, 0); } while (0)
; #define PG8_WAIT_V(n) asm volatile("s_waitcnt vmcnt(" #n ")" ::: "memory")
; #define PG8_WAIT_L(n) asm volatile("s_waitcnt lgkmcnt(" #n ")" ::: "memory")
; #define PG8_BAR __builtin_amdgcn_s_barrier()
; #define PG8_SCHED __builtin_amdgcn_sched_barrier(0)
;     __device__ __forceinline__ int nt(const pg8::Unit& u) const { return u.kind == 0 ? ntiles : q_nt(u.kind - 1); }
; template <class Epi, class Sched, bool ALIGN_EPI = true, bool SP2 = true>
; __device__ __forceinline__ void gemm_phase(PG8_LAS unsigned char* lds, const int K  , const Sched& S, const Epi& E) {
;     ...
;         for (int t = 0; t < nt; t += 2) {
;     ...
;             PG8_LDA(At, 1, 1); PG8_STAGE(PG8_SB(1, 0), b3, voffB); PG8_STAGE(PG8_SB(1, 1), b3 + hstep, voffB); PG8_STAGE(PG8_SA(1, 0), a3, voffA);
;             PG8_WAIT_V(8); PG8_WAIT_L(0); PG8_BAR; PG8_MMA(1, 0, At, B0); PG8_MMA(1, 1, At, B1); PG8_BAR; PG8_SCHED;
	s_setprio 0
	s_add_i32 s28, s74, s33
	v_lshl_add_u64 v[194:195], v[194:195], 0, s[8:9]
	s_mov_b32 m0, s28
	ds_read_b128 v[162:165], v234 offset:49152
	ds_read_b128 v[166:169], v234 offset:50176
	ds_read_b128 v[170:173], v234 offset:51200
	ds_read_b128 v[174:177], v234 offset:52224
	ds_read_b128 v[178:181], v234 offset:53248
	ds_read_b128 v[182:185], v234 offset:54272
	ds_read_b128 v[186:189], v234 offset:55296
	ds_read_b128 v[190:193], v234 offset:56320
	global_load_lds_dwordx4 v[194:195], off
	s_add_i32 m0, s28, 0x2000
	s_add_u32 s26, s26, 0x80080
	v_lshl_add_u64 v[194:195], v[196:197], 0, s[8:9]
	s_addc_u32 s27, s27, 0
	s_add_i32 s28, s75, s33
	global_load_lds_dwordx4 v[194:195], off
	v_lshl_add_u64 v[194:195], s[26:27], 0, v[208:209]
	s_mov_b32 m0, s28
	s_nop 0
	global_load_lds_dwordx4 v[194:195], off
	v_lshl_add_u64 v[194:195], s[26:27], 0, v[212:213]
	s_add_i32 m0, s28, 0x2000
	s_nop 0
	global_load_lds_dwordx4 v[194:195], off
	v_lshl_add_u64 v[194:195], v[198:199], 0, s[8:9]
	s_mov_b32 m0, s42
	s_nop 0
	global_load_lds_dwordx4 v[194:195], off
	v_lshl_add_u64 v[194:195], v[200:201], 0, s[8:9]
	s_mov_b32 m0, s43
	s_nop 0
	global_load_lds_dwordx4 v[194:195], off
	s_add_u32 s24, s24, 0x100
	s_addc_u32 s25, s25, 0
	s_add_u32 s15, s15, 0x100
	s_addc_u32 s21, s21, 0
	s_cmp_ge_u32 s73, s4
	s_mov_b32 s28, s73
	s_waitcnt vmcnt(8)
	s_waitcnt lgkmcnt(0)
	s_setprio 1
	s_barrier
	v_mfma_f32_16x16x32_bf16 v[62:65], v[130:133], v[162:165], v[62:65]
	v_mfma_f32_16x16x32_bf16 v[58:61], v[138:141], v[162:165], v[58:61]
	v_mfma_f32_16x16x32_bf16 v[54:57], v[130:133], v[170:173], v[54:57]
	v_mfma_f32_16x16x32_bf16 v[46:49], v[138:141], v[170:173], v[46:49]
	v_mfma_f32_16x16x32_bf16 v[38:41], v[130:133], v[178:181], v[38:41]
	v_mfma_f32_16x16x32_bf16 v[30:33], v[138:141], v[178:181], v[30:33]
	v_mfma_f32_16x16x32_bf16 v[22:25], v[130:133], v[186:189], v[22:25]
	v_mfma_f32_16x16x32_bf16 v[14:17], v[138:141], v[186:189], v[14:17]
	v_mfma_f32_16x16x32_bf16 v[62:65], v[134:137], v[166:169], v[62:65]
	v_mfma_f32_16x16x32_bf16 v[58:61], v[142:145], v[166:169], v[58:61]
	v_mfma_f32_16x16x32_bf16 v[54:57], v[134:137], v[174:177], v[54:57]
	v_mfma_f32_16x16x32_bf16 v[46:49], v[142:145], v[174:177], v[46:49]
	v_mfma_f32_16x16x32_bf16 v[38:41], v[134:137], v[182:185], v[38:41]
	v_mfma_f32_16x16x32_bf16 v[30:33], v[142:145], v[182:185], v[30:33]
	v_mfma_f32_16x16x32_bf16 v[22:25], v[134:137], v[190:193], v[22:25]
	v_mfma_f32_16x16x32_bf16 v[14:17], v[142:145], v[190:193], v[14:17]
	s_setprio 0
	s_setprio 1
	v_mfma_f32_16x16x32_bf16 v[50:53], v[146:149], v[162:165], v[50:53]
	v_mfma_f32_16x16x32_bf16 v[42:45], v[154:157], v[162:165], v[42:45]
	v_mfma_f32_16x16x32_bf16 v[34:37], v[146:149], v[170:173], v[34:37]
	v_mfma_f32_16x16x32_bf16 v[26:29], v[154:157], v[170:173], v[26:29]
	v_mfma_f32_16x16x32_bf16 v[18:21], v[146:149], v[178:181], v[18:21]
	v_mfma_f32_16x16x32_bf16 v[10:13], v[154:157], v[178:181], v[10:13]
	v_mfma_f32_16x16x32_bf16 v[6:9], v[146:149], v[186:189], v[6:9]
	v_mfma_f32_16x16x32_bf16 v[2:5], v[154:157], v[186:189], v[2:5]
	v_mfma_f32_16x16x32_bf16 v[50:53], v[150:153], v[166:169], v[50:53]
	v_mfma_f32_16x16x32_bf16 v[42:45], v[158:161], v[166:169], v[42:45]
	v_mfma_f32_16x16x32_bf16 v[34:37], v[150:153], v[174:177], v[34:37]
	v_mfma_f32_16x16x32_bf16 v[26:29], v[158:161], v[174:177], v[26:29]
	v_mfma_f32_16x16x32_bf16 v[18:21], v[150:153], v[182:185], v[18:21]
	v_mfma_f32_16x16x32_bf16 v[10:13], v[158:161], v[182:185], v[10:13]
	v_mfma_f32_16x16x32_bf16 v[6:9], v[150:153], v[190:193], v[6:9]
	v_mfma_f32_16x16x32_bf16 v[2:5], v[158:161], v[190:193], v[2:5]
	s_barrier
	s_setprio 0
	s_cbranch_scc0 .LBB0_955
	s_and_b64 vcc, exec, s[10:11]
	s_cbranch_vccz .LBB0_958
	s_barrier

; #define PG8_STAGE(bufoff, gbase, voff) do { _Pragma("unroll") for (int _i = 0; _i < 2; ++_i) \
;         __builtin_amdgcn_global_load_lds((const unsigned*)((const char*)(gbase) + (voff)[_i]), (PG8_LAS unsigned*)(lds + (bufoff) + ldsw + _i * 8192), 16, 0, 0); } while (0)
; #define PG8_WAIT_V(n) asm volatile("s_waitcnt vmcnt(" #n ")" ::: "memory")
; #define PG8_WAIT_L(n) asm volatile("s_waitcnt lgkmcnt(" #n ")" ::: "memory")
; #define PG8_BAR __builtin_amdgcn_s_barrier()
; #define PG8_SCHED __builtin_amdgcn_sched_barrier(0)
;     __device__ __forceinline__ int nt(const pg8::Unit& u) const { return u.kind == 0 ? ntiles : q_nt(u.kind - 1); }
; template <class Epi, class Sched, bool ALIGN_EPI = true, bool SP2 = true>
; __device__ __forceinline__ void gemm_phase(PG8_LAS unsigned char* lds, const int K  , const Sched& S, const Epi& E) {
;     ...
;             const bool last = (t == nt - 2);
;             const char* a1 = cA + (size_t)(t + 1) * kstep;
;             const char* a2 = last ? nA : cA + (size_t)(t + 2) * kstep; const char* b2 = last ? nB : cB + (size_t)(t + 2) * kstep;
;             const char* a3 = a2 + kstep; const char* b3 = b2 + kstep;
;             if constexpr (SP2) {
;             PG8_LDB(B0, 0, 0); PG8_LDB(B1, 0, 1); PG8_SCHED; PG8_LDA(At, 0, 0); PG8_STAGE(PG8_SA(1, 1), a1 + hstep, voffA);
;             PG8_WAIT_V(8); PG8_WAIT_L(0); PG8_BAR; PG8_MMA(0, 0, At, B0); PG8_MMA(0, 1, At, B1); PG8_BAR; PG8_SCHED;
;             PG8_LDA(At, 0, 1); PG8_STAGE(PG8_SB(0, 0), b2, voffB); PG8_STAGE(PG8_SB(0, 1), b2 + hstep, voffB); PG8_STAGE(PG8_SA(0, 0), a2, voffA);
;             PG8_WAIT_V(8); PG8_WAIT_L(0); PG8_BAR; PG8_MMA(1, 0, At, B0); PG8_MMA(1, 1, At, B1); PG8_BAR; PG8_SCHED;
.LBB0_1099:
	ds_read_b128 v[148:151], v154
	ds_read_b128 v[160:163], v154 offset:1024
	ds_read_b128 v[164:167], v154 offset:2048
	ds_read_b128 v[168:171], v154 offset:3072
	ds_read_b128 v[172:175], v155
	ds_read_b128 v[176:179], v155 offset:1024
	ds_read_b128 v[180:183], v155 offset:2048
	ds_read_b128 v[184:187], v155 offset:3072
	s_add_u32 s24, s22, 0xfff80080
	s_addc_u32 s25, s23, -1
	s_cmp_eq_u32 s48, 28
	s_cselect_b32 s27, s15, s25
	s_cselect_b32 s26, s44, s24
	s_cselect_b32 s25, s11, s47
	s_cselect_b32 s24, s45, s46
	v_lshl_add_u64 v[220:221], s[22:23], 0, v[140:141]
	s_add_i32 m0, s21, 0xc000
	ds_read_b128 v[188:191], v156
	ds_read_b128 v[192:195], v156 offset:1024
	ds_read_b128 v[196:199], v156 offset:2048
	ds_read_b128 v[200:203], v156 offset:3072
	ds_read_b128 v[204:207], v156 offset:4096
	ds_read_b128 v[208:211], v156 offset:5120
	ds_read_b128 v[212:215], v156 offset:6144
	ds_read_b128 v[216:219], v156 offset:7168
	global_load_lds_dwordx4 v[220:221], off
	v_lshl_add_u64 v[220:221], s[22:23], 0, v[142:143]
	s_add_i32 m0, s21, 0xe000
	s_nop 0
	global_load_lds_dwordx4 v[220:221], off
	s_waitcnt vmcnt(8)
	s_waitcnt lgkmcnt(0)
	s_setprio 1
	s_barrier
	v_mfma_f32_16x16x32_bf16 v[126:129], v[148:151], v[188:191], v[126:129]
	v_mfma_f32_16x16x32_bf16 v[118:121], v[164:167], v[188:191], v[118:121]
	v_mfma_f32_16x16x32_bf16 v[110:113], v[148:151], v[196:199], v[110:113]
	v_mfma_f32_16x16x32_bf16 v[102:105], v[164:167], v[196:199], v[102:105]
	v_mfma_f32_16x16x32_bf16 v[94:97], v[148:151], v[204:207], v[94:97]
	v_mfma_f32_16x16x32_bf16 v[86:89], v[164:167], v[204:207], v[86:89]
	v_mfma_f32_16x16x32_bf16 v[78:81], v[148:151], v[212:215], v[78:81]
	v_mfma_f32_16x16x32_bf16 v[70:73], v[164:167], v[212:215], v[70:73]
	v_mfma_f32_16x16x32_bf16 v[126:129], v[160:163], v[192:195], v[126:129]
	v_mfma_f32_16x16x32_bf16 v[118:121], v[168:171], v[192:195], v[118:121]
	v_mfma_f32_16x16x32_bf16 v[110:113], v[160:163], v[200:203], v[110:113]
	v_mfma_f32_16x16x32_bf16 v[102:105], v[168:171], v[200:203], v[102:105]
	v_mfma_f32_16x16x32_bf16 v[94:97], v[160:163], v[208:211], v[94:97]
	v_mfma_f32_16x16x32_bf16 v[86:89], v[168:171], v[208:211], v[86:89]
	v_mfma_f32_16x16x32_bf16 v[78:81], v[160:163], v[216:219], v[78:81]
	v_mfma_f32_16x16x32_bf16 v[70:73], v[168:171], v[216:219], v[70:73]
	s_setprio 0
	s_setprio 1
	v_mfma_f32_16x16x32_bf16 v[122:125], v[172:175], v[188:191], v[122:125]
	v_mfma_f32_16x16x32_bf16 v[114:117], v[180:183], v[188:191], v[114:117]
	v_mfma_f32_16x16x32_bf16 v[106:109], v[172:175], v[196:199], v[106:109]
	v_mfma_f32_16x16x32_bf16 v[98:101], v[180:183], v[196:199], v[98:101]
	v_mfma_f32_16x16x32_bf16 v[90:93], v[172:175], v[204:207], v[90:93]
	v_mfma_f32_16x16x32_bf16 v[82:85], v[180:183], v[204:207], v[82:85]
	v_mfma_f32_16x16x32_bf16 v[74:77], v[172:175], v[212:215], v[74:77]
	v_mfma_f32_16x16x32_bf16 v[66:69], v[180:183], v[212:215], v[66:69]
	v_mfma_f32_16x16x32_bf16 v[122:125], v[176:179], v[192:195], v[122:125]
	v_mfma_f32_16x16x32_bf16 v[114:117], v[184:187], v[192:195], v[114:117]
	v_mfma_f32_16x16x32_bf16 v[106:109], v[176:179], v[200:203], v[106:109]
	v_mfma_f32_16x16x32_bf16 v[98:101], v[184:187], v[200:203], v[98:101]
	v_mfma_f32_16x16x32_bf16 v[90:93], v[176:179], v[208:211], v[90:93]
	v_mfma_f32_16x16x32_bf16 v[82:85], v[184:187], v[208:211], v[82:85]
	v_mfma_f32_16x16x32_bf16 v[74:77], v[176:179], v[216:219], v[74:77]
	v_mfma_f32_16x16x32_bf16 v[66:69], v[184:187], v[216:219], v[66:69]
	s_barrier
	s_setprio 0
	s_add_i32 s49, s39, s29
	v_lshl_add_u64 v[220:221], s[24:25], 0, v[136:137]
	s_mov_b32 m0, s49
	ds_read_b128 v[188:191], v156 offset:16384
	ds_read_b128 v[192:195], v156 offset:17408
	ds_read_b128 v[196:199], v156 offset:18432
	ds_read_b128 v[200:203], v156 offset:19456
	ds_read_b128 v[204:207], v156 offset:20480
	ds_read_b128 v[208:211], v156 offset:21504
	ds_read_b128 v[212:215], v156 offset:22528
	ds_read_b128 v[216:219], v156 offset:23552
	global_load_lds_dwordx4 v[220:221], off
	s_add_i32 m0, s49, 0x2000
	s_add_u32 s50, s24, 0x80000
	v_lshl_add_u64 v[222:223], s[24:25], 0, v[132:133]
	s_addc_u32 s51, s25, 0
	s_add_i32 s49, s40, s29
	global_load_lds_dwordx4 v[222:223], off
	v_lshl_add_u64 v[224:225], s[50:51], 0, v[136:137]
	s_mov_b32 m0, s49
	v_lshl_add_u64 v[226:227], s[26:27], 0, v[134:135]
	global_load_lds_dwordx4 v[224:225], off
	v_lshl_add_u64 v[224:225], s[50:51], 0, v[132:133]
	s_add_i32 m0, s49, 0x2000
	s_nop 0
	global_load_lds_dwordx4 v[224:225], off
	v_lshl_add_u64 v[224:225], s[26:27], 0, v[138:139]
	s_mov_b32 m0, s21
	s_nop 0
	global_load_lds_dwordx4 v[224:225], off
	s_mov_b32 m0, s31
	s_nop 0
	global_load_lds_dwordx4 v[226:227], off
	s_waitcnt vmcnt(8)
	s_waitcnt lgkmcnt(0)
	s_setprio 1
	s_barrier
; #define PG8_STAGE(bufoff, gbase, voff) do { _Pragma("unroll") for (int _i = 0; _i < 2; ++_i) \
;         __builtin_amdgcn_global_load_lds((const unsigned*)((const char*)(gbase) + (voff)[_i]), (PG8_LAS unsigned*)(lds + (bufoff) + ldsw + _i * 8192), 16, 0, 0); } while (0)
; #define PG8_WAIT_V(n) asm volatile("s_waitcnt vmcnt(" #n ")" ::: "memory")
; #define PG8_WAIT_L(n) asm volatile("s_waitcnt lgkmcnt(" #n ")" ::: "memory")
; #define PG8_BAR __builtin_amdgcn_s_barrier()
; #define PG8_SCHED __builtin_amdgcn_sched_barrier(0)
; template <class Epi, class Sched, bool ALIGN_EPI = true, bool SP2 = true>
; __device__ __forceinline__ void gemm_phase(PG8_LAS unsigned char* lds, const int K  , const Sched& S, const Epi& E) {
;     ...
;             PG8_WAIT_V(8); PG8_WAIT_L(0); PG8_BAR; PG8_MMA(1, 0, At, B0); PG8_MMA(1, 1, At, B1); PG8_BAR; PG8_SCHED;
;             PG8_LDB(B0, 1, 0); PG8_LDB(B1, 1, 1); PG8_SCHED; PG8_LDA(At, 1, 0); PG8_STAGE(PG8_SA(0, 1), a2 + hstep, voffA);
;             PG8_WAIT_V(8); PG8_WAIT_L(0); PG8_BAR; PG8_MMA(0, 0, At, B0); PG8_MMA(0, 1, At, B1); PG8_BAR; PG8_SCHED;
	v_mfma_f32_16x16x32_bf16 v[62:65], v[148:151], v[188:191], v[62:65]
	v_mfma_f32_16x16x32_bf16 v[54:57], v[164:167], v[188:191], v[54:57]
	v_mfma_f32_16x16x32_bf16 v[46:49], v[148:151], v[196:199], v[46:49]
	v_mfma_f32_16x16x32_bf16 v[38:41], v[164:167], v[196:199], v[38:41]
	v_mfma_f32_16x16x32_bf16 v[30:33], v[148:151], v[204:207], v[30:33]
	v_mfma_f32_16x16x32_bf16 v[22:25], v[164:167], v[204:207], v[22:25]
	v_mfma_f32_16x16x32_bf16 v[14:17], v[148:151], v[212:215], v[14:17]
	v_mfma_f32_16x16x32_bf16 v[6:9], v[164:167], v[212:215], v[6:9]
	v_mfma_f32_16x16x32_bf16 v[62:65], v[160:163], v[192:195], v[62:65]
	v_mfma_f32_16x16x32_bf16 v[54:57], v[168:171], v[192:195], v[54:57]
	v_mfma_f32_16x16x32_bf16 v[46:49], v[160:163], v[200:203], v[46:49]
	v_mfma_f32_16x16x32_bf16 v[38:41], v[168:171], v[200:203], v[38:41]
	v_mfma_f32_16x16x32_bf16 v[30:33], v[160:163], v[208:211], v[30:33]
	v_mfma_f32_16x16x32_bf16 v[22:25], v[168:171], v[208:211], v[22:25]
	v_mfma_f32_16x16x32_bf16 v[14:17], v[160:163], v[216:219], v[14:17]
	v_mfma_f32_16x16x32_bf16 v[6:9], v[168:171], v[216:219], v[6:9]
	s_setprio 0
	s_setprio 1
	v_mfma_f32_16x16x32_bf16 v[58:61], v[172:175], v[188:191], v[58:61]
	v_mfma_f32_16x16x32_bf16 v[50:53], v[180:183], v[188:191], v[50:53]
	v_mfma_f32_16x16x32_bf16 v[42:45], v[172:175], v[196:199], v[42:45]
	v_mfma_f32_16x16x32_bf16 v[34:37], v[180:183], v[196:199], v[34:37]
	v_mfma_f32_16x16x32_bf16 v[26:29], v[172:175], v[204:207], v[26:29]
	v_mfma_f32_16x16x32_bf16 v[18:21], v[180:183], v[204:207], v[18:21]
	v_mfma_f32_16x16x32_bf16 v[10:13], v[172:175], v[212:215], v[10:13]
	v_mfma_f32_16x16x32_bf16 v[2:5], v[180:183], v[212:215], v[2:5]
	v_mfma_f32_16x16x32_bf16 v[58:61], v[176:179], v[192:195], v[58:61]
	v_mfma_f32_16x16x32_bf16 v[50:53], v[184:187], v[192:195], v[50:53]
	v_mfma_f32_16x16x32_bf16 v[42:45], v[176:179], v[200:203], v[42:45]
	v_mfma_f32_16x16x32_bf16 v[34:37], v[184:187], v[200:203], v[34:37]
	v_mfma_f32_16x16x32_bf16 v[26:29], v[176:179], v[208:211], v[26:29]
	v_mfma_f32_16x16x32_bf16 v[18:21], v[184:187], v[208:211], v[18:21]
	v_mfma_f32_16x16x32_bf16 v[10:13], v[176:179], v[216:219], v[10:13]
	v_mfma_f32_16x16x32_bf16 v[2:5], v[184:187], v[216:219], v[2:5]
	s_barrier
	s_setprio 0
	s_add_i32 s49, 0, 0x18000
	v_add_u32_e32 v159, s49, v152
	s_add_i32 s50, 0, 0x1c000
	ds_read_b128 v[148:151], v159
	ds_read_b128 v[160:163], v159 offset:1024
	ds_read_b128 v[164:167], v159 offset:2048
	ds_read_b128 v[168:171], v159 offset:3072
	v_add_u32_e32 v159, s50, v152
	ds_read_b128 v[172:175], v159
	ds_read_b128 v[176:179], v159 offset:1024
	ds_read_b128 v[180:183], v159 offset:2048
	ds_read_b128 v[184:187], v159 offset:3072
	s_add_u32 s26, s26, 0x80000
	s_addc_u32 s27, s27, 0
	s_mov_b32 m0, s33
	v_lshl_add_u64 v[230:231], s[26:27], 0, v[138:139]
	ds_read_b128 v[188:191], v156 offset:32768
	ds_read_b128 v[192:195], v156 offset:33792
	ds_read_b128 v[196:199], v156 offset:34816
	ds_read_b128 v[200:203], v156 offset:35840
	ds_read_b128 v[204:207], v156 offset:36864
	ds_read_b128 v[208:211], v156 offset:37888
	ds_read_b128 v[212:215], v156 offset:38912
	ds_read_b128 v[216:219], v156 offset:39936
	global_load_lds_dwordx4 v[230:231], off
	v_lshl_add_u64 v[230:231], s[26:27], 0, v[134:135]
	s_mov_b32 m0, s34
	s_nop 0
	global_load_lds_dwordx4 v[230:231], off
	s_waitcnt vmcnt(8)
	s_waitcnt lgkmcnt(0)
	s_setprio 1
	s_barrier
	v_mfma_f32_16x16x32_bf16 v[126:129], v[148:151], v[188:191], v[126:129]
	v_mfma_f32_16x16x32_bf16 v[118:121], v[164:167], v[188:191], v[118:121]
	v_mfma_f32_16x16x32_bf16 v[110:113], v[148:151], v[196:199], v[110:113]
	v_mfma_f32_16x16x32_bf16 v[102:105], v[164:167], v[196:199], v[102:105]
	v_mfma_f32_16x16x32_bf16 v[94:97], v[148:151], v[204:207], v[94:97]
	v_mfma_f32_16x16x32_bf16 v[86:89], v[164:167], v[204:207], v[86:89]
	v_mfma_f32_16x16x32_bf16 v[78:81], v[148:151], v[212:215], v[78:81]
	v_mfma_f32_16x16x32_bf16 v[70:73], v[164:167], v[212:215], v[70:73]
	v_mfma_f32_16x16x32_bf16 v[126:129], v[160:163], v[192:195], v[126:129]
	v_mfma_f32_16x16x32_bf16 v[118:121], v[168:171], v[192:195], v[118:121]
	v_mfma_f32_16x16x32_bf16 v[110:113], v[160:163], v[200:203], v[110:113]
	v_mfma_f32_16x16x32_bf16 v[102:105], v[168:171], v[200:203], v[102:105]
	v_mfma_f32_16x16x32_bf16 v[94:97], v[160:163], v[208:211], v[94:97]
	v_mfma_f32_16x16x32_bf16 v[86:89], v[168:171], v[208:211], v[86:89]
	v_mfma_f32_16x16x32_bf16 v[78:81], v[160:163], v[216:219], v[78:81]
	v_mfma_f32_16x16x32_bf16 v[70:73], v[168:171], v[216:219], v[70:73]
	s_setprio 0
	s_setprio 1
	v_mfma_f32_16x16x32_bf16 v[122:125], v[172:175], v[188:191], v[122:125]
	v_mfma_f32_16x16x32_bf16 v[114:117], v[180:183], v[188:191], v[114:117]
	v_mfma_f32_16x16x32_bf16 v[106:109], v[172:175], v[196:199], v[106:109]
	v_mfma_f32_16x16x32_bf16 v[98:101], v[180:183], v[196:199], v[98:101]
	v_mfma_f32_16x16x32_bf16 v[90:93], v[172:175], v[204:207], v[90:93]
	v_mfma_f32_16x16x32_bf16 v[82:85], v[180:183], v[204:207], v[82:85]
	v_mfma_f32_16x16x32_bf16 v[74:77], v[172:175], v[212:215], v[74:77]
	v_mfma_f32_16x16x32_bf16 v[66:69], v[180:183], v[212:215], v[66:69]
	v_mfma_f32_16x16x32_bf16 v[122:125], v[176:179], v[192:195], v[122:125]
	v_mfma_f32_16x16x32_bf16 v[114:117], v[184:187], v[192:195], v[114:117]
	v_mfma_f32_16x16x32_bf16 v[106:109], v[176:179], v[200:203], v[106:109]
	v_mfma_f32_16x16x32_bf16 v[98:101], v[184:187], v[200:203], v[98:101]
	v_mfma_f32_16x16x32_bf16 v[90:93], v[176:179], v[208:211], v[90:93]
	v_mfma_f32_16x16x32_bf16 v[82:85], v[184:187], v[208:211], v[82:85]
	v_mfma_f32_16x16x32_bf16 v[74:77], v[176:179], v[216:219], v[74:77]
	v_mfma_f32_16x16x32_bf16 v[66:69], v[184:187], v[216:219], v[66:69]
	s_barrier
; #define PG8_STAGE(bufoff, gbase, voff) do { _Pragma("unroll") for (int _i = 0; _i < 2; ++_i) \
;         __builtin_amdgcn_global_load_lds((const unsigned*)((const char*)(gbase) + (voff)[_i]), (PG8_LAS unsigned*)(lds + (bufoff) + ldsw + _i * 8192), 16, 0, 0); } while (0)
; #define PG8_WAIT_V(n) asm volatile("s_waitcnt vmcnt(" #n ")" ::: "memory")
; #define PG8_WAIT_L(n) asm volatile("s_waitcnt lgkmcnt(" #n ")" ::: "memory")
; #define PG8_BAR __builtin_amdgcn_s_barrier()
; #define PG8_SCHED __builtin_amdgcn_sched_barrier(0)
;     __device__ __forceinline__ int nt(const pg8::Unit& u) const { return u.kind == 0 ? ntiles : q_nt(u.kind - 1); }
; template <class Epi, class Sched, bool ALIGN_EPI = true, bool SP2 = true>
; __device__ __forceinline__ void gemm_phase(PG8_LAS unsigned char* lds, const int K  , const Sched& S, const Epi& E) {
;     ...
;         for (int t = 0; t < nt; t += 2) {
;     ...
;             PG8_LDA(At, 1, 1); PG8_STAGE(PG8_SB(1, 0), b3, voffB); PG8_STAGE(PG8_SB(1, 1), b3 + hstep, voffB); PG8_STAGE(PG8_SA(1, 0), a3, voffA);
;             PG8_WAIT_V(8); PG8_WAIT_L(0); PG8_BAR; PG8_MMA(1, 0, At, B0); PG8_MMA(1, 1, At, B1); PG8_BAR; PG8_SCHED;
	s_setprio 0
	s_add_i32 s26, s49, s29
	v_lshl_add_u64 v[220:221], v[220:221], 0, s[4:5]
	s_mov_b32 m0, s26
	ds_read_b128 v[188:191], v156 offset:49152
	ds_read_b128 v[192:195], v156 offset:50176
	ds_read_b128 v[196:199], v156 offset:51200
	ds_read_b128 v[200:203], v156 offset:52224
	ds_read_b128 v[204:207], v156 offset:53248
	ds_read_b128 v[208:211], v156 offset:54272
	ds_read_b128 v[212:215], v156 offset:55296
	ds_read_b128 v[216:219], v156 offset:56320
	global_load_lds_dwordx4 v[220:221], off
	s_add_i32 m0, s26, 0x2000
	s_add_u32 s24, s24, 0x80080
	v_lshl_add_u64 v[220:221], v[222:223], 0, s[4:5]
	s_addc_u32 s25, s25, 0
	s_add_i32 s26, s50, s29
	global_load_lds_dwordx4 v[220:221], off
	v_lshl_add_u64 v[220:221], s[24:25], 0, v[136:137]
	s_mov_b32 m0, s26
	s_nop 0
	global_load_lds_dwordx4 v[220:221], off
	v_lshl_add_u64 v[220:221], s[24:25], 0, v[132:133]
	s_add_i32 m0, s26, 0x2000
	s_nop 0
	global_load_lds_dwordx4 v[220:221], off
	v_lshl_add_u64 v[220:221], v[224:225], 0, s[4:5]
	s_mov_b32 m0, s36
	s_nop 0
	global_load_lds_dwordx4 v[220:221], off
	v_lshl_add_u64 v[220:221], v[226:227], 0, s[4:5]
	s_mov_b32 m0, s37
	s_nop 0
	global_load_lds_dwordx4 v[220:221], off
	s_add_i32 s48, s48, 2
	s_add_u32 s22, s22, 0x100
	s_addc_u32 s23, s23, 0
	s_add_u32 s46, s46, 0x100
	s_addc_u32 s47, s47, 0
	s_cmp_gt_u32 s48, 29
	s_waitcnt vmcnt(8)
	s_waitcnt lgkmcnt(0)
	s_setprio 1
	s_barrier
	v_mfma_f32_16x16x32_bf16 v[62:65], v[148:151], v[188:191], v[62:65]
	v_mfma_f32_16x16x32_bf16 v[54:57], v[164:167], v[188:191], v[54:57]
	v_mfma_f32_16x16x32_bf16 v[46:49], v[148:151], v[196:199], v[46:49]
	v_mfma_f32_16x16x32_bf16 v[38:41], v[164:167], v[196:199], v[38:41]
	v_mfma_f32_16x16x32_bf16 v[30:33], v[148:151], v[204:207], v[30:33]
	v_mfma_f32_16x16x32_bf16 v[22:25], v[164:167], v[204:207], v[22:25]
	v_mfma_f32_16x16x32_bf16 v[14:17], v[148:151], v[212:215], v[14:17]
	v_mfma_f32_16x16x32_bf16 v[6:9], v[164:167], v[212:215], v[6:9]
	v_mfma_f32_16x16x32_bf16 v[62:65], v[160:163], v[192:195], v[62:65]
	v_mfma_f32_16x16x32_bf16 v[54:57], v[168:171], v[192:195], v[54:57]
	v_mfma_f32_16x16x32_bf16 v[46:49], v[160:163], v[200:203], v[46:49]
	v_mfma_f32_16x16x32_bf16 v[38:41], v[168:171], v[200:203], v[38:41]
	v_mfma_f32_16x16x32_bf16 v[30:33], v[160:163], v[208:211], v[30:33]
	v_mfma_f32_16x16x32_bf16 v[22:25], v[168:171], v[208:211], v[22:25]
	v_mfma_f32_16x16x32_bf16 v[14:17], v[160:163], v[216:219], v[14:17]
	v_mfma_f32_16x16x32_bf16 v[6:9], v[168:171], v[216:219], v[6:9]
	s_setprio 0
	s_setprio 1
	v_mfma_f32_16x16x32_bf16 v[58:61], v[172:175], v[188:191], v[58:61]
	v_mfma_f32_16x16x32_bf16 v[50:53], v[180:183], v[188:191], v[50:53]
	v_mfma_f32_16x16x32_bf16 v[42:45], v[172:175], v[196:199], v[42:45]
	v_mfma_f32_16x16x32_bf16 v[34:37], v[180:183], v[196:199], v[34:37]
	v_mfma_f32_16x16x32_bf16 v[26:29], v[172:175], v[204:207], v[26:29]
	v_mfma_f32_16x16x32_bf16 v[18:21], v[180:183], v[204:207], v[18:21]
	v_mfma_f32_16x16x32_bf16 v[10:13], v[172:175], v[212:215], v[10:13]
	v_mfma_f32_16x16x32_bf16 v[2:5], v[180:183], v[212:215], v[2:5]
	v_mfma_f32_16x16x32_bf16 v[58:61], v[176:179], v[192:195], v[58:61]
	v_mfma_f32_16x16x32_bf16 v[50:53], v[184:187], v[192:195], v[50:53]
	v_mfma_f32_16x16x32_bf16 v[42:45], v[176:179], v[200:203], v[42:45]
	v_mfma_f32_16x16x32_bf16 v[34:37], v[184:187], v[200:203], v[34:37]
	v_mfma_f32_16x16x32_bf16 v[26:29], v[176:179], v[208:211], v[26:29]
	v_mfma_f32_16x16x32_bf16 v[18:21], v[184:187], v[208:211], v[18:21]
	v_mfma_f32_16x16x32_bf16 v[10:13], v[176:179], v[216:219], v[10:13]
	v_mfma_f32_16x16x32_bf16 v[2:5], v[184:187], v[216:219], v[2:5]
	s_barrier
	s_setprio 0
	s_cbranch_scc0 .LBB0_1099
	s_and_b64 vcc, exec, s[8:9]
	s_cbranch_vccz .LBB0_1102
	s_barrier

; #define PG8_STAGE(bufoff, gbase, voff) do { _Pragma("unroll") for (int _i = 0; _i < 2; ++_i) \
;         __builtin_amdgcn_global_load_lds((const unsigned*)((const char*)(gbase) + (voff)[_i]), (PG8_LAS unsigned*)(lds + (bufoff) + ldsw + _i * 8192), 16, 0, 0); } while (0)
; #define PG8_WAIT_V(n) asm volatile("s_waitcnt vmcnt(" #n ")" ::: "memory")
; #define PG8_WAIT_L(n) asm volatile("s_waitcnt lgkmcnt(" #n ")" ::: "memory")
; #define PG8_BAR __builtin_amdgcn_s_barrier()
; #define PG8_SCHED __builtin_amdgcn_sched_barrier(0)
;     __device__ __forceinline__ int nt(const pg8::Unit& u) const { return u.kind == 0 ? ntiles : q_nt(u.kind - 1); }
; template <class Epi, class Sched, bool ALIGN_EPI = true, bool SP2 = true>
; __device__ __forceinline__ void gemm_phase(PG8_LAS unsigned char* lds, const int K  , const Sched& S, const Epi& E) {
;     ...
;             const bool last = (t == nt - 2);
;             const char* a1 = cA + (size_t)(t + 1) * kstep;
;             const char* a2 = last ? nA : cA + (size_t)(t + 2) * kstep; const char* b2 = last ? nB : cB + (size_t)(t + 2) * kstep;
;             const char* a3 = a2 + kstep; const char* b3 = b2 + kstep;
;             if constexpr (SP2) {
;             PG8_LDB(B0, 0, 0); PG8_LDB(B1, 0, 1); PG8_SCHED; PG8_LDA(At, 0, 0); PG8_STAGE(PG8_SA(1, 1), a1 + hstep, voffA);
;             PG8_WAIT_V(8); PG8_WAIT_L(0); PG8_BAR; PG8_MMA(0, 0, At, B0); PG8_MMA(0, 1, At, B1); PG8_BAR; PG8_SCHED;
;             PG8_LDA(At, 0, 1); PG8_STAGE(PG8_SB(0, 0), b2, voffB); PG8_STAGE(PG8_SB(0, 1), b2 + hstep, voffB); PG8_STAGE(PG8_SA(0, 0), a2, voffA);
;             PG8_WAIT_V(8); PG8_WAIT_L(0); PG8_BAR; PG8_MMA(1, 0, At, B0); PG8_MMA(1, 1, At, B1); PG8_BAR; PG8_SCHED;
.LBB0_1304:
	ds_read_b128 v[18:21], v233
	ds_read_b128 v[22:25], v233 offset:1024
	ds_read_b128 v[26:29], v233 offset:2048
	ds_read_b128 v[30:33], v233 offset:3072
	ds_read_b128 v[2:5], v234
	ds_read_b128 v[6:9], v234 offset:1024
	ds_read_b128 v[10:13], v234 offset:2048
	ds_read_b128 v[14:17], v234 offset:3072
	s_add_i32 s74, s22, 2
	s_add_u32 s20, s18, 0xfff50080
	s_addc_u32 s21, s19, -1
	s_cmp_eq_u32 s71, s22
	s_cselect_b32 s22, s14, s20
	s_cselect_b32 s23, s15, s21
	s_cselect_b32 s21, s17, s73
	s_cselect_b32 s20, s16, s72
	v_lshl_add_u64 v[186:187], s[18:19], 0, v[198:199]
	s_add_i32 m0, s26, 0xc000
	ds_read_b128 v[162:165], v235
	ds_read_b128 v[166:169], v235 offset:1024
	ds_read_b128 v[170:173], v235 offset:2048
	ds_read_b128 v[174:177], v235 offset:3072
	ds_read_b128 v[178:181], v235 offset:4096
	ds_read_b128 v[182:185], v235 offset:5120
	ds_read_b128 v[206:209], v235 offset:6144
	ds_read_b128 v[210:213], v235 offset:7168
	global_load_lds_dwordx4 v[186:187], off
	v_lshl_add_u64 v[186:187], s[18:19], 0, v[200:201]
	s_add_i32 m0, s26, 0xe000
	s_nop 0
	global_load_lds_dwordx4 v[186:187], off
	s_waitcnt vmcnt(8)
	s_waitcnt lgkmcnt(0)
	s_setprio 1
	s_barrier
	v_mfma_scale_f32_16x16x128_f8f6f4 v[158:161], v[18:25], v[162:169], v[158:161], v229, v229 op_sel_hi:[0,0,0]
	v_mfma_scale_f32_16x16x128_f8f6f4 v[154:157], v[26:33], v[162:169], v[154:157], v229, v229 op_sel_hi:[0,0,0]
	v_mfma_scale_f32_16x16x128_f8f6f4 v[150:153], v[18:25], v[170:177], v[150:153], v229, v229 op_sel_hi:[0,0,0]
	v_mfma_scale_f32_16x16x128_f8f6f4 v[142:145], v[26:33], v[170:177], v[142:145], v229, v229 op_sel_hi:[0,0,0]
	v_mfma_scale_f32_16x16x128_f8f6f4 v[134:137], v[18:25], v[178:185], v[134:137], v229, v229 op_sel_hi:[0,0,0]
	v_mfma_scale_f32_16x16x128_f8f6f4 v[126:129], v[26:33], v[178:185], v[126:129], v229, v229 op_sel_hi:[0,0,0]
	v_mfma_scale_f32_16x16x128_f8f6f4 v[118:121], v[18:25], v[206:213], v[118:121], v229, v229 op_sel_hi:[0,0,0]
	v_mfma_scale_f32_16x16x128_f8f6f4 v[110:113], v[26:33], v[206:213], v[110:113], v229, v229 op_sel_hi:[0,0,0]
	s_setprio 0
	s_setprio 1
	v_mfma_scale_f32_16x16x128_f8f6f4 v[146:149], v[2:9], v[162:169], v[146:149], v229, v229 op_sel_hi:[0,0,0]
	v_mfma_scale_f32_16x16x128_f8f6f4 v[138:141], v[10:17], v[162:169], v[138:141], v229, v229 op_sel_hi:[0,0,0]
	v_mfma_scale_f32_16x16x128_f8f6f4 v[130:133], v[2:9], v[170:177], v[130:133], v229, v229 op_sel_hi:[0,0,0]
	v_mfma_scale_f32_16x16x128_f8f6f4 v[122:125], v[10:17], v[170:177], v[122:125], v229, v229 op_sel_hi:[0,0,0]
	v_mfma_scale_f32_16x16x128_f8f6f4 v[114:117], v[2:9], v[178:185], v[114:117], v229, v229 op_sel_hi:[0,0,0]
	v_mfma_scale_f32_16x16x128_f8f6f4 v[106:109], v[10:17], v[178:185], v[106:109], v229, v229 op_sel_hi:[0,0,0]
	v_mfma_scale_f32_16x16x128_f8f6f4 v[102:105], v[2:9], v[206:213], v[102:105], v229, v229 op_sel_hi:[0,0,0]
	v_mfma_scale_f32_16x16x128_f8f6f4 v[98:101], v[10:17], v[206:213], v[98:101], v229, v229 op_sel_hi:[0,0,0]
	s_barrier
	s_setprio 0
	s_add_i32 s75, s40, s25
	v_lshl_add_u64 v[162:163], s[20:21], 0, v[192:193]
	s_mov_b32 m0, s75
	ds_read_b128 v[170:173], v235 offset:16384
	ds_read_b128 v[174:177], v235 offset:17408
	ds_read_b128 v[178:181], v235 offset:18432
	ds_read_b128 v[182:185], v235 offset:19456
	ds_read_b128 v[206:209], v235 offset:20480
	ds_read_b128 v[210:213], v235 offset:21504
	ds_read_b128 v[214:217], v235 offset:22528
	ds_read_b128 v[218:221], v235 offset:23552
	global_load_lds_dwordx4 v[162:163], off
	s_add_i32 m0, s75, 0x2000
	s_add_u32 s76, s20, 0xb0000
	v_lshl_add_u64 v[164:165], s[20:21], 0, v[196:197]
	s_addc_u32 s77, s21, 0
	s_add_i32 s75, s41, s25
	global_load_lds_dwordx4 v[164:165], off
	v_lshl_add_u64 v[166:167], s[76:77], 0, v[192:193]
	s_mov_b32 m0, s75
	v_lshl_add_u64 v[168:169], s[22:23], 0, v[194:195]
	global_load_lds_dwordx4 v[166:167], off
	v_lshl_add_u64 v[166:167], s[76:77], 0, v[196:197]
	s_add_i32 m0, s75, 0x2000
	s_nop 0
	global_load_lds_dwordx4 v[166:167], off
	v_lshl_add_u64 v[166:167], s[22:23], 0, v[190:191]
	s_mov_b32 m0, s26
	s_nop 0
	global_load_lds_dwordx4 v[166:167], off
	s_mov_b32 m0, s27
	s_nop 0
	global_load_lds_dwordx4 v[168:169], off
	s_waitcnt vmcnt(8)
	s_waitcnt lgkmcnt(0)
	s_setprio 1
	s_barrier
	v_mfma_scale_f32_16x16x128_f8f6f4 v[94:97], v[18:25], v[170:177], v[94:97], v229, v229 op_sel_hi:[0,0,0]
	v_mfma_scale_f32_16x16x128_f8f6f4 v[90:93], v[26:33], v[170:177], v[90:93], v229, v229 op_sel_hi:[0,0,0]
	v_mfma_scale_f32_16x16x128_f8f6f4 v[86:89], v[18:25], v[178:185], v[86:89], v229, v229 op_sel_hi:[0,0,0]
	v_mfma_scale_f32_16x16x128_f8f6f4 v[78:81], v[26:33], v[178:185], v[78:81], v229, v229 op_sel_hi:[0,0,0]
	v_mfma_scale_f32_16x16x128_f8f6f4 v[70:73], v[18:25], v[206:213], v[70:73], v229, v229 op_sel_hi:[0,0,0]
	v_mfma_scale_f32_16x16x128_f8f6f4 v[62:65], v[26:33], v[206:213], v[62:65], v229, v229 op_sel_hi:[0,0,0]
	v_mfma_scale_f32_16x16x128_f8f6f4 v[54:57], v[18:25], v[214:221], v[54:57], v229, v229 op_sel_hi:[0,0,0]
	v_mfma_scale_f32_16x16x128_f8f6f4 v[46:49], v[26:33], v[214:221], v[46:49], v229, v229 op_sel_hi:[0,0,0]
	s_setprio 0
	s_setprio 1
	v_mfma_scale_f32_16x16x128_f8f6f4 v[82:85], v[2:9], v[170:177], v[82:85], v229, v229 op_sel_hi:[0,0,0]
	v_mfma_scale_f32_16x16x128_f8f6f4 v[74:77], v[10:17], v[170:177], v[74:77], v229, v229 op_sel_hi:[0,0,0]
	v_mfma_scale_f32_16x16x128_f8f6f4 v[66:69], v[2:9], v[178:185], v[66:69], v229, v229 op_sel_hi:[0,0,0]
	v_mfma_scale_f32_16x16x128_f8f6f4 v[58:61], v[10:17], v[178:185], v[58:61], v229, v229 op_sel_hi:[0,0,0]
	v_mfma_scale_f32_16x16x128_f8f6f4 v[50:53], v[2:9], v[206:213], v[50:53], v229, v229 op_sel_hi:[0,0,0]
	v_mfma_scale_f32_16x16x128_f8f6f4 v[42:45], v[10:17], v[206:213], v[42:45], v229, v229 op_sel_hi:[0,0,0]
	v_mfma_scale_f32_16x16x128_f8f6f4 v[38:41], v[2:9], v[214:221], v[38:41], v229, v229 op_sel_hi:[0,0,0]
	v_mfma_scale_f32_16x16x128_f8f6f4 v[34:37], v[10:17], v[214:221], v[34:37], v229, v229 op_sel_hi:[0,0,0]
	s_barrier
; #define PG8_STAGE(bufoff, gbase, voff) do { _Pragma("unroll") for (int _i = 0; _i < 2; ++_i) \
;         __builtin_amdgcn_global_load_lds((const unsigned*)((const char*)(gbase) + (voff)[_i]), (PG8_LAS unsigned*)(lds + (bufoff) + ldsw + _i * 8192), 16, 0, 0); } while (0)
; #define PG8_WAIT_V(n) asm volatile("s_waitcnt vmcnt(" #n ")" ::: "memory")
; #define PG8_WAIT_L(n) asm volatile("s_waitcnt lgkmcnt(" #n ")" ::: "memory")
; #define PG8_BAR __builtin_amdgcn_s_barrier()
; #define PG8_SCHED __builtin_amdgcn_sched_barrier(0)
;     __device__ __forceinline__ int nt(const pg8::Unit& u) const { return u.kind == 0 ? ntiles : q_nt(u.kind - 1); }
; template <class Epi, class Sched, bool ALIGN_EPI = true, bool SP2 = true>
; __device__ __forceinline__ void gemm_phase(PG8_LAS unsigned char* lds, const int K  , const Sched& S, const Epi& E) {
;     ...
;         for (int t = 0; t < nt; t += 2) {
;     ...
;             PG8_LDB(B0, 1, 0); PG8_LDB(B1, 1, 1); PG8_SCHED; PG8_LDA(At, 1, 0); PG8_STAGE(PG8_SA(0, 1), a2 + hstep, voffA);
;             PG8_WAIT_V(8); PG8_WAIT_L(0); PG8_BAR; PG8_MMA(0, 0, At, B0); PG8_MMA(0, 1, At, B1); PG8_BAR; PG8_SCHED;
;             PG8_LDA(At, 1, 1); PG8_STAGE(PG8_SB(1, 0), b3, voffB); PG8_STAGE(PG8_SB(1, 1), b3 + hstep, voffB); PG8_STAGE(PG8_SA(1, 0), a3, voffA);
;             PG8_WAIT_V(8); PG8_WAIT_L(0); PG8_BAR; PG8_MMA(1, 0, At, B0); PG8_MMA(1, 1, At, B1); PG8_BAR; PG8_SCHED;
;     ...
;         if constexpr (Epi::FP8) asm volatile("s_nop 15\n\ts_nop 15\n\ts_nop 15\n\ts_nop 15\n\ts_nop 15" ::: "memory");
;         if constexpr (ALIGN_EPI) { if (wr == 0) PG8_BAR; }
	s_setprio 0
	s_add_i32 s75, 0, 0x18000
	s_add_i32 s76, 0, 0x1c000
	v_add_u32_e32 v14, s75, v231
	v_add_u32_e32 v30, s76, v231
	ds_read_b128 v[2:5], v14
	ds_read_b128 v[6:9], v14 offset:1024
	ds_read_b128 v[10:13], v14 offset:2048
	ds_read_b128 v[14:17], v14 offset:3072
	ds_read_b128 v[18:21], v30
	ds_read_b128 v[22:25], v30 offset:1024
	ds_read_b128 v[26:29], v30 offset:2048
	ds_read_b128 v[30:33], v30 offset:3072
	s_add_u32 s22, s22, 0xb0000
	s_addc_u32 s23, s23, 0
	s_mov_b32 m0, s28
	v_lshl_add_u64 v[186:187], s[22:23], 0, v[190:191]
	ds_read_b128 v[170:173], v235 offset:32768
	ds_read_b128 v[174:177], v235 offset:33792
	ds_read_b128 v[178:181], v235 offset:34816
	ds_read_b128 v[182:185], v235 offset:35840
	ds_read_b128 v[206:209], v235 offset:36864
	ds_read_b128 v[210:213], v235 offset:37888
	ds_read_b128 v[214:217], v235 offset:38912
	ds_read_b128 v[218:221], v235 offset:39936
	global_load_lds_dwordx4 v[186:187], off
	v_lshl_add_u64 v[186:187], s[22:23], 0, v[194:195]
	s_mov_b32 m0, s29
	s_nop 0
	global_load_lds_dwordx4 v[186:187], off
	s_waitcnt vmcnt(8)
	s_waitcnt lgkmcnt(0)
	s_setprio 1
	s_barrier
	v_mfma_scale_f32_16x16x128_f8f6f4 v[158:161], v[2:9], v[170:177], v[158:161], v229, v229 op_sel_hi:[0,0,0]
	v_mfma_scale_f32_16x16x128_f8f6f4 v[154:157], v[10:17], v[170:177], v[154:157], v229, v229 op_sel_hi:[0,0,0]
	v_mfma_scale_f32_16x16x128_f8f6f4 v[150:153], v[2:9], v[178:185], v[150:153], v229, v229 op_sel_hi:[0,0,0]
	v_mfma_scale_f32_16x16x128_f8f6f4 v[142:145], v[10:17], v[178:185], v[142:145], v229, v229 op_sel_hi:[0,0,0]
	v_mfma_scale_f32_16x16x128_f8f6f4 v[134:137], v[2:9], v[206:213], v[134:137], v229, v229 op_sel_hi:[0,0,0]
	v_mfma_scale_f32_16x16x128_f8f6f4 v[126:129], v[10:17], v[206:213], v[126:129], v229, v229 op_sel_hi:[0,0,0]
	v_mfma_scale_f32_16x16x128_f8f6f4 v[118:121], v[2:9], v[214:221], v[118:121], v229, v229 op_sel_hi:[0,0,0]
	v_mfma_scale_f32_16x16x128_f8f6f4 v[110:113], v[10:17], v[214:221], v[110:113], v229, v229 op_sel_hi:[0,0,0]
	s_setprio 0
	s_setprio 1
	v_mfma_scale_f32_16x16x128_f8f6f4 v[146:149], v[18:25], v[170:177], v[146:149], v229, v229 op_sel_hi:[0,0,0]
	v_mfma_scale_f32_16x16x128_f8f6f4 v[138:141], v[26:33], v[170:177], v[138:141], v229, v229 op_sel_hi:[0,0,0]
	v_mfma_scale_f32_16x16x128_f8f6f4 v[130:133], v[18:25], v[178:185], v[130:133], v229, v229 op_sel_hi:[0,0,0]
	v_mfma_scale_f32_16x16x128_f8f6f4 v[122:125], v[26:33], v[178:185], v[122:125], v229, v229 op_sel_hi:[0,0,0]
	v_mfma_scale_f32_16x16x128_f8f6f4 v[114:117], v[18:25], v[206:213], v[114:117], v229, v229 op_sel_hi:[0,0,0]
	v_mfma_scale_f32_16x16x128_f8f6f4 v[106:109], v[26:33], v[206:213], v[106:109], v229, v229 op_sel_hi:[0,0,0]
	v_mfma_scale_f32_16x16x128_f8f6f4 v[102:105], v[18:25], v[214:221], v[102:105], v229, v229 op_sel_hi:[0,0,0]
	v_mfma_scale_f32_16x16x128_f8f6f4 v[98:101], v[26:33], v[214:221], v[98:101], v229, v229 op_sel_hi:[0,0,0]
	s_barrier
	s_setprio 0
	s_add_i32 s22, s75, s25
	v_lshl_add_u64 v[162:163], v[162:163], 0, s[8:9]
	s_mov_b32 m0, s22
	ds_read_b128 v[170:173], v235 offset:49152
	ds_read_b128 v[174:177], v235 offset:50176
	ds_read_b128 v[178:181], v235 offset:51200
	ds_read_b128 v[182:185], v235 offset:52224
	ds_read_b128 v[206:209], v235 offset:53248
	ds_read_b128 v[210:213], v235 offset:54272
	ds_read_b128 v[214:217], v235 offset:55296
	ds_read_b128 v[218:221], v235 offset:56320
	global_load_lds_dwordx4 v[162:163], off
	s_add_i32 m0, s22, 0x2000
	s_add_u32 s20, s20, 0xb0080
	v_lshl_add_u64 v[162:163], v[164:165], 0, s[8:9]
	s_addc_u32 s21, s21, 0
	s_add_i32 s22, s76, s25
	global_load_lds_dwordx4 v[162:163], off
	v_lshl_add_u64 v[162:163], s[20:21], 0, v[192:193]
	s_mov_b32 m0, s22
	s_nop 0
	global_load_lds_dwordx4 v[162:163], off
	v_lshl_add_u64 v[162:163], s[20:21], 0, v[196:197]
	s_add_i32 m0, s22, 0x2000
	s_nop 0
	global_load_lds_dwordx4 v[162:163], off
	v_lshl_add_u64 v[162:163], v[166:167], 0, s[8:9]
	s_mov_b32 m0, s36
	s_nop 0
	global_load_lds_dwordx4 v[162:163], off
	v_lshl_add_u64 v[162:163], v[168:169], 0, s[8:9]
	s_mov_b32 m0, s37
	s_nop 0
	global_load_lds_dwordx4 v[162:163], off
	s_add_u32 s18, s18, 0x100
	s_addc_u32 s19, s19, 0
	s_add_u32 s72, s72, 0x100
	s_addc_u32 s73, s73, 0
	s_cmp_ge_u32 s74, s4
	s_mov_b32 s22, s74
	s_waitcnt vmcnt(8)
	s_waitcnt lgkmcnt(0)
	s_setprio 1
	s_barrier
	v_mfma_scale_f32_16x16x128_f8f6f4 v[94:97], v[2:9], v[170:177], v[94:97], v229, v229 op_sel_hi:[0,0,0]
	v_mfma_scale_f32_16x16x128_f8f6f4 v[90:93], v[10:17], v[170:177], v[90:93], v229, v229 op_sel_hi:[0,0,0]
	v_mfma_scale_f32_16x16x128_f8f6f4 v[86:89], v[2:9], v[178:185], v[86:89], v229, v229 op_sel_hi:[0,0,0]
	v_mfma_scale_f32_16x16x128_f8f6f4 v[78:81], v[10:17], v[178:185], v[78:81], v229, v229 op_sel_hi:[0,0,0]
	v_mfma_scale_f32_16x16x128_f8f6f4 v[70:73], v[2:9], v[206:213], v[70:73], v229, v229 op_sel_hi:[0,0,0]
	v_mfma_scale_f32_16x16x128_f8f6f4 v[62:65], v[10:17], v[206:213], v[62:65], v229, v229 op_sel_hi:[0,0,0]
	v_mfma_scale_f32_16x16x128_f8f6f4 v[54:57], v[2:9], v[214:221], v[54:57], v229, v229 op_sel_hi:[0,0,0]
	v_mfma_scale_f32_16x16x128_f8f6f4 v[46:49], v[10:17], v[214:221], v[46:49], v229, v229 op_sel_hi:[0,0,0]
	s_setprio 0
	s_setprio 1
	v_mfma_scale_f32_16x16x128_f8f6f4 v[82:85], v[18:25], v[170:177], v[82:85], v229, v229 op_sel_hi:[0,0,0]
	v_mfma_scale_f32_16x16x128_f8f6f4 v[74:77], v[26:33], v[170:177], v[74:77], v229, v229 op_sel_hi:[0,0,0]
	v_mfma_scale_f32_16x16x128_f8f6f4 v[66:69], v[18:25], v[178:185], v[66:69], v229, v229 op_sel_hi:[0,0,0]
	v_mfma_scale_f32_16x16x128_f8f6f4 v[58:61], v[26:33], v[178:185], v[58:61], v229, v229 op_sel_hi:[0,0,0]
	v_mfma_scale_f32_16x16x128_f8f6f4 v[50:53], v[18:25], v[206:213], v[50:53], v229, v229 op_sel_hi:[0,0,0]
	v_mfma_scale_f32_16x16x128_f8f6f4 v[42:45], v[26:33], v[206:213], v[42:45], v229, v229 op_sel_hi:[0,0,0]
	v_mfma_scale_f32_16x16x128_f8f6f4 v[38:41], v[18:25], v[214:221], v[38:41], v229, v229 op_sel_hi:[0,0,0]
	v_mfma_scale_f32_16x16x128_f8f6f4 v[34:37], v[26:33], v[214:221], v[34:37], v229, v229 op_sel_hi:[0,0,0]
	s_barrier
	s_setprio 0
	s_cbranch_scc0 .LBB0_1304
	s_nop 15
	s_nop 15
	s_nop 15
	s_nop 15
	s_nop 15
	s_and_b64 vcc, exec, s[10:11]
	s_cbranch_vccz .LBB0_1307
	s_barrier

; #define PG8_STAGE(bufoff, gbase, voff) do { _Pragma("unroll") for (int _i = 0; _i < 2; ++_i) \
;         __builtin_amdgcn_global_load_lds((const unsigned*)((const char*)(gbase) + (voff)[_i]), (PG8_LAS unsigned*)(lds + (bufoff) + ldsw + _i * 8192), 16, 0, 0); } while (0)
; #define PG8_WAIT_V(n) asm volatile("s_waitcnt vmcnt(" #n ")" ::: "memory")
; #define PG8_WAIT_L(n) asm volatile("s_waitcnt lgkmcnt(" #n ")" ::: "memory")
; #define PG8_BAR __builtin_amdgcn_s_barrier()
; #define PG8_SCHED __builtin_amdgcn_sched_barrier(0)
;     __device__ __forceinline__ int nt(const pg8::Unit& u) const { return u.kind == 0 ? ntiles : q_nt(u.kind - 1); }
; template <class Epi, class Sched, bool ALIGN_EPI = true, bool SP2 = true>
; __device__ __forceinline__ void gemm_phase(PG8_LAS unsigned char* lds, const int K  , const Sched& S, const Epi& E) {
;     ...
;             const bool last = (t == nt - 2);
;             const char* a1 = cA + (size_t)(t + 1) * kstep;
;             const char* a2 = last ? nA : cA + (size_t)(t + 2) * kstep; const char* b2 = last ? nB : cB + (size_t)(t + 2) * kstep;
;             const char* a3 = a2 + kstep; const char* b3 = b2 + kstep;
;             if constexpr (SP2) {
;             PG8_LDB(B0, 0, 0); PG8_LDB(B1, 0, 1); PG8_SCHED; PG8_LDA(At, 0, 0); PG8_STAGE(PG8_SA(1, 1), a1 + hstep, voffA);
;             PG8_WAIT_V(8); PG8_WAIT_L(0); PG8_BAR; PG8_MMA(0, 0, At, B0); PG8_MMA(0, 1, At, B1); PG8_BAR; PG8_SCHED;
;             PG8_LDA(At, 0, 1); PG8_STAGE(PG8_SB(0, 0), b2, voffB); PG8_STAGE(PG8_SB(0, 1), b2 + hstep, voffB); PG8_STAGE(PG8_SA(0, 0), a2, voffA);
;             PG8_WAIT_V(8); PG8_WAIT_L(0); PG8_BAR; PG8_MMA(1, 0, At, B0); PG8_MMA(1, 1, At, B1); PG8_BAR; PG8_SCHED;
.LBB0_1448:
	ds_read_b128 v[148:151], v154
	ds_read_b128 v[160:163], v154 offset:1024
	ds_read_b128 v[164:167], v154 offset:2048
	ds_read_b128 v[168:171], v154 offset:3072
	ds_read_b128 v[172:175], v155
	ds_read_b128 v[176:179], v155 offset:1024
	ds_read_b128 v[180:183], v155 offset:2048
	ds_read_b128 v[184:187], v155 offset:3072
	s_add_u32 s26, s24, 0xfff80080
	s_addc_u32 s27, s25, -1
	s_cmp_eq_u32 s50, 28
	s_cselect_b32 s29, s17, s27
	s_cselect_b32 s28, s46, s26
	s_cselect_b32 s27, s11, s49
	s_cselect_b32 s26, s47, s48
	v_lshl_add_u64 v[220:221], s[24:25], 0, v[140:141]
	s_add_i32 m0, s23, 0xc000
	ds_read_b128 v[188:191], v156
	ds_read_b128 v[192:195], v156 offset:1024
	ds_read_b128 v[196:199], v156 offset:2048
	ds_read_b128 v[200:203], v156 offset:3072
	ds_read_b128 v[204:207], v156 offset:4096
	ds_read_b128 v[208:211], v156 offset:5120
	ds_read_b128 v[212:215], v156 offset:6144
	ds_read_b128 v[216:219], v156 offset:7168
	global_load_lds_dwordx4 v[220:221], off
	v_lshl_add_u64 v[220:221], s[24:25], 0, v[142:143]
	s_add_i32 m0, s23, 0xe000
	s_nop 0
	global_load_lds_dwordx4 v[220:221], off
	s_waitcnt vmcnt(8)
	s_waitcnt lgkmcnt(0)
	s_setprio 1
	s_barrier
	v_mfma_f32_16x16x32_bf16 v[126:129], v[148:151], v[188:191], v[126:129]
	v_mfma_f32_16x16x32_bf16 v[118:121], v[164:167], v[188:191], v[118:121]
	v_mfma_f32_16x16x32_bf16 v[110:113], v[148:151], v[196:199], v[110:113]
	v_mfma_f32_16x16x32_bf16 v[102:105], v[164:167], v[196:199], v[102:105]
	v_mfma_f32_16x16x32_bf16 v[94:97], v[148:151], v[204:207], v[94:97]
	v_mfma_f32_16x16x32_bf16 v[86:89], v[164:167], v[204:207], v[86:89]
	v_mfma_f32_16x16x32_bf16 v[78:81], v[148:151], v[212:215], v[78:81]
	v_mfma_f32_16x16x32_bf16 v[70:73], v[164:167], v[212:215], v[70:73]
	v_mfma_f32_16x16x32_bf16 v[126:129], v[160:163], v[192:195], v[126:129]
	v_mfma_f32_16x16x32_bf16 v[118:121], v[168:171], v[192:195], v[118:121]
	v_mfma_f32_16x16x32_bf16 v[110:113], v[160:163], v[200:203], v[110:113]
	v_mfma_f32_16x16x32_bf16 v[102:105], v[168:171], v[200:203], v[102:105]
	v_mfma_f32_16x16x32_bf16 v[94:97], v[160:163], v[208:211], v[94:97]
	v_mfma_f32_16x16x32_bf16 v[86:89], v[168:171], v[208:211], v[86:89]
	v_mfma_f32_16x16x32_bf16 v[78:81], v[160:163], v[216:219], v[78:81]
	v_mfma_f32_16x16x32_bf16 v[70:73], v[168:171], v[216:219], v[70:73]
	s_setprio 0
	s_setprio 1
	v_mfma_f32_16x16x32_bf16 v[122:125], v[172:175], v[188:191], v[122:125]
	v_mfma_f32_16x16x32_bf16 v[114:117], v[180:183], v[188:191], v[114:117]
	v_mfma_f32_16x16x32_bf16 v[106:109], v[172:175], v[196:199], v[106:109]
	v_mfma_f32_16x16x32_bf16 v[98:101], v[180:183], v[196:199], v[98:101]
	v_mfma_f32_16x16x32_bf16 v[90:93], v[172:175], v[204:207], v[90:93]
	v_mfma_f32_16x16x32_bf16 v[82:85], v[180:183], v[204:207], v[82:85]
	v_mfma_f32_16x16x32_bf16 v[74:77], v[172:175], v[212:215], v[74:77]
	v_mfma_f32_16x16x32_bf16 v[66:69], v[180:183], v[212:215], v[66:69]
	v_mfma_f32_16x16x32_bf16 v[122:125], v[176:179], v[192:195], v[122:125]
	v_mfma_f32_16x16x32_bf16 v[114:117], v[184:187], v[192:195], v[114:117]
	v_mfma_f32_16x16x32_bf16 v[106:109], v[176:179], v[200:203], v[106:109]
	v_mfma_f32_16x16x32_bf16 v[98:101], v[184:187], v[200:203], v[98:101]
	v_mfma_f32_16x16x32_bf16 v[90:93], v[176:179], v[208:211], v[90:93]
	v_mfma_f32_16x16x32_bf16 v[82:85], v[184:187], v[208:211], v[82:85]
	v_mfma_f32_16x16x32_bf16 v[74:77], v[176:179], v[216:219], v[74:77]
	v_mfma_f32_16x16x32_bf16 v[66:69], v[184:187], v[216:219], v[66:69]
	s_barrier
	s_setprio 0
	s_add_i32 s51, s41, s31
	v_lshl_add_u64 v[220:221], s[26:27], 0, v[136:137]
	s_mov_b32 m0, s51
	ds_read_b128 v[188:191], v156 offset:16384
	ds_read_b128 v[192:195], v156 offset:17408
	ds_read_b128 v[196:199], v156 offset:18432
	ds_read_b128 v[200:203], v156 offset:19456
	ds_read_b128 v[204:207], v156 offset:20480
	ds_read_b128 v[208:211], v156 offset:21504
	ds_read_b128 v[212:215], v156 offset:22528
	ds_read_b128 v[216:219], v156 offset:23552
	global_load_lds_dwordx4 v[220:221], off
	s_add_i32 m0, s51, 0x2000
	s_add_u32 s68, s26, 0x80000
	v_lshl_add_u64 v[222:223], s[26:27], 0, v[132:133]
	s_addc_u32 s69, s27, 0
	s_add_i32 s51, s42, s31
	global_load_lds_dwordx4 v[222:223], off
	v_lshl_add_u64 v[224:225], s[68:69], 0, v[136:137]
	s_mov_b32 m0, s51
	v_lshl_add_u64 v[226:227], s[28:29], 0, v[134:135]
	global_load_lds_dwordx4 v[224:225], off
	v_lshl_add_u64 v[224:225], s[68:69], 0, v[132:133]
	s_add_i32 m0, s51, 0x2000
	s_nop 0
	global_load_lds_dwordx4 v[224:225], off
	v_lshl_add_u64 v[224:225], s[28:29], 0, v[138:139]
	s_mov_b32 m0, s23
	s_nop 0
	global_load_lds_dwordx4 v[224:225], off
	s_mov_b32 m0, s34
	s_nop 0
	global_load_lds_dwordx4 v[226:227], off
	s_waitcnt vmcnt(8)
	s_waitcnt lgkmcnt(0)
	s_setprio 1
	s_barrier
; #define PG8_STAGE(bufoff, gbase, voff) do { _Pragma("unroll") for (int _i = 0; _i < 2; ++_i) \
;         __builtin_amdgcn_global_load_lds((const unsigned*)((const char*)(gbase) + (voff)[_i]), (PG8_LAS unsigned*)(lds + (bufoff) + ldsw + _i * 8192), 16, 0, 0); } while (0)
; #define PG8_WAIT_V(n) asm volatile("s_waitcnt vmcnt(" #n ")" ::: "memory")
; #define PG8_WAIT_L(n) asm volatile("s_waitcnt lgkmcnt(" #n ")" ::: "memory")
; #define PG8_BAR __builtin_amdgcn_s_barrier()
; #define PG8_SCHED __builtin_amdgcn_sched_barrier(0)
; template <class Epi, class Sched, bool ALIGN_EPI = true, bool SP2 = true>
; __device__ __forceinline__ void gemm_phase(PG8_LAS unsigned char* lds, const int K  , const Sched& S, const Epi& E) {
;     ...
;             PG8_WAIT_V(8); PG8_WAIT_L(0); PG8_BAR; PG8_MMA(1, 0, At, B0); PG8_MMA(1, 1, At, B1); PG8_BAR; PG8_SCHED;
;             PG8_LDB(B0, 1, 0); PG8_LDB(B1, 1, 1); PG8_SCHED; PG8_LDA(At, 1, 0); PG8_STAGE(PG8_SA(0, 1), a2 + hstep, voffA);
;             PG8_WAIT_V(8); PG8_WAIT_L(0); PG8_BAR; PG8_MMA(0, 0, At, B0); PG8_MMA(0, 1, At, B1); PG8_BAR; PG8_SCHED;
	v_mfma_f32_16x16x32_bf16 v[62:65], v[148:151], v[188:191], v[62:65]
	v_mfma_f32_16x16x32_bf16 v[54:57], v[164:167], v[188:191], v[54:57]
	v_mfma_f32_16x16x32_bf16 v[46:49], v[148:151], v[196:199], v[46:49]
	v_mfma_f32_16x16x32_bf16 v[38:41], v[164:167], v[196:199], v[38:41]
	v_mfma_f32_16x16x32_bf16 v[30:33], v[148:151], v[204:207], v[30:33]
	v_mfma_f32_16x16x32_bf16 v[22:25], v[164:167], v[204:207], v[22:25]
	v_mfma_f32_16x16x32_bf16 v[14:17], v[148:151], v[212:215], v[14:17]
	v_mfma_f32_16x16x32_bf16 v[6:9], v[164:167], v[212:215], v[6:9]
	v_mfma_f32_16x16x32_bf16 v[62:65], v[160:163], v[192:195], v[62:65]
	v_mfma_f32_16x16x32_bf16 v[54:57], v[168:171], v[192:195], v[54:57]
	v_mfma_f32_16x16x32_bf16 v[46:49], v[160:163], v[200:203], v[46:49]
	v_mfma_f32_16x16x32_bf16 v[38:41], v[168:171], v[200:203], v[38:41]
	v_mfma_f32_16x16x32_bf16 v[30:33], v[160:163], v[208:211], v[30:33]
	v_mfma_f32_16x16x32_bf16 v[22:25], v[168:171], v[208:211], v[22:25]
	v_mfma_f32_16x16x32_bf16 v[14:17], v[160:163], v[216:219], v[14:17]
	v_mfma_f32_16x16x32_bf16 v[6:9], v[168:171], v[216:219], v[6:9]
	s_setprio 0
	s_setprio 1
	v_mfma_f32_16x16x32_bf16 v[58:61], v[172:175], v[188:191], v[58:61]
	v_mfma_f32_16x16x32_bf16 v[50:53], v[180:183], v[188:191], v[50:53]
	v_mfma_f32_16x16x32_bf16 v[42:45], v[172:175], v[196:199], v[42:45]
	v_mfma_f32_16x16x32_bf16 v[34:37], v[180:183], v[196:199], v[34:37]
	v_mfma_f32_16x16x32_bf16 v[26:29], v[172:175], v[204:207], v[26:29]
	v_mfma_f32_16x16x32_bf16 v[18:21], v[180:183], v[204:207], v[18:21]
	v_mfma_f32_16x16x32_bf16 v[10:13], v[172:175], v[212:215], v[10:13]
	v_mfma_f32_16x16x32_bf16 v[2:5], v[180:183], v[212:215], v[2:5]
	v_mfma_f32_16x16x32_bf16 v[58:61], v[176:179], v[192:195], v[58:61]
	v_mfma_f32_16x16x32_bf16 v[50:53], v[184:187], v[192:195], v[50:53]
	v_mfma_f32_16x16x32_bf16 v[42:45], v[176:179], v[200:203], v[42:45]
	v_mfma_f32_16x16x32_bf16 v[34:37], v[184:187], v[200:203], v[34:37]
	v_mfma_f32_16x16x32_bf16 v[26:29], v[176:179], v[208:211], v[26:29]
	v_mfma_f32_16x16x32_bf16 v[18:21], v[184:187], v[208:211], v[18:21]
	v_mfma_f32_16x16x32_bf16 v[10:13], v[176:179], v[216:219], v[10:13]
	v_mfma_f32_16x16x32_bf16 v[2:5], v[184:187], v[216:219], v[2:5]
	s_barrier
	s_setprio 0
	s_add_i32 s51, 0, 0x18000
	v_add_u32_e32 v159, s51, v152
	s_add_i32 s68, 0, 0x1c000
	ds_read_b128 v[148:151], v159
	ds_read_b128 v[160:163], v159 offset:1024
	ds_read_b128 v[164:167], v159 offset:2048
	ds_read_b128 v[168:171], v159 offset:3072
	v_add_u32_e32 v159, s68, v152
	ds_read_b128 v[172:175], v159
	ds_read_b128 v[176:179], v159 offset:1024
	ds_read_b128 v[180:183], v159 offset:2048
	ds_read_b128 v[184:187], v159 offset:3072
	s_add_u32 s28, s28, 0x80000
	s_addc_u32 s29, s29, 0
	s_mov_b32 m0, s35
	v_lshl_add_u64 v[230:231], s[28:29], 0, v[138:139]
	ds_read_b128 v[188:191], v156 offset:32768
	ds_read_b128 v[192:195], v156 offset:33792
	ds_read_b128 v[196:199], v156 offset:34816
	ds_read_b128 v[200:203], v156 offset:35840
	ds_read_b128 v[204:207], v156 offset:36864
	ds_read_b128 v[208:211], v156 offset:37888
	ds_read_b128 v[212:215], v156 offset:38912
	ds_read_b128 v[216:219], v156 offset:39936
	global_load_lds_dwordx4 v[230:231], off
	v_lshl_add_u64 v[230:231], s[28:29], 0, v[134:135]
	s_mov_b32 m0, s36
	s_nop 0
	global_load_lds_dwordx4 v[230:231], off
	s_waitcnt vmcnt(8)
	s_waitcnt lgkmcnt(0)
	s_setprio 1
	s_barrier
	v_mfma_f32_16x16x32_bf16 v[126:129], v[148:151], v[188:191], v[126:129]
	v_mfma_f32_16x16x32_bf16 v[118:121], v[164:167], v[188:191], v[118:121]
	v_mfma_f32_16x16x32_bf16 v[110:113], v[148:151], v[196:199], v[110:113]
	v_mfma_f32_16x16x32_bf16 v[102:105], v[164:167], v[196:199], v[102:105]
	v_mfma_f32_16x16x32_bf16 v[94:97], v[148:151], v[204:207], v[94:97]
	v_mfma_f32_16x16x32_bf16 v[86:89], v[164:167], v[204:207], v[86:89]
	v_mfma_f32_16x16x32_bf16 v[78:81], v[148:151], v[212:215], v[78:81]
	v_mfma_f32_16x16x32_bf16 v[70:73], v[164:167], v[212:215], v[70:73]
	v_mfma_f32_16x16x32_bf16 v[126:129], v[160:163], v[192:195], v[126:129]
	v_mfma_f32_16x16x32_bf16 v[118:121], v[168:171], v[192:195], v[118:121]
	v_mfma_f32_16x16x32_bf16 v[110:113], v[160:163], v[200:203], v[110:113]
	v_mfma_f32_16x16x32_bf16 v[102:105], v[168:171], v[200:203], v[102:105]
	v_mfma_f32_16x16x32_bf16 v[94:97], v[160:163], v[208:211], v[94:97]
	v_mfma_f32_16x16x32_bf16 v[86:89], v[168:171], v[208:211], v[86:89]
	v_mfma_f32_16x16x32_bf16 v[78:81], v[160:163], v[216:219], v[78:81]
	v_mfma_f32_16x16x32_bf16 v[70:73], v[168:171], v[216:219], v[70:73]
	s_setprio 0
	s_setprio 1
	v_mfma_f32_16x16x32_bf16 v[122:125], v[172:175], v[188:191], v[122:125]
	v_mfma_f32_16x16x32_bf16 v[114:117], v[180:183], v[188:191], v[114:117]
	v_mfma_f32_16x16x32_bf16 v[106:109], v[172:175], v[196:199], v[106:109]
	v_mfma_f32_16x16x32_bf16 v[98:101], v[180:183], v[196:199], v[98:101]
	v_mfma_f32_16x16x32_bf16 v[90:93], v[172:175], v[204:207], v[90:93]
	v_mfma_f32_16x16x32_bf16 v[82:85], v[180:183], v[204:207], v[82:85]
	v_mfma_f32_16x16x32_bf16 v[74:77], v[172:175], v[212:215], v[74:77]
	v_mfma_f32_16x16x32_bf16 v[66:69], v[180:183], v[212:215], v[66:69]
	v_mfma_f32_16x16x32_bf16 v[122:125], v[176:179], v[192:195], v[122:125]
	v_mfma_f32_16x16x32_bf16 v[114:117], v[184:187], v[192:195], v[114:117]
	v_mfma_f32_16x16x32_bf16 v[106:109], v[176:179], v[200:203], v[106:109]
	v_mfma_f32_16x16x32_bf16 v[98:101], v[184:187], v[200:203], v[98:101]
	v_mfma_f32_16x16x32_bf16 v[90:93], v[176:179], v[208:211], v[90:93]
	v_mfma_f32_16x16x32_bf16 v[82:85], v[184:187], v[208:211], v[82:85]
	v_mfma_f32_16x16x32_bf16 v[74:77], v[176:179], v[216:219], v[74:77]
	v_mfma_f32_16x16x32_bf16 v[66:69], v[184:187], v[216:219], v[66:69]
	s_barrier
; #define PG8_STAGE(bufoff, gbase, voff) do { _Pragma("unroll") for (int _i = 0; _i < 2; ++_i) \
;         __builtin_amdgcn_global_load_lds((const unsigned*)((const char*)(gbase) + (voff)[_i]), (PG8_LAS unsigned*)(lds + (bufoff) + ldsw + _i * 8192), 16, 0, 0); } while (0)
; #define PG8_WAIT_V(n) asm volatile("s_waitcnt vmcnt(" #n ")" ::: "memory")
; #define PG8_WAIT_L(n) asm volatile("s_waitcnt lgkmcnt(" #n ")" ::: "memory")
; #define PG8_BAR __builtin_amdgcn_s_barrier()
; #define PG8_SCHED __builtin_amdgcn_sched_barrier(0)
;     __device__ __forceinline__ int nt(const pg8::Unit& u) const { return u.kind == 0 ? ntiles : q_nt(u.kind - 1); }
; template <class Epi, class Sched, bool ALIGN_EPI = true, bool SP2 = true>
; __device__ __forceinline__ void gemm_phase(PG8_LAS unsigned char* lds, const int K  , const Sched& S, const Epi& E) {
;     ...
;         for (int t = 0; t < nt; t += 2) {
;     ...
;             PG8_LDA(At, 1, 1); PG8_STAGE(PG8_SB(1, 0), b3, voffB); PG8_STAGE(PG8_SB(1, 1), b3 + hstep, voffB); PG8_STAGE(PG8_SA(1, 0), a3, voffA);
;             PG8_WAIT_V(8); PG8_WAIT_L(0); PG8_BAR; PG8_MMA(1, 0, At, B0); PG8_MMA(1, 1, At, B1); PG8_BAR; PG8_SCHED;
	s_setprio 0
	s_add_i32 s28, s51, s31
	v_lshl_add_u64 v[220:221], v[220:221], 0, s[4:5]
	s_mov_b32 m0, s28
	ds_read_b128 v[188:191], v156 offset:49152
	ds_read_b128 v[192:195], v156 offset:50176
	ds_read_b128 v[196:199], v156 offset:51200
	ds_read_b128 v[200:203], v156 offset:52224
	ds_read_b128 v[204:207], v156 offset:53248
	ds_read_b128 v[208:211], v156 offset:54272
	ds_read_b128 v[212:215], v156 offset:55296
	ds_read_b128 v[216:219], v156 offset:56320
	global_load_lds_dwordx4 v[220:221], off
	s_add_i32 m0, s28, 0x2000
	s_add_u32 s26, s26, 0x80080
	v_lshl_add_u64 v[220:221], v[222:223], 0, s[4:5]
	s_addc_u32 s27, s27, 0
	s_add_i32 s28, s68, s31
	global_load_lds_dwordx4 v[220:221], off
	v_lshl_add_u64 v[220:221], s[26:27], 0, v[136:137]
	s_mov_b32 m0, s28
	s_nop 0
	global_load_lds_dwordx4 v[220:221], off
	v_lshl_add_u64 v[220:221], s[26:27], 0, v[132:133]
	s_add_i32 m0, s28, 0x2000
	s_nop 0
	global_load_lds_dwordx4 v[220:221], off
	v_lshl_add_u64 v[220:221], v[224:225], 0, s[4:5]
	s_mov_b32 m0, s38
	s_nop 0
	global_load_lds_dwordx4 v[220:221], off
	v_lshl_add_u64 v[220:221], v[226:227], 0, s[4:5]
	s_mov_b32 m0, s39
	s_nop 0
	global_load_lds_dwordx4 v[220:221], off
	s_add_i32 s50, s50, 2
	s_add_u32 s24, s24, 0x100
	s_addc_u32 s25, s25, 0
	s_add_u32 s48, s48, 0x100
	s_addc_u32 s49, s49, 0
	s_cmp_gt_u32 s50, 29
	s_waitcnt vmcnt(8)
	s_waitcnt lgkmcnt(0)
	s_setprio 1
	s_barrier
	v_mfma_f32_16x16x32_bf16 v[62:65], v[148:151], v[188:191], v[62:65]
	v_mfma_f32_16x16x32_bf16 v[54:57], v[164:167], v[188:191], v[54:57]
	v_mfma_f32_16x16x32_bf16 v[46:49], v[148:151], v[196:199], v[46:49]
	v_mfma_f32_16x16x32_bf16 v[38:41], v[164:167], v[196:199], v[38:41]
	v_mfma_f32_16x16x32_bf16 v[30:33], v[148:151], v[204:207], v[30:33]
	v_mfma_f32_16x16x32_bf16 v[22:25], v[164:167], v[204:207], v[22:25]
	v_mfma_f32_16x16x32_bf16 v[14:17], v[148:151], v[212:215], v[14:17]
	v_mfma_f32_16x16x32_bf16 v[6:9], v[164:167], v[212:215], v[6:9]
	v_mfma_f32_16x16x32_bf16 v[62:65], v[160:163], v[192:195], v[62:65]
	v_mfma_f32_16x16x32_bf16 v[54:57], v[168:171], v[192:195], v[54:57]
	v_mfma_f32_16x16x32_bf16 v[46:49], v[160:163], v[200:203], v[46:49]
	v_mfma_f32_16x16x32_bf16 v[38:41], v[168:171], v[200:203], v[38:41]
	v_mfma_f32_16x16x32_bf16 v[30:33], v[160:163], v[208:211], v[30:33]
	v_mfma_f32_16x16x32_bf16 v[22:25], v[168:171], v[208:211], v[22:25]
	v_mfma_f32_16x16x32_bf16 v[14:17], v[160:163], v[216:219], v[14:17]
	v_mfma_f32_16x16x32_bf16 v[6:9], v[168:171], v[216:219], v[6:9]
	s_setprio 0
	s_setprio 1
	v_mfma_f32_16x16x32_bf16 v[58:61], v[172:175], v[188:191], v[58:61]
	v_mfma_f32_16x16x32_bf16 v[50:53], v[180:183], v[188:191], v[50:53]
	v_mfma_f32_16x16x32_bf16 v[42:45], v[172:175], v[196:199], v[42:45]
	v_mfma_f32_16x16x32_bf16 v[34:37], v[180:183], v[196:199], v[34:37]
	v_mfma_f32_16x16x32_bf16 v[26:29], v[172:175], v[204:207], v[26:29]
	v_mfma_f32_16x16x32_bf16 v[18:21], v[180:183], v[204:207], v[18:21]
	v_mfma_f32_16x16x32_bf16 v[10:13], v[172:175], v[212:215], v[10:13]
	v_mfma_f32_16x16x32_bf16 v[2:5], v[180:183], v[212:215], v[2:5]
	v_mfma_f32_16x16x32_bf16 v[58:61], v[176:179], v[192:195], v[58:61]
	v_mfma_f32_16x16x32_bf16 v[50:53], v[184:187], v[192:195], v[50:53]
	v_mfma_f32_16x16x32_bf16 v[42:45], v[176:179], v[200:203], v[42:45]
	v_mfma_f32_16x16x32_bf16 v[34:37], v[184:187], v[200:203], v[34:37]
	v_mfma_f32_16x16x32_bf16 v[26:29], v[176:179], v[208:211], v[26:29]
	v_mfma_f32_16x16x32_bf16 v[18:21], v[184:187], v[208:211], v[18:21]
	v_mfma_f32_16x16x32_bf16 v[10:13], v[176:179], v[216:219], v[10:13]
	v_mfma_f32_16x16x32_bf16 v[2:5], v[184:187], v[216:219], v[2:5]
	s_barrier
	s_setprio 0
	s_cbranch_scc0 .LBB0_1448
	s_and_b64 vcc, exec, s[8:9]
	s_cbranch_vccz .LBB0_1451
	s_barrier

; #define PG8_STAGE(bufoff, gbase, voff) do { _Pragma("unroll") for (int _i = 0; _i < 2; ++_i) \
;         __builtin_amdgcn_global_load_lds((const unsigned*)((const char*)(gbase) + (voff)[_i]), (PG8_LAS unsigned*)(lds + (bufoff) + ldsw + _i * 8192), 16, 0, 0); } while (0)
; #define PG8_WAIT_V(n) asm volatile("s_waitcnt vmcnt(" #n ")" ::: "memory")
; #define PG8_WAIT_L(n) asm volatile("s_waitcnt lgkmcnt(" #n ")" ::: "memory")
; #define PG8_BAR __builtin_amdgcn_s_barrier()
; #define PG8_SCHED __builtin_amdgcn_sched_barrier(0)
;     __device__ __forceinline__ int nt(const pg8::Unit& u) const { return u.kind == 0 ? ntiles : q_nt(u.kind - 1); }
; template <class Epi, class Sched, bool ALIGN_EPI = true, bool SP2 = true>
; __device__ __forceinline__ void gemm_phase(PG8_LAS unsigned char* lds, const int K  , const Sched& S, const Epi& E) {
;     ...
;             const bool last = (t == nt - 2);
;             const char* a1 = cA + (size_t)(t + 1) * kstep;
;             const char* a2 = last ? nA : cA + (size_t)(t + 2) * kstep; const char* b2 = last ? nB : cB + (size_t)(t + 2) * kstep;
;             const char* a3 = a2 + kstep; const char* b3 = b2 + kstep;
;             if constexpr (SP2) {
;             PG8_LDB(B0, 0, 0); PG8_LDB(B1, 0, 1); PG8_SCHED; PG8_LDA(At, 0, 0); PG8_STAGE(PG8_SA(1, 1), a1 + hstep, voffA);
;             PG8_WAIT_V(8); PG8_WAIT_L(0); PG8_BAR; PG8_MMA(0, 0, At, B0); PG8_MMA(0, 1, At, B1); PG8_BAR; PG8_SCHED;
;             PG8_LDA(At, 0, 1); PG8_STAGE(PG8_SB(0, 0), b2, voffB); PG8_STAGE(PG8_SB(0, 1), b2 + hstep, voffB); PG8_STAGE(PG8_SA(0, 0), a2, voffA);
;             PG8_WAIT_V(8); PG8_WAIT_L(0); PG8_BAR; PG8_MMA(1, 0, At, B0); PG8_MMA(1, 1, At, B1); PG8_BAR; PG8_SCHED;
.LBB0_1695:
	ds_read_b128 v[18:21], v233
	ds_read_b128 v[22:25], v233 offset:1024
	ds_read_b128 v[26:29], v233 offset:2048
	ds_read_b128 v[30:33], v233 offset:3072
	ds_read_b128 v[2:5], v234
	ds_read_b128 v[6:9], v234 offset:1024
	ds_read_b128 v[10:13], v234 offset:2048
	ds_read_b128 v[14:17], v234 offset:3072
	s_add_i32 s74, s24, 2
	s_add_u32 s22, s20, 0xfff50080
	s_addc_u32 s23, s21, -1
	s_cmp_eq_u32 s71, s24
	s_cselect_b32 s24, s16, s22
	s_cselect_b32 s25, s17, s23
	s_cselect_b32 s23, s19, s73
	s_cselect_b32 s22, s18, s72
	v_lshl_add_u64 v[186:187], s[20:21], 0, v[198:199]
	s_add_i32 m0, s28, 0xc000
	ds_read_b128 v[162:165], v235
	ds_read_b128 v[166:169], v235 offset:1024
	ds_read_b128 v[170:173], v235 offset:2048
	ds_read_b128 v[174:177], v235 offset:3072
	ds_read_b128 v[178:181], v235 offset:4096
	ds_read_b128 v[182:185], v235 offset:5120
	ds_read_b128 v[206:209], v235 offset:6144
	ds_read_b128 v[210:213], v235 offset:7168
	global_load_lds_dwordx4 v[186:187], off
	v_lshl_add_u64 v[186:187], s[20:21], 0, v[200:201]
	s_add_i32 m0, s28, 0xe000
	s_nop 0
	global_load_lds_dwordx4 v[186:187], off
	s_waitcnt vmcnt(8)
	s_waitcnt lgkmcnt(0)
	s_setprio 1
	s_barrier
	v_mfma_scale_f32_16x16x128_f8f6f4 v[158:161], v[18:25], v[162:169], v[158:161], v229, v229 op_sel_hi:[0,0,0]
	v_mfma_scale_f32_16x16x128_f8f6f4 v[154:157], v[26:33], v[162:169], v[154:157], v229, v229 op_sel_hi:[0,0,0]
	v_mfma_scale_f32_16x16x128_f8f6f4 v[150:153], v[18:25], v[170:177], v[150:153], v229, v229 op_sel_hi:[0,0,0]
	v_mfma_scale_f32_16x16x128_f8f6f4 v[142:145], v[26:33], v[170:177], v[142:145], v229, v229 op_sel_hi:[0,0,0]
	v_mfma_scale_f32_16x16x128_f8f6f4 v[134:137], v[18:25], v[178:185], v[134:137], v229, v229 op_sel_hi:[0,0,0]
	v_mfma_scale_f32_16x16x128_f8f6f4 v[126:129], v[26:33], v[178:185], v[126:129], v229, v229 op_sel_hi:[0,0,0]
	v_mfma_scale_f32_16x16x128_f8f6f4 v[118:121], v[18:25], v[206:213], v[118:121], v229, v229 op_sel_hi:[0,0,0]
	v_mfma_scale_f32_16x16x128_f8f6f4 v[110:113], v[26:33], v[206:213], v[110:113], v229, v229 op_sel_hi:[0,0,0]
	s_setprio 0
	s_setprio 1
	v_mfma_scale_f32_16x16x128_f8f6f4 v[146:149], v[2:9], v[162:169], v[146:149], v229, v229 op_sel_hi:[0,0,0]
	v_mfma_scale_f32_16x16x128_f8f6f4 v[138:141], v[10:17], v[162:169], v[138:141], v229, v229 op_sel_hi:[0,0,0]
	v_mfma_scale_f32_16x16x128_f8f6f4 v[130:133], v[2:9], v[170:177], v[130:133], v229, v229 op_sel_hi:[0,0,0]
	v_mfma_scale_f32_16x16x128_f8f6f4 v[122:125], v[10:17], v[170:177], v[122:125], v229, v229 op_sel_hi:[0,0,0]
	v_mfma_scale_f32_16x16x128_f8f6f4 v[114:117], v[2:9], v[178:185], v[114:117], v229, v229 op_sel_hi:[0,0,0]
	v_mfma_scale_f32_16x16x128_f8f6f4 v[106:109], v[10:17], v[178:185], v[106:109], v229, v229 op_sel_hi:[0,0,0]
	v_mfma_scale_f32_16x16x128_f8f6f4 v[102:105], v[2:9], v[206:213], v[102:105], v229, v229 op_sel_hi:[0,0,0]
	v_mfma_scale_f32_16x16x128_f8f6f4 v[98:101], v[10:17], v[206:213], v[98:101], v229, v229 op_sel_hi:[0,0,0]
	s_barrier
	s_setprio 0
	s_add_i32 s75, s40, s27
	v_lshl_add_u64 v[162:163], s[22:23], 0, v[192:193]
	s_mov_b32 m0, s75
	ds_read_b128 v[170:173], v235 offset:16384
	ds_read_b128 v[174:177], v235 offset:17408
	ds_read_b128 v[178:181], v235 offset:18432
	ds_read_b128 v[182:185], v235 offset:19456
	ds_read_b128 v[206:209], v235 offset:20480
	ds_read_b128 v[210:213], v235 offset:21504
	ds_read_b128 v[214:217], v235 offset:22528
	ds_read_b128 v[218:221], v235 offset:23552
	global_load_lds_dwordx4 v[162:163], off
	s_add_i32 m0, s75, 0x2000
	s_add_u32 s78, s22, 0xb0000
	v_lshl_add_u64 v[164:165], s[22:23], 0, v[196:197]
	s_addc_u32 s79, s23, 0
	s_add_i32 s75, s41, s27
	global_load_lds_dwordx4 v[164:165], off
	v_lshl_add_u64 v[166:167], s[78:79], 0, v[192:193]
	s_mov_b32 m0, s75
	v_lshl_add_u64 v[168:169], s[24:25], 0, v[194:195]
	global_load_lds_dwordx4 v[166:167], off
	v_lshl_add_u64 v[166:167], s[78:79], 0, v[196:197]
	s_add_i32 m0, s75, 0x2000
	s_nop 0
	global_load_lds_dwordx4 v[166:167], off
	v_lshl_add_u64 v[166:167], s[24:25], 0, v[190:191]
	s_mov_b32 m0, s28
	s_nop 0
	global_load_lds_dwordx4 v[166:167], off
	s_mov_b32 m0, s29
	s_nop 0
	global_load_lds_dwordx4 v[168:169], off
	s_waitcnt vmcnt(8)
	s_waitcnt lgkmcnt(0)
	s_setprio 1
	s_barrier
	v_mfma_scale_f32_16x16x128_f8f6f4 v[94:97], v[18:25], v[170:177], v[94:97], v229, v229 op_sel_hi:[0,0,0]
	v_mfma_scale_f32_16x16x128_f8f6f4 v[90:93], v[26:33], v[170:177], v[90:93], v229, v229 op_sel_hi:[0,0,0]
	v_mfma_scale_f32_16x16x128_f8f6f4 v[86:89], v[18:25], v[178:185], v[86:89], v229, v229 op_sel_hi:[0,0,0]
	v_mfma_scale_f32_16x16x128_f8f6f4 v[78:81], v[26:33], v[178:185], v[78:81], v229, v229 op_sel_hi:[0,0,0]
	v_mfma_scale_f32_16x16x128_f8f6f4 v[70:73], v[18:25], v[206:213], v[70:73], v229, v229 op_sel_hi:[0,0,0]
	v_mfma_scale_f32_16x16x128_f8f6f4 v[62:65], v[26:33], v[206:213], v[62:65], v229, v229 op_sel_hi:[0,0,0]
	v_mfma_scale_f32_16x16x128_f8f6f4 v[54:57], v[18:25], v[214:221], v[54:57], v229, v229 op_sel_hi:[0,0,0]
	v_mfma_scale_f32_16x16x128_f8f6f4 v[46:49], v[26:33], v[214:221], v[46:49], v229, v229 op_sel_hi:[0,0,0]
	s_setprio 0
	s_setprio 1
	v_mfma_scale_f32_16x16x128_f8f6f4 v[82:85], v[2:9], v[170:177], v[82:85], v229, v229 op_sel_hi:[0,0,0]
	v_mfma_scale_f32_16x16x128_f8f6f4 v[74:77], v[10:17], v[170:177], v[74:77], v229, v229 op_sel_hi:[0,0,0]
	v_mfma_scale_f32_16x16x128_f8f6f4 v[66:69], v[2:9], v[178:185], v[66:69], v229, v229 op_sel_hi:[0,0,0]
	v_mfma_scale_f32_16x16x128_f8f6f4 v[58:61], v[10:17], v[178:185], v[58:61], v229, v229 op_sel_hi:[0,0,0]
	v_mfma_scale_f32_16x16x128_f8f6f4 v[50:53], v[2:9], v[206:213], v[50:53], v229, v229 op_sel_hi:[0,0,0]
	v_mfma_scale_f32_16x16x128_f8f6f4 v[42:45], v[10:17], v[206:213], v[42:45], v229, v229 op_sel_hi:[0,0,0]
	v_mfma_scale_f32_16x16x128_f8f6f4 v[38:41], v[2:9], v[214:221], v[38:41], v229, v229 op_sel_hi:[0,0,0]
	v_mfma_scale_f32_16x16x128_f8f6f4 v[34:37], v[10:17], v[214:221], v[34:37], v229, v229 op_sel_hi:[0,0,0]
	s_barrier
; #define PG8_STAGE(bufoff, gbase, voff) do { _Pragma("unroll") for (int _i = 0; _i < 2; ++_i) \
;         __builtin_amdgcn_global_load_lds((const unsigned*)((const char*)(gbase) + (voff)[_i]), (PG8_LAS unsigned*)(lds + (bufoff) + ldsw + _i * 8192), 16, 0, 0); } while (0)
; #define PG8_WAIT_V(n) asm volatile("s_waitcnt vmcnt(" #n ")" ::: "memory")
; #define PG8_WAIT_L(n) asm volatile("s_waitcnt lgkmcnt(" #n ")" ::: "memory")
; #define PG8_BAR __builtin_amdgcn_s_barrier()
; #define PG8_SCHED __builtin_amdgcn_sched_barrier(0)
;     __device__ __forceinline__ int nt(const pg8::Unit& u) const { return u.kind == 0 ? ntiles : q_nt(u.kind - 1); }
; template <class Epi, class Sched, bool ALIGN_EPI = true, bool SP2 = true>
; __device__ __forceinline__ void gemm_phase(PG8_LAS unsigned char* lds, const int K  , const Sched& S, const Epi& E) {
;     ...
;         for (int t = 0; t < nt; t += 2) {
;     ...
;             PG8_LDB(B0, 1, 0); PG8_LDB(B1, 1, 1); PG8_SCHED; PG8_LDA(At, 1, 0); PG8_STAGE(PG8_SA(0, 1), a2 + hstep, voffA);
;             PG8_WAIT_V(8); PG8_WAIT_L(0); PG8_BAR; PG8_MMA(0, 0, At, B0); PG8_MMA(0, 1, At, B1); PG8_BAR; PG8_SCHED;
;             PG8_LDA(At, 1, 1); PG8_STAGE(PG8_SB(1, 0), b3, voffB); PG8_STAGE(PG8_SB(1, 1), b3 + hstep, voffB); PG8_STAGE(PG8_SA(1, 0), a3, voffA);
;             PG8_WAIT_V(8); PG8_WAIT_L(0); PG8_BAR; PG8_MMA(1, 0, At, B0); PG8_MMA(1, 1, At, B1); PG8_BAR; PG8_SCHED;
;     ...
;         if constexpr (Epi::FP8) asm volatile("s_nop 15\n\ts_nop 15\n\ts_nop 15\n\ts_nop 15\n\ts_nop 15" ::: "memory");
;         if constexpr (ALIGN_EPI) { if (wr == 0) PG8_BAR; }
	s_setprio 0
	s_add_i32 s75, 0, 0x18000
	s_add_i32 s78, 0, 0x1c000
	v_add_u32_e32 v14, s75, v231
	v_add_u32_e32 v30, s78, v231
	ds_read_b128 v[2:5], v14
	ds_read_b128 v[6:9], v14 offset:1024
	ds_read_b128 v[10:13], v14 offset:2048
	ds_read_b128 v[14:17], v14 offset:3072
	ds_read_b128 v[18:21], v30
	ds_read_b128 v[22:25], v30 offset:1024
	ds_read_b128 v[26:29], v30 offset:2048
	ds_read_b128 v[30:33], v30 offset:3072
	s_add_u32 s24, s24, 0xb0000
	s_addc_u32 s25, s25, 0
	s_mov_b32 m0, s30
	v_lshl_add_u64 v[186:187], s[24:25], 0, v[190:191]
	ds_read_b128 v[170:173], v235 offset:32768
	ds_read_b128 v[174:177], v235 offset:33792
	ds_read_b128 v[178:181], v235 offset:34816
	ds_read_b128 v[182:185], v235 offset:35840
	ds_read_b128 v[206:209], v235 offset:36864
	ds_read_b128 v[210:213], v235 offset:37888
	ds_read_b128 v[214:217], v235 offset:38912
	ds_read_b128 v[218:221], v235 offset:39936
	global_load_lds_dwordx4 v[186:187], off
	v_lshl_add_u64 v[186:187], s[24:25], 0, v[194:195]
	s_mov_b32 m0, s31
	s_nop 0
	global_load_lds_dwordx4 v[186:187], off
	s_waitcnt vmcnt(8)
	s_waitcnt lgkmcnt(0)
	s_setprio 1
	s_barrier
	v_mfma_scale_f32_16x16x128_f8f6f4 v[158:161], v[2:9], v[170:177], v[158:161], v229, v229 op_sel_hi:[0,0,0]
	v_mfma_scale_f32_16x16x128_f8f6f4 v[154:157], v[10:17], v[170:177], v[154:157], v229, v229 op_sel_hi:[0,0,0]
	v_mfma_scale_f32_16x16x128_f8f6f4 v[150:153], v[2:9], v[178:185], v[150:153], v229, v229 op_sel_hi:[0,0,0]
	v_mfma_scale_f32_16x16x128_f8f6f4 v[142:145], v[10:17], v[178:185], v[142:145], v229, v229 op_sel_hi:[0,0,0]
	v_mfma_scale_f32_16x16x128_f8f6f4 v[134:137], v[2:9], v[206:213], v[134:137], v229, v229 op_sel_hi:[0,0,0]
	v_mfma_scale_f32_16x16x128_f8f6f4 v[126:129], v[10:17], v[206:213], v[126:129], v229, v229 op_sel_hi:[0,0,0]
	v_mfma_scale_f32_16x16x128_f8f6f4 v[118:121], v[2:9], v[214:221], v[118:121], v229, v229 op_sel_hi:[0,0,0]
	v_mfma_scale_f32_16x16x128_f8f6f4 v[110:113], v[10:17], v[214:221], v[110:113], v229, v229 op_sel_hi:[0,0,0]
	s_setprio 0
	s_setprio 1
	v_mfma_scale_f32_16x16x128_f8f6f4 v[146:149], v[18:25], v[170:177], v[146:149], v229, v229 op_sel_hi:[0,0,0]
	v_mfma_scale_f32_16x16x128_f8f6f4 v[138:141], v[26:33], v[170:177], v[138:141], v229, v229 op_sel_hi:[0,0,0]
	v_mfma_scale_f32_16x16x128_f8f6f4 v[130:133], v[18:25], v[178:185], v[130:133], v229, v229 op_sel_hi:[0,0,0]
	v_mfma_scale_f32_16x16x128_f8f6f4 v[122:125], v[26:33], v[178:185], v[122:125], v229, v229 op_sel_hi:[0,0,0]
	v_mfma_scale_f32_16x16x128_f8f6f4 v[114:117], v[18:25], v[206:213], v[114:117], v229, v229 op_sel_hi:[0,0,0]
	v_mfma_scale_f32_16x16x128_f8f6f4 v[106:109], v[26:33], v[206:213], v[106:109], v229, v229 op_sel_hi:[0,0,0]
	v_mfma_scale_f32_16x16x128_f8f6f4 v[102:105], v[18:25], v[214:221], v[102:105], v229, v229 op_sel_hi:[0,0,0]
	v_mfma_scale_f32_16x16x128_f8f6f4 v[98:101], v[26:33], v[214:221], v[98:101], v229, v229 op_sel_hi:[0,0,0]
	s_barrier
	s_setprio 0
	s_add_i32 s24, s75, s27
	v_lshl_add_u64 v[162:163], v[162:163], 0, s[10:11]
	s_mov_b32 m0, s24
	ds_read_b128 v[170:173], v235 offset:49152
	ds_read_b128 v[174:177], v235 offset:50176
	ds_read_b128 v[178:181], v235 offset:51200
	ds_read_b128 v[182:185], v235 offset:52224
	ds_read_b128 v[206:209], v235 offset:53248
	ds_read_b128 v[210:213], v235 offset:54272
	ds_read_b128 v[214:217], v235 offset:55296
	ds_read_b128 v[218:221], v235 offset:56320
	global_load_lds_dwordx4 v[162:163], off
	s_add_i32 m0, s24, 0x2000
	s_add_u32 s22, s22, 0xb0080
	v_lshl_add_u64 v[162:163], v[164:165], 0, s[10:11]
	s_addc_u32 s23, s23, 0
	s_add_i32 s24, s78, s27
	global_load_lds_dwordx4 v[162:163], off
	v_lshl_add_u64 v[162:163], s[22:23], 0, v[192:193]
	s_mov_b32 m0, s24
	s_nop 0
	global_load_lds_dwordx4 v[162:163], off
	v_lshl_add_u64 v[162:163], s[22:23], 0, v[196:197]
	s_add_i32 m0, s24, 0x2000
	s_nop 0
	global_load_lds_dwordx4 v[162:163], off
	v_lshl_add_u64 v[162:163], v[166:167], 0, s[10:11]
	s_mov_b32 m0, s36
	s_nop 0
	global_load_lds_dwordx4 v[162:163], off
	v_lshl_add_u64 v[162:163], v[168:169], 0, s[10:11]
	s_mov_b32 m0, s37
	s_nop 0
	global_load_lds_dwordx4 v[162:163], off
	s_add_u32 s20, s20, 0x100
	s_addc_u32 s21, s21, 0
	s_add_u32 s72, s72, 0x100
	s_addc_u32 s73, s73, 0
	s_cmp_ge_u32 s74, s4
	s_mov_b32 s24, s74
	s_waitcnt vmcnt(8)
	s_waitcnt lgkmcnt(0)
	s_setprio 1
	s_barrier
	v_mfma_scale_f32_16x16x128_f8f6f4 v[94:97], v[2:9], v[170:177], v[94:97], v229, v229 op_sel_hi:[0,0,0]
	v_mfma_scale_f32_16x16x128_f8f6f4 v[90:93], v[10:17], v[170:177], v[90:93], v229, v229 op_sel_hi:[0,0,0]
	v_mfma_scale_f32_16x16x128_f8f6f4 v[86:89], v[2:9], v[178:185], v[86:89], v229, v229 op_sel_hi:[0,0,0]
	v_mfma_scale_f32_16x16x128_f8f6f4 v[78:81], v[10:17], v[178:185], v[78:81], v229, v229 op_sel_hi:[0,0,0]
	v_mfma_scale_f32_16x16x128_f8f6f4 v[70:73], v[2:9], v[206:213], v[70:73], v229, v229 op_sel_hi:[0,0,0]
	v_mfma_scale_f32_16x16x128_f8f6f4 v[62:65], v[10:17], v[206:213], v[62:65], v229, v229 op_sel_hi:[0,0,0]
	v_mfma_scale_f32_16x16x128_f8f6f4 v[54:57], v[2:9], v[214:221], v[54:57], v229, v229 op_sel_hi:[0,0,0]
	v_mfma_scale_f32_16x16x128_f8f6f4 v[46:49], v[10:17], v[214:221], v[46:49], v229, v229 op_sel_hi:[0,0,0]
	s_setprio 0
	s_setprio 1
	v_mfma_scale_f32_16x16x128_f8f6f4 v[82:85], v[18:25], v[170:177], v[82:85], v229, v229 op_sel_hi:[0,0,0]
	v_mfma_scale_f32_16x16x128_f8f6f4 v[74:77], v[26:33], v[170:177], v[74:77], v229, v229 op_sel_hi:[0,0,0]
	v_mfma_scale_f32_16x16x128_f8f6f4 v[66:69], v[18:25], v[178:185], v[66:69], v229, v229 op_sel_hi:[0,0,0]
	v_mfma_scale_f32_16x16x128_f8f6f4 v[58:61], v[26:33], v[178:185], v[58:61], v229, v229 op_sel_hi:[0,0,0]
	v_mfma_scale_f32_16x16x128_f8f6f4 v[50:53], v[18:25], v[206:213], v[50:53], v229, v229 op_sel_hi:[0,0,0]
	v_mfma_scale_f32_16x16x128_f8f6f4 v[42:45], v[26:33], v[206:213], v[42:45], v229, v229 op_sel_hi:[0,0,0]
	v_mfma_scale_f32_16x16x128_f8f6f4 v[38:41], v[18:25], v[214:221], v[38:41], v229, v229 op_sel_hi:[0,0,0]
	v_mfma_scale_f32_16x16x128_f8f6f4 v[34:37], v[26:33], v[214:221], v[34:37], v229, v229 op_sel_hi:[0,0,0]
	s_barrier
	s_setprio 0
	s_cbranch_scc0 .LBB0_1695
	s_nop 15
	s_nop 15
	s_nop 15
	s_nop 15
	s_nop 15
	s_and_b64 vcc, exec, s[12:13]
	s_cbranch_vccz .LBB0_1698
	s_barrier

; #define PG8_STAGE(bufoff, gbase, voff) do { _Pragma("unroll") for (int _i = 0; _i < 2; ++_i) \
;         __builtin_amdgcn_global_load_lds((const unsigned*)((const char*)(gbase) + (voff)[_i]), (PG8_LAS unsigned*)(lds + (bufoff) + ldsw + _i * 8192), 16, 0, 0); } while (0)
; #define PG8_WAIT_V(n) asm volatile("s_waitcnt vmcnt(" #n ")" ::: "memory")
; #define PG8_WAIT_L(n) asm volatile("s_waitcnt lgkmcnt(" #n ")" ::: "memory")
; #define PG8_BAR __builtin_amdgcn_s_barrier()
; #define PG8_SCHED __builtin_amdgcn_sched_barrier(0)
;     __device__ __forceinline__ int nt(const pg8::Unit& u) const { return u.kind == 0 ? ntiles : q_nt(u.kind - 1); }
; template <class Epi, class Sched, bool ALIGN_EPI = true, bool SP2 = true>
; __device__ __forceinline__ void gemm_phase(PG8_LAS unsigned char* lds, const int K  , const Sched& S, const Epi& E) {
;     ...
;             const bool last = (t == nt - 2);
;             const char* a1 = cA + (size_t)(t + 1) * kstep;
;             const char* a2 = last ? nA : cA + (size_t)(t + 2) * kstep; const char* b2 = last ? nB : cB + (size_t)(t + 2) * kstep;
;             const char* a3 = a2 + kstep; const char* b3 = b2 + kstep;
;             if constexpr (SP2) {
;             PG8_LDB(B0, 0, 0); PG8_LDB(B1, 0, 1); PG8_SCHED; PG8_LDA(At, 0, 0); PG8_STAGE(PG8_SA(1, 1), a1 + hstep, voffA);
;             PG8_WAIT_V(8); PG8_WAIT_L(0); PG8_BAR; PG8_MMA(0, 0, At, B0); PG8_MMA(0, 1, At, B1); PG8_BAR; PG8_SCHED;
;             PG8_LDA(At, 0, 1); PG8_STAGE(PG8_SB(0, 0), b2, voffB); PG8_STAGE(PG8_SB(0, 1), b2 + hstep, voffB); PG8_STAGE(PG8_SA(0, 0), a2, voffA);
;             PG8_WAIT_V(8); PG8_WAIT_L(0); PG8_BAR; PG8_MMA(1, 0, At, B0); PG8_MMA(1, 1, At, B1); PG8_BAR; PG8_SCHED;
.LBB0_1847:
	ds_read_b128 v[130:133], v176
	ds_read_b128 v[134:137], v176 offset:1024
	ds_read_b128 v[138:141], v176 offset:2048
	ds_read_b128 v[142:145], v176 offset:3072
	ds_read_b128 v[168:171], v177
	ds_read_b128 v[184:187], v177 offset:1024
	ds_read_b128 v[188:191], v177 offset:2048
	ds_read_b128 v[192:195], v177 offset:3072
	s_add_u32 s22, s0, 0xfff80080
	s_addc_u32 s23, s1, -1
	s_cmp_eq_u32 s51, 28
	s_cselect_b32 s25, s7, s23
	s_cselect_b32 s24, s47, s22
	s_cselect_b32 s23, s11, s50
	s_cselect_b32 s22, s48, s49
	v_lshl_add_u64 v[230:231], s[0:1], 0, v[160:161]
	s_add_i32 m0, s27, 0xc000
	ds_read_b128 v[196:199], v178
	ds_read_b128 v[200:203], v178 offset:1024
	ds_read_b128 v[204:207], v178 offset:2048
	ds_read_b128 v[208:211], v178 offset:3072
	ds_read_b128 v[212:215], v178 offset:4096
	ds_read_b128 v[216:219], v178 offset:5120
	ds_read_b128 v[220:223], v178 offset:6144
	ds_read_b128 v[224:227], v178 offset:7168
	global_load_lds_dwordx4 v[230:231], off
	v_lshl_add_u64 v[230:231], s[0:1], 0, v[162:163]
	s_add_i32 m0, s27, 0xe000
	s_nop 0
	global_load_lds_dwordx4 v[230:231], off
	s_waitcnt vmcnt(8)
	s_waitcnt lgkmcnt(0)
	s_setprio 1
	s_barrier
	v_mfma_f32_16x16x32_bf16 v[126:129], v[130:133], v[196:199], v[126:129]
	v_mfma_f32_16x16x32_bf16 v[122:125], v[138:141], v[196:199], v[122:125]
	v_mfma_f32_16x16x32_bf16 v[110:113], v[130:133], v[204:207], v[110:113]
	v_mfma_f32_16x16x32_bf16 v[106:109], v[138:141], v[204:207], v[106:109]
	v_mfma_f32_16x16x32_bf16 v[94:97], v[130:133], v[212:215], v[94:97]
	v_mfma_f32_16x16x32_bf16 v[90:93], v[138:141], v[212:215], v[90:93]
	v_mfma_f32_16x16x32_bf16 v[78:81], v[130:133], v[220:223], v[78:81]
	v_mfma_f32_16x16x32_bf16 v[74:77], v[138:141], v[220:223], v[74:77]
	v_mfma_f32_16x16x32_bf16 v[126:129], v[134:137], v[200:203], v[126:129]
	v_mfma_f32_16x16x32_bf16 v[122:125], v[142:145], v[200:203], v[122:125]
	v_mfma_f32_16x16x32_bf16 v[110:113], v[134:137], v[208:211], v[110:113]
	v_mfma_f32_16x16x32_bf16 v[106:109], v[142:145], v[208:211], v[106:109]
	v_mfma_f32_16x16x32_bf16 v[94:97], v[134:137], v[216:219], v[94:97]
	v_mfma_f32_16x16x32_bf16 v[90:93], v[142:145], v[216:219], v[90:93]
	v_mfma_f32_16x16x32_bf16 v[78:81], v[134:137], v[224:227], v[78:81]
	v_mfma_f32_16x16x32_bf16 v[74:77], v[142:145], v[224:227], v[74:77]
	s_setprio 0
	s_setprio 1
	v_mfma_f32_16x16x32_bf16 v[118:121], v[168:171], v[196:199], v[118:121]
	v_mfma_f32_16x16x32_bf16 v[114:117], v[188:191], v[196:199], v[114:117]
	v_mfma_f32_16x16x32_bf16 v[102:105], v[168:171], v[204:207], v[102:105]
	v_mfma_f32_16x16x32_bf16 v[98:101], v[188:191], v[204:207], v[98:101]
	v_mfma_f32_16x16x32_bf16 v[86:89], v[168:171], v[212:215], v[86:89]
	v_mfma_f32_16x16x32_bf16 v[82:85], v[188:191], v[212:215], v[82:85]
	v_mfma_f32_16x16x32_bf16 v[70:73], v[168:171], v[220:223], v[70:73]
	v_mfma_f32_16x16x32_bf16 v[66:69], v[188:191], v[220:223], v[66:69]
	v_mfma_f32_16x16x32_bf16 v[118:121], v[184:187], v[200:203], v[118:121]
	v_mfma_f32_16x16x32_bf16 v[114:117], v[192:195], v[200:203], v[114:117]
	v_mfma_f32_16x16x32_bf16 v[102:105], v[184:187], v[208:211], v[102:105]
	v_mfma_f32_16x16x32_bf16 v[98:101], v[192:195], v[208:211], v[98:101]
	v_mfma_f32_16x16x32_bf16 v[86:89], v[184:187], v[216:219], v[86:89]
	v_mfma_f32_16x16x32_bf16 v[82:85], v[192:195], v[216:219], v[82:85]
	v_mfma_f32_16x16x32_bf16 v[70:73], v[184:187], v[224:227], v[70:73]
	v_mfma_f32_16x16x32_bf16 v[66:69], v[192:195], v[224:227], v[66:69]
	s_barrier
	s_setprio 0
	s_add_i32 s68, s39, s26
	v_lshl_add_u64 v[230:231], s[22:23], 0, v[150:151]
	s_mov_b32 m0, s68
	ds_read_b128 v[196:199], v178 offset:16384
	ds_read_b128 v[200:203], v178 offset:17408
	ds_read_b128 v[204:207], v178 offset:18432
	ds_read_b128 v[208:211], v178 offset:19456
	ds_read_b128 v[212:215], v178 offset:20480
	ds_read_b128 v[216:219], v178 offset:21504
	ds_read_b128 v[220:223], v178 offset:22528
	ds_read_b128 v[224:227], v178 offset:23552
	global_load_lds_dwordx4 v[230:231], off
	s_add_i32 m0, s68, 0x2000
	s_add_u32 s68, s22, 0x80000
	v_lshl_add_u64 v[232:233], s[22:23], 0, v[154:155]
	s_addc_u32 s69, s23, 0
	s_add_i32 s70, s40, s26
	global_load_lds_dwordx4 v[232:233], off
	v_lshl_add_u64 v[234:235], s[68:69], 0, v[150:151]
	s_mov_b32 m0, s70
	v_lshl_add_u64 v[236:237], s[24:25], 0, v[152:153]
	global_load_lds_dwordx4 v[234:235], off
	v_lshl_add_u64 v[234:235], s[68:69], 0, v[154:155]
	s_add_i32 m0, s70, 0x2000
	s_nop 0
	global_load_lds_dwordx4 v[234:235], off
	v_lshl_add_u64 v[234:235], s[24:25], 0, v[148:149]
	s_mov_b32 m0, s27
	s_nop 0
	global_load_lds_dwordx4 v[234:235], off
	s_mov_b32 m0, s28
	s_nop 0
	global_load_lds_dwordx4 v[236:237], off
	s_waitcnt vmcnt(8)
	s_waitcnt lgkmcnt(0)
	s_setprio 1
	s_barrier
; #define PG8_STAGE(bufoff, gbase, voff) do { _Pragma("unroll") for (int _i = 0; _i < 2; ++_i) \
;         __builtin_amdgcn_global_load_lds((const unsigned*)((const char*)(gbase) + (voff)[_i]), (PG8_LAS unsigned*)(lds + (bufoff) + ldsw + _i * 8192), 16, 0, 0); } while (0)
; #define PG8_WAIT_V(n) asm volatile("s_waitcnt vmcnt(" #n ")" ::: "memory")
; #define PG8_WAIT_L(n) asm volatile("s_waitcnt lgkmcnt(" #n ")" ::: "memory")
; #define PG8_BAR __builtin_amdgcn_s_barrier()
; #define PG8_SCHED __builtin_amdgcn_sched_barrier(0)
; template <class Epi, class Sched, bool ALIGN_EPI = true, bool SP2 = true>
; __device__ __forceinline__ void gemm_phase(PG8_LAS unsigned char* lds, const int K  , const Sched& S, const Epi& E) {
;     ...
;             PG8_WAIT_V(8); PG8_WAIT_L(0); PG8_BAR; PG8_MMA(1, 0, At, B0); PG8_MMA(1, 1, At, B1); PG8_BAR; PG8_SCHED;
;             PG8_LDB(B0, 1, 0); PG8_LDB(B1, 1, 1); PG8_SCHED; PG8_LDA(At, 1, 0); PG8_STAGE(PG8_SA(0, 1), a2 + hstep, voffA);
;             PG8_WAIT_V(8); PG8_WAIT_L(0); PG8_BAR; PG8_MMA(0, 0, At, B0); PG8_MMA(0, 1, At, B1); PG8_BAR; PG8_SCHED;
	v_mfma_f32_16x16x32_bf16 v[62:65], v[130:133], v[196:199], v[62:65]
	v_mfma_f32_16x16x32_bf16 v[58:61], v[138:141], v[196:199], v[58:61]
	v_mfma_f32_16x16x32_bf16 v[46:49], v[130:133], v[204:207], v[46:49]
	v_mfma_f32_16x16x32_bf16 v[42:45], v[138:141], v[204:207], v[42:45]
	v_mfma_f32_16x16x32_bf16 v[30:33], v[130:133], v[212:215], v[30:33]
	v_mfma_f32_16x16x32_bf16 v[26:29], v[138:141], v[212:215], v[26:29]
	v_mfma_f32_16x16x32_bf16 v[14:17], v[130:133], v[220:223], v[14:17]
	v_mfma_f32_16x16x32_bf16 v[10:13], v[138:141], v[220:223], v[10:13]
	v_mfma_f32_16x16x32_bf16 v[62:65], v[134:137], v[200:203], v[62:65]
	v_mfma_f32_16x16x32_bf16 v[58:61], v[142:145], v[200:203], v[58:61]
	v_mfma_f32_16x16x32_bf16 v[46:49], v[134:137], v[208:211], v[46:49]
	v_mfma_f32_16x16x32_bf16 v[42:45], v[142:145], v[208:211], v[42:45]
	v_mfma_f32_16x16x32_bf16 v[30:33], v[134:137], v[216:219], v[30:33]
	v_mfma_f32_16x16x32_bf16 v[26:29], v[142:145], v[216:219], v[26:29]
	v_mfma_f32_16x16x32_bf16 v[14:17], v[134:137], v[224:227], v[14:17]
	v_mfma_f32_16x16x32_bf16 v[10:13], v[142:145], v[224:227], v[10:13]
	s_setprio 0
	s_setprio 1
	v_mfma_f32_16x16x32_bf16 v[54:57], v[168:171], v[196:199], v[54:57]
	v_mfma_f32_16x16x32_bf16 v[50:53], v[188:191], v[196:199], v[50:53]
	v_mfma_f32_16x16x32_bf16 v[38:41], v[168:171], v[204:207], v[38:41]
	v_mfma_f32_16x16x32_bf16 v[34:37], v[188:191], v[204:207], v[34:37]
	v_mfma_f32_16x16x32_bf16 v[22:25], v[168:171], v[212:215], v[22:25]
	v_mfma_f32_16x16x32_bf16 v[18:21], v[188:191], v[212:215], v[18:21]
	v_mfma_f32_16x16x32_bf16 v[6:9], v[168:171], v[220:223], v[6:9]
	v_mfma_f32_16x16x32_bf16 v[2:5], v[188:191], v[220:223], v[2:5]
	v_mfma_f32_16x16x32_bf16 v[54:57], v[184:187], v[200:203], v[54:57]
	v_mfma_f32_16x16x32_bf16 v[50:53], v[192:195], v[200:203], v[50:53]
	v_mfma_f32_16x16x32_bf16 v[38:41], v[184:187], v[208:211], v[38:41]
	v_mfma_f32_16x16x32_bf16 v[34:37], v[192:195], v[208:211], v[34:37]
	v_mfma_f32_16x16x32_bf16 v[22:25], v[184:187], v[216:219], v[22:25]
	v_mfma_f32_16x16x32_bf16 v[18:21], v[192:195], v[216:219], v[18:21]
	v_mfma_f32_16x16x32_bf16 v[6:9], v[184:187], v[224:227], v[6:9]
	v_mfma_f32_16x16x32_bf16 v[2:5], v[192:195], v[224:227], v[2:5]
	s_barrier
	s_setprio 0
	s_add_i32 s68, 0, 0x18000
	s_add_i32 s69, 0, 0x1c000
	v_add_u32_e32 v142, s68, v172
	v_add_u32_e32 v192, s69, v172
	ds_read_b128 v[130:133], v142
	ds_read_b128 v[134:137], v142 offset:1024
	ds_read_b128 v[138:141], v142 offset:2048
	ds_read_b128 v[142:145], v142 offset:3072
	ds_read_b128 v[168:171], v192
	ds_read_b128 v[184:187], v192 offset:1024
	ds_read_b128 v[188:191], v192 offset:2048
	ds_read_b128 v[192:195], v192 offset:3072
	s_add_u32 s24, s24, 0x80000
	s_addc_u32 s25, s25, 0
	s_mov_b32 m0, s29
	v_lshl_add_u64 v[238:239], s[24:25], 0, v[148:149]
	ds_read_b128 v[196:199], v178 offset:32768
	ds_read_b128 v[200:203], v178 offset:33792
	ds_read_b128 v[204:207], v178 offset:34816
	ds_read_b128 v[208:211], v178 offset:35840
	ds_read_b128 v[212:215], v178 offset:36864
	ds_read_b128 v[216:219], v178 offset:37888
	ds_read_b128 v[220:223], v178 offset:38912
	ds_read_b128 v[224:227], v178 offset:39936
	global_load_lds_dwordx4 v[238:239], off
	v_lshl_add_u64 v[238:239], s[24:25], 0, v[152:153]
	s_mov_b32 m0, s30
	s_nop 0
	global_load_lds_dwordx4 v[238:239], off
	s_waitcnt vmcnt(8)
	s_waitcnt lgkmcnt(0)
	s_setprio 1
	s_barrier
	v_mfma_f32_16x16x32_bf16 v[126:129], v[130:133], v[196:199], v[126:129]
	v_mfma_f32_16x16x32_bf16 v[122:125], v[138:141], v[196:199], v[122:125]
	v_mfma_f32_16x16x32_bf16 v[110:113], v[130:133], v[204:207], v[110:113]
	v_mfma_f32_16x16x32_bf16 v[106:109], v[138:141], v[204:207], v[106:109]
	v_mfma_f32_16x16x32_bf16 v[94:97], v[130:133], v[212:215], v[94:97]
	v_mfma_f32_16x16x32_bf16 v[90:93], v[138:141], v[212:215], v[90:93]
	v_mfma_f32_16x16x32_bf16 v[78:81], v[130:133], v[220:223], v[78:81]
	v_mfma_f32_16x16x32_bf16 v[74:77], v[138:141], v[220:223], v[74:77]
	v_mfma_f32_16x16x32_bf16 v[126:129], v[134:137], v[200:203], v[126:129]
	v_mfma_f32_16x16x32_bf16 v[122:125], v[142:145], v[200:203], v[122:125]
	v_mfma_f32_16x16x32_bf16 v[110:113], v[134:137], v[208:211], v[110:113]
	v_mfma_f32_16x16x32_bf16 v[106:109], v[142:145], v[208:211], v[106:109]
	v_mfma_f32_16x16x32_bf16 v[94:97], v[134:137], v[216:219], v[94:97]
	v_mfma_f32_16x16x32_bf16 v[90:93], v[142:145], v[216:219], v[90:93]
	v_mfma_f32_16x16x32_bf16 v[78:81], v[134:137], v[224:227], v[78:81]
	v_mfma_f32_16x16x32_bf16 v[74:77], v[142:145], v[224:227], v[74:77]
	s_setprio 0
	s_setprio 1
	v_mfma_f32_16x16x32_bf16 v[118:121], v[168:171], v[196:199], v[118:121]
	v_mfma_f32_16x16x32_bf16 v[114:117], v[188:191], v[196:199], v[114:117]
	v_mfma_f32_16x16x32_bf16 v[102:105], v[168:171], v[204:207], v[102:105]
	v_mfma_f32_16x16x32_bf16 v[98:101], v[188:191], v[204:207], v[98:101]
	v_mfma_f32_16x16x32_bf16 v[86:89], v[168:171], v[212:215], v[86:89]
	v_mfma_f32_16x16x32_bf16 v[82:85], v[188:191], v[212:215], v[82:85]
	v_mfma_f32_16x16x32_bf16 v[70:73], v[168:171], v[220:223], v[70:73]
	v_mfma_f32_16x16x32_bf16 v[66:69], v[188:191], v[220:223], v[66:69]
	v_mfma_f32_16x16x32_bf16 v[118:121], v[184:187], v[200:203], v[118:121]
	v_mfma_f32_16x16x32_bf16 v[114:117], v[192:195], v[200:203], v[114:117]
	v_mfma_f32_16x16x32_bf16 v[102:105], v[184:187], v[208:211], v[102:105]
	v_mfma_f32_16x16x32_bf16 v[98:101], v[192:195], v[208:211], v[98:101]
	v_mfma_f32_16x16x32_bf16 v[86:89], v[184:187], v[216:219], v[86:89]
	v_mfma_f32_16x16x32_bf16 v[82:85], v[192:195], v[216:219], v[82:85]
	v_mfma_f32_16x16x32_bf16 v[70:73], v[184:187], v[224:227], v[70:73]
	v_mfma_f32_16x16x32_bf16 v[66:69], v[192:195], v[224:227], v[66:69]
	s_barrier
; #define PG8_STAGE(bufoff, gbase, voff) do { _Pragma("unroll") for (int _i = 0; _i < 2; ++_i) \
;         __builtin_amdgcn_global_load_lds((const unsigned*)((const char*)(gbase) + (voff)[_i]), (PG8_LAS unsigned*)(lds + (bufoff) + ldsw + _i * 8192), 16, 0, 0); } while (0)
; #define PG8_WAIT_V(n) asm volatile("s_waitcnt vmcnt(" #n ")" ::: "memory")
; #define PG8_WAIT_L(n) asm volatile("s_waitcnt lgkmcnt(" #n ")" ::: "memory")
; #define PG8_BAR __builtin_amdgcn_s_barrier()
; #define PG8_SCHED __builtin_amdgcn_sched_barrier(0)
; template <class Epi, class Sched, bool ALIGN_EPI = true, bool SP2 = true>
; __device__ __forceinline__ void gemm_phase(PG8_LAS unsigned char* lds, const int K  , const Sched& S, const Epi& E) {
;     ...
;             PG8_LDA(At, 1, 1); PG8_STAGE(PG8_SB(1, 0), b3, voffB); PG8_STAGE(PG8_SB(1, 1), b3 + hstep, voffB); PG8_STAGE(PG8_SA(1, 0), a3, voffA);
;             PG8_WAIT_V(8); PG8_WAIT_L(0); PG8_BAR; PG8_MMA(1, 0, At, B0); PG8_MMA(1, 1, At, B1); PG8_BAR; PG8_SCHED;
	s_setprio 0
	s_add_i32 s24, s68, s26
	v_lshl_add_u64 v[230:231], v[230:231], 0, s[4:5]
	s_mov_b32 m0, s24
	ds_read_b128 v[196:199], v178 offset:49152
	ds_read_b128 v[200:203], v178 offset:50176
	ds_read_b128 v[204:207], v178 offset:51200
	ds_read_b128 v[208:211], v178 offset:52224
	ds_read_b128 v[212:215], v178 offset:53248
	ds_read_b128 v[216:219], v178 offset:54272
	ds_read_b128 v[220:223], v178 offset:55296
	ds_read_b128 v[224:227], v178 offset:56320
	global_load_lds_dwordx4 v[230:231], off
	s_add_i32 m0, s24, 0x2000
	s_add_u32 s22, s22, 0x80080
	v_lshl_add_u64 v[230:231], v[232:233], 0, s[4:5]
	s_addc_u32 s23, s23, 0
	s_add_i32 s24, s69, s26
	global_load_lds_dwordx4 v[230:231], off
	v_lshl_add_u64 v[230:231], s[22:23], 0, v[150:151]
	s_mov_b32 m0, s24
	s_nop 0
	global_load_lds_dwordx4 v[230:231], off
	v_lshl_add_u64 v[230:231], s[22:23], 0, v[154:155]
	s_add_i32 m0, s24, 0x2000
	s_nop 0
	global_load_lds_dwordx4 v[230:231], off
	v_lshl_add_u64 v[230:231], v[234:235], 0, s[4:5]
	s_mov_b32 m0, s35
	s_nop 0
	global_load_lds_dwordx4 v[230:231], off
	v_lshl_add_u64 v[230:231], v[236:237], 0, s[4:5]
	s_mov_b32 m0, s36
	s_nop 0
	global_load_lds_dwordx4 v[230:231], off
	s_add_i32 s51, s51, 2
	s_add_u32 s0, s0, 0x100
	s_addc_u32 s1, s1, 0
	s_add_u32 s49, s49, 0x100
	s_addc_u32 s50, s50, 0
	s_cmp_gt_u32 s51, 29
	s_waitcnt vmcnt(8)
	s_waitcnt lgkmcnt(0)
	s_setprio 1
	s_barrier
	v_mfma_f32_16x16x32_bf16 v[62:65], v[130:133], v[196:199], v[62:65]
	v_mfma_f32_16x16x32_bf16 v[58:61], v[138:141], v[196:199], v[58:61]
	v_mfma_f32_16x16x32_bf16 v[46:49], v[130:133], v[204:207], v[46:49]
	v_mfma_f32_16x16x32_bf16 v[42:45], v[138:141], v[204:207], v[42:45]
	v_mfma_f32_16x16x32_bf16 v[30:33], v[130:133], v[212:215], v[30:33]
	v_mfma_f32_16x16x32_bf16 v[26:29], v[138:141], v[212:215], v[26:29]
	v_mfma_f32_16x16x32_bf16 v[14:17], v[130:133], v[220:223], v[14:17]
	v_mfma_f32_16x16x32_bf16 v[10:13], v[138:141], v[220:223], v[10:13]
	v_mfma_f32_16x16x32_bf16 v[62:65], v[134:137], v[200:203], v[62:65]
	v_mfma_f32_16x16x32_bf16 v[58:61], v[142:145], v[200:203], v[58:61]
	v_mfma_f32_16x16x32_bf16 v[46:49], v[134:137], v[208:211], v[46:49]
	v_mfma_f32_16x16x32_bf16 v[42:45], v[142:145], v[208:211], v[42:45]
	v_mfma_f32_16x16x32_bf16 v[30:33], v[134:137], v[216:219], v[30:33]
	v_mfma_f32_16x16x32_bf16 v[26:29], v[142:145], v[216:219], v[26:29]
	v_mfma_f32_16x16x32_bf16 v[14:17], v[134:137], v[224:227], v[14:17]
	v_mfma_f32_16x16x32_bf16 v[10:13], v[142:145], v[224:227], v[10:13]
	s_setprio 0
	s_setprio 1
	v_mfma_f32_16x16x32_bf16 v[54:57], v[168:171], v[196:199], v[54:57]
	v_mfma_f32_16x16x32_bf16 v[50:53], v[188:191], v[196:199], v[50:53]
	v_mfma_f32_16x16x32_bf16 v[38:41], v[168:171], v[204:207], v[38:41]
	v_mfma_f32_16x16x32_bf16 v[34:37], v[188:191], v[204:207], v[34:37]
	v_mfma_f32_16x16x32_bf16 v[22:25], v[168:171], v[212:215], v[22:25]
	v_mfma_f32_16x16x32_bf16 v[18:21], v[188:191], v[212:215], v[18:21]
	v_mfma_f32_16x16x32_bf16 v[6:9], v[168:171], v[220:223], v[6:9]
	v_mfma_f32_16x16x32_bf16 v[2:5], v[188:191], v[220:223], v[2:5]
	v_mfma_f32_16x16x32_bf16 v[54:57], v[184:187], v[200:203], v[54:57]
	v_mfma_f32_16x16x32_bf16 v[50:53], v[192:195], v[200:203], v[50:53]
	v_mfma_f32_16x16x32_bf16 v[38:41], v[184:187], v[208:211], v[38:41]
	v_mfma_f32_16x16x32_bf16 v[34:37], v[192:195], v[208:211], v[34:37]
	v_mfma_f32_16x16x32_bf16 v[22:25], v[184:187], v[216:219], v[22:25]
	v_mfma_f32_16x16x32_bf16 v[18:21], v[192:195], v[216:219], v[18:21]
	v_mfma_f32_16x16x32_bf16 v[6:9], v[184:187], v[224:227], v[6:9]
	v_mfma_f32_16x16x32_bf16 v[2:5], v[192:195], v[224:227], v[2:5]
	s_barrier
	s_setprio 0
	s_cbranch_scc0 .LBB0_1847
	s_and_b64 vcc, exec, s[8:9]
	s_cbranch_vccz .LBB0_1850
	s_barrier

; #define PG8_STAGE(bufoff, gbase, voff) do { _Pragma("unroll") for (int _i = 0; _i < 2; ++_i) \
;         __builtin_amdgcn_global_load_lds((const unsigned*)((const char*)(gbase) + (voff)[_i]), (PG8_LAS unsigned*)(lds + (bufoff) + ldsw + _i * 8192), 16, 0, 0); } while (0)
; #define PG8_WAIT_V(n) asm volatile("s_waitcnt vmcnt(" #n ")" ::: "memory")
; #define PG8_WAIT_L(n) asm volatile("s_waitcnt lgkmcnt(" #n ")" ::: "memory")
; #define PG8_BAR __builtin_amdgcn_s_barrier()
; #define PG8_SCHED __builtin_amdgcn_sched_barrier(0)
;     __device__ __forceinline__ int nt(const pg8::Unit& u) const { return u.kind == 0 ? ntiles : q_nt(u.kind - 1); }
; template <class Epi, class Sched, bool ALIGN_EPI = true, bool SP2 = true>
; __device__ __forceinline__ void gemm_phase(PG8_LAS unsigned char* lds, const int K  , const Sched& S, const Epi& E) {
;     ...
;             const bool last = (t == nt - 2);
;             const char* a1 = cA + (size_t)(t + 1) * kstep;
;             const char* a2 = last ? nA : cA + (size_t)(t + 2) * kstep; const char* b2 = last ? nB : cB + (size_t)(t + 2) * kstep;
;             const char* a3 = a2 + kstep; const char* b3 = b2 + kstep;
;             if constexpr (SP2) {
;             PG8_LDB(B0, 0, 0); PG8_LDB(B1, 0, 1); PG8_SCHED; PG8_LDA(At, 0, 0); PG8_STAGE(PG8_SA(1, 1), a1 + hstep, voffA);
;             PG8_WAIT_V(8); PG8_WAIT_L(0); PG8_BAR; PG8_MMA(0, 0, At, B0); PG8_MMA(0, 1, At, B1); PG8_BAR; PG8_SCHED;
;             PG8_LDA(At, 0, 1); PG8_STAGE(PG8_SB(0, 0), b2, voffB); PG8_STAGE(PG8_SB(0, 1), b2 + hstep, voffB); PG8_STAGE(PG8_SA(0, 0), a2, voffA);
;             PG8_WAIT_V(8); PG8_WAIT_L(0); PG8_BAR; PG8_MMA(1, 0, At, B0); PG8_MMA(1, 1, At, B1); PG8_BAR; PG8_SCHED;
.LBB0_2296:
	ds_read_b128 v[130:133], v203
	ds_read_b128 v[134:137], v203 offset:1024
	ds_read_b128 v[138:141], v203 offset:2048
	ds_read_b128 v[142:145], v203 offset:3072
	ds_read_b128 v[146:149], v204
	ds_read_b128 v[150:153], v204 offset:1024
	ds_read_b128 v[154:157], v204 offset:2048
	ds_read_b128 v[158:161], v204 offset:3072
	s_add_u32 s22, s20, 0xfff80080
	s_addc_u32 s23, s21, -1
	s_cmp_eq_u32 s54, 28
	s_cselect_b32 s25, s13, s23
	s_cselect_b32 s24, s50, s22
	s_cselect_b32 s23, s11, s53
	s_cselect_b32 s22, s51, s52
	v_lshl_add_u64 v[198:199], s[20:21], 0, v[190:191]
	s_add_i32 m0, s19, 0xc000
	ds_read_b128 v[162:165], v205
	ds_read_b128 v[166:169], v205 offset:1024
	ds_read_b128 v[170:173], v205 offset:2048
	ds_read_b128 v[174:177], v205 offset:3072
	ds_read_b128 v[178:181], v205 offset:4096
	ds_read_b128 v[206:209], v205 offset:5120
	ds_read_b128 v[210:213], v205 offset:6144
	ds_read_b128 v[214:217], v205 offset:7168
	global_load_lds_dwordx4 v[198:199], off
	v_lshl_add_u64 v[198:199], s[20:21], 0, v[192:193]
	s_add_i32 m0, s19, 0xe000
	s_nop 0
	global_load_lds_dwordx4 v[198:199], off
	s_waitcnt vmcnt(8)
	s_waitcnt lgkmcnt(0)
	s_setprio 1
	s_barrier
	v_mfma_f32_16x16x32_bf16 v[126:129], v[130:133], v[162:165], v[126:129]
	v_mfma_f32_16x16x32_bf16 v[122:125], v[138:141], v[162:165], v[122:125]
	v_mfma_f32_16x16x32_bf16 v[114:117], v[130:133], v[170:173], v[114:117]
	v_mfma_f32_16x16x32_bf16 v[106:109], v[138:141], v[170:173], v[106:109]
	v_mfma_f32_16x16x32_bf16 v[98:101], v[130:133], v[178:181], v[98:101]
	v_mfma_f32_16x16x32_bf16 v[90:93], v[138:141], v[178:181], v[90:93]
	v_mfma_f32_16x16x32_bf16 v[82:85], v[130:133], v[210:213], v[82:85]
	v_mfma_f32_16x16x32_bf16 v[74:77], v[138:141], v[210:213], v[74:77]
	v_mfma_f32_16x16x32_bf16 v[126:129], v[134:137], v[166:169], v[126:129]
	v_mfma_f32_16x16x32_bf16 v[122:125], v[142:145], v[166:169], v[122:125]
	v_mfma_f32_16x16x32_bf16 v[114:117], v[134:137], v[174:177], v[114:117]
	v_mfma_f32_16x16x32_bf16 v[106:109], v[142:145], v[174:177], v[106:109]
	v_mfma_f32_16x16x32_bf16 v[98:101], v[134:137], v[206:209], v[98:101]
	v_mfma_f32_16x16x32_bf16 v[90:93], v[142:145], v[206:209], v[90:93]
	v_mfma_f32_16x16x32_bf16 v[82:85], v[134:137], v[214:217], v[82:85]
	v_mfma_f32_16x16x32_bf16 v[74:77], v[142:145], v[214:217], v[74:77]
	s_setprio 0
	s_setprio 1
	v_mfma_f32_16x16x32_bf16 v[118:121], v[146:149], v[162:165], v[118:121]
	v_mfma_f32_16x16x32_bf16 v[110:113], v[154:157], v[162:165], v[110:113]
	v_mfma_f32_16x16x32_bf16 v[102:105], v[146:149], v[170:173], v[102:105]
	v_mfma_f32_16x16x32_bf16 v[94:97], v[154:157], v[170:173], v[94:97]
	v_mfma_f32_16x16x32_bf16 v[86:89], v[146:149], v[178:181], v[86:89]
	v_mfma_f32_16x16x32_bf16 v[78:81], v[154:157], v[178:181], v[78:81]
	v_mfma_f32_16x16x32_bf16 v[70:73], v[146:149], v[210:213], v[70:73]
	v_mfma_f32_16x16x32_bf16 v[66:69], v[154:157], v[210:213], v[66:69]
	v_mfma_f32_16x16x32_bf16 v[118:121], v[150:153], v[166:169], v[118:121]
	v_mfma_f32_16x16x32_bf16 v[110:113], v[158:161], v[166:169], v[110:113]
	v_mfma_f32_16x16x32_bf16 v[102:105], v[150:153], v[174:177], v[102:105]
	v_mfma_f32_16x16x32_bf16 v[94:97], v[158:161], v[174:177], v[94:97]
	v_mfma_f32_16x16x32_bf16 v[86:89], v[150:153], v[206:209], v[86:89]
	v_mfma_f32_16x16x32_bf16 v[78:81], v[158:161], v[206:209], v[78:81]
	v_mfma_f32_16x16x32_bf16 v[70:73], v[150:153], v[214:217], v[70:73]
	v_mfma_f32_16x16x32_bf16 v[66:69], v[158:161], v[214:217], v[66:69]
	s_barrier
	s_setprio 0
	s_add_i32 s55, s42, s29
	v_lshl_add_u64 v[198:199], s[22:23], 0, v[184:185]
	s_mov_b32 m0, s55
	ds_read_b128 v[162:165], v205 offset:16384
	ds_read_b128 v[166:169], v205 offset:17408
	ds_read_b128 v[170:173], v205 offset:18432
	ds_read_b128 v[174:177], v205 offset:19456
	ds_read_b128 v[178:181], v205 offset:20480
	ds_read_b128 v[206:209], v205 offset:21504
	ds_read_b128 v[210:213], v205 offset:22528
	ds_read_b128 v[214:217], v205 offset:23552
	global_load_lds_dwordx4 v[198:199], off
	s_add_i32 m0, s55, 0x2000
	s_add_u32 s56, s22, 0x80000
	v_lshl_add_u64 v[218:219], s[22:23], 0, v[188:189]
	s_addc_u32 s57, s23, 0
	s_add_i32 s55, s43, s29
	global_load_lds_dwordx4 v[218:219], off
	v_lshl_add_u64 v[220:221], s[56:57], 0, v[184:185]
	s_mov_b32 m0, s55
	v_lshl_add_u64 v[222:223], s[24:25], 0, v[186:187]
	global_load_lds_dwordx4 v[220:221], off
	v_lshl_add_u64 v[220:221], s[56:57], 0, v[188:189]
	s_add_i32 m0, s55, 0x2000
	s_nop 0
	global_load_lds_dwordx4 v[220:221], off
	v_lshl_add_u64 v[220:221], s[24:25], 0, v[182:183]
	s_mov_b32 m0, s19
	s_nop 0
	global_load_lds_dwordx4 v[220:221], off
	s_mov_b32 m0, s30
	s_nop 0
	global_load_lds_dwordx4 v[222:223], off
	s_waitcnt vmcnt(8)
	s_waitcnt lgkmcnt(0)
	s_setprio 1
	s_barrier
; #define PG8_STAGE(bufoff, gbase, voff) do { _Pragma("unroll") for (int _i = 0; _i < 2; ++_i) \
;         __builtin_amdgcn_global_load_lds((const unsigned*)((const char*)(gbase) + (voff)[_i]), (PG8_LAS unsigned*)(lds + (bufoff) + ldsw + _i * 8192), 16, 0, 0); } while (0)
; #define PG8_WAIT_V(n) asm volatile("s_waitcnt vmcnt(" #n ")" ::: "memory")
; #define PG8_WAIT_L(n) asm volatile("s_waitcnt lgkmcnt(" #n ")" ::: "memory")
; #define PG8_BAR __builtin_amdgcn_s_barrier()
; #define PG8_SCHED __builtin_amdgcn_sched_barrier(0)
; template <class Epi, class Sched, bool ALIGN_EPI = true, bool SP2 = true>
; __device__ __forceinline__ void gemm_phase(PG8_LAS unsigned char* lds, const int K  , const Sched& S, const Epi& E) {
;     ...
;             PG8_WAIT_V(8); PG8_WAIT_L(0); PG8_BAR; PG8_MMA(1, 0, At, B0); PG8_MMA(1, 1, At, B1); PG8_BAR; PG8_SCHED;
;             PG8_LDB(B0, 1, 0); PG8_LDB(B1, 1, 1); PG8_SCHED; PG8_LDA(At, 1, 0); PG8_STAGE(PG8_SA(0, 1), a2 + hstep, voffA);
;             PG8_WAIT_V(8); PG8_WAIT_L(0); PG8_BAR; PG8_MMA(0, 0, At, B0); PG8_MMA(0, 1, At, B1); PG8_BAR; PG8_SCHED;
	v_mfma_f32_16x16x32_bf16 v[62:65], v[130:133], v[162:165], v[62:65]
	v_mfma_f32_16x16x32_bf16 v[58:61], v[138:141], v[162:165], v[58:61]
	v_mfma_f32_16x16x32_bf16 v[50:53], v[130:133], v[170:173], v[50:53]
	v_mfma_f32_16x16x32_bf16 v[42:45], v[138:141], v[170:173], v[42:45]
	v_mfma_f32_16x16x32_bf16 v[34:37], v[130:133], v[178:181], v[34:37]
	v_mfma_f32_16x16x32_bf16 v[26:29], v[138:141], v[178:181], v[26:29]
	v_mfma_f32_16x16x32_bf16 v[18:21], v[130:133], v[210:213], v[18:21]
	v_mfma_f32_16x16x32_bf16 v[10:13], v[138:141], v[210:213], v[10:13]
	v_mfma_f32_16x16x32_bf16 v[62:65], v[134:137], v[166:169], v[62:65]
	v_mfma_f32_16x16x32_bf16 v[58:61], v[142:145], v[166:169], v[58:61]
	v_mfma_f32_16x16x32_bf16 v[50:53], v[134:137], v[174:177], v[50:53]
	v_mfma_f32_16x16x32_bf16 v[42:45], v[142:145], v[174:177], v[42:45]
	v_mfma_f32_16x16x32_bf16 v[34:37], v[134:137], v[206:209], v[34:37]
	v_mfma_f32_16x16x32_bf16 v[26:29], v[142:145], v[206:209], v[26:29]
	v_mfma_f32_16x16x32_bf16 v[18:21], v[134:137], v[214:217], v[18:21]
	v_mfma_f32_16x16x32_bf16 v[10:13], v[142:145], v[214:217], v[10:13]
	s_setprio 0
	s_setprio 1
	v_mfma_f32_16x16x32_bf16 v[54:57], v[146:149], v[162:165], v[54:57]
	v_mfma_f32_16x16x32_bf16 v[46:49], v[154:157], v[162:165], v[46:49]
	v_mfma_f32_16x16x32_bf16 v[38:41], v[146:149], v[170:173], v[38:41]
	v_mfma_f32_16x16x32_bf16 v[30:33], v[154:157], v[170:173], v[30:33]
	v_mfma_f32_16x16x32_bf16 v[22:25], v[146:149], v[178:181], v[22:25]
	v_mfma_f32_16x16x32_bf16 v[14:17], v[154:157], v[178:181], v[14:17]
	v_mfma_f32_16x16x32_bf16 v[6:9], v[146:149], v[210:213], v[6:9]
	v_mfma_f32_16x16x32_bf16 v[2:5], v[154:157], v[210:213], v[2:5]
	v_mfma_f32_16x16x32_bf16 v[54:57], v[150:153], v[166:169], v[54:57]
	v_mfma_f32_16x16x32_bf16 v[46:49], v[158:161], v[166:169], v[46:49]
	v_mfma_f32_16x16x32_bf16 v[38:41], v[150:153], v[174:177], v[38:41]
	v_mfma_f32_16x16x32_bf16 v[30:33], v[158:161], v[174:177], v[30:33]
	v_mfma_f32_16x16x32_bf16 v[22:25], v[150:153], v[206:209], v[22:25]
	v_mfma_f32_16x16x32_bf16 v[14:17], v[158:161], v[206:209], v[14:17]
	v_mfma_f32_16x16x32_bf16 v[6:9], v[150:153], v[214:217], v[6:9]
	v_mfma_f32_16x16x32_bf16 v[2:5], v[158:161], v[214:217], v[2:5]
	s_barrier
	s_setprio 0
	s_add_i32 s55, 0, 0x18000
	s_add_i32 s56, 0, 0x1c000
	v_add_u32_e32 v142, s55, v201
	v_add_u32_e32 v158, s56, v201
	ds_read_b128 v[130:133], v142
	ds_read_b128 v[134:137], v142 offset:1024
	ds_read_b128 v[138:141], v142 offset:2048
	ds_read_b128 v[142:145], v142 offset:3072
	ds_read_b128 v[146:149], v158
	ds_read_b128 v[150:153], v158 offset:1024
	ds_read_b128 v[154:157], v158 offset:2048
	ds_read_b128 v[158:161], v158 offset:3072
	s_add_u32 s24, s24, 0x80000
	s_addc_u32 s25, s25, 0
	s_mov_b32 m0, s31
	v_lshl_add_u64 v[224:225], s[24:25], 0, v[182:183]
	ds_read_b128 v[162:165], v205 offset:32768
	ds_read_b128 v[166:169], v205 offset:33792
	ds_read_b128 v[170:173], v205 offset:34816
	ds_read_b128 v[174:177], v205 offset:35840
	ds_read_b128 v[178:181], v205 offset:36864
	ds_read_b128 v[206:209], v205 offset:37888
	ds_read_b128 v[210:213], v205 offset:38912
	ds_read_b128 v[214:217], v205 offset:39936
	global_load_lds_dwordx4 v[224:225], off
	v_lshl_add_u64 v[224:225], s[24:25], 0, v[186:187]
	s_mov_b32 m0, s33
	s_nop 0
	global_load_lds_dwordx4 v[224:225], off
	s_waitcnt vmcnt(8)
	s_waitcnt lgkmcnt(0)
	s_setprio 1
	s_barrier
	v_mfma_f32_16x16x32_bf16 v[126:129], v[130:133], v[162:165], v[126:129]
	v_mfma_f32_16x16x32_bf16 v[122:125], v[138:141], v[162:165], v[122:125]
	v_mfma_f32_16x16x32_bf16 v[114:117], v[130:133], v[170:173], v[114:117]
	v_mfma_f32_16x16x32_bf16 v[106:109], v[138:141], v[170:173], v[106:109]
	v_mfma_f32_16x16x32_bf16 v[98:101], v[130:133], v[178:181], v[98:101]
	v_mfma_f32_16x16x32_bf16 v[90:93], v[138:141], v[178:181], v[90:93]
	v_mfma_f32_16x16x32_bf16 v[82:85], v[130:133], v[210:213], v[82:85]
	v_mfma_f32_16x16x32_bf16 v[74:77], v[138:141], v[210:213], v[74:77]
	v_mfma_f32_16x16x32_bf16 v[126:129], v[134:137], v[166:169], v[126:129]
	v_mfma_f32_16x16x32_bf16 v[122:125], v[142:145], v[166:169], v[122:125]
	v_mfma_f32_16x16x32_bf16 v[114:117], v[134:137], v[174:177], v[114:117]
	v_mfma_f32_16x16x32_bf16 v[106:109], v[142:145], v[174:177], v[106:109]
	v_mfma_f32_16x16x32_bf16 v[98:101], v[134:137], v[206:209], v[98:101]
	v_mfma_f32_16x16x32_bf16 v[90:93], v[142:145], v[206:209], v[90:93]
	v_mfma_f32_16x16x32_bf16 v[82:85], v[134:137], v[214:217], v[82:85]
	v_mfma_f32_16x16x32_bf16 v[74:77], v[142:145], v[214:217], v[74:77]
	s_setprio 0
	s_setprio 1
	v_mfma_f32_16x16x32_bf16 v[118:121], v[146:149], v[162:165], v[118:121]
	v_mfma_f32_16x16x32_bf16 v[110:113], v[154:157], v[162:165], v[110:113]
	v_mfma_f32_16x16x32_bf16 v[102:105], v[146:149], v[170:173], v[102:105]
	v_mfma_f32_16x16x32_bf16 v[94:97], v[154:157], v[170:173], v[94:97]
	v_mfma_f32_16x16x32_bf16 v[86:89], v[146:149], v[178:181], v[86:89]
	v_mfma_f32_16x16x32_bf16 v[78:81], v[154:157], v[178:181], v[78:81]
	v_mfma_f32_16x16x32_bf16 v[70:73], v[146:149], v[210:213], v[70:73]
	v_mfma_f32_16x16x32_bf16 v[66:69], v[154:157], v[210:213], v[66:69]
	v_mfma_f32_16x16x32_bf16 v[118:121], v[150:153], v[166:169], v[118:121]
	v_mfma_f32_16x16x32_bf16 v[110:113], v[158:161], v[166:169], v[110:113]
	v_mfma_f32_16x16x32_bf16 v[102:105], v[150:153], v[174:177], v[102:105]
	v_mfma_f32_16x16x32_bf16 v[94:97], v[158:161], v[174:177], v[94:97]
	v_mfma_f32_16x16x32_bf16 v[86:89], v[150:153], v[206:209], v[86:89]
	v_mfma_f32_16x16x32_bf16 v[78:81], v[158:161], v[206:209], v[78:81]
	v_mfma_f32_16x16x32_bf16 v[70:73], v[150:153], v[214:217], v[70:73]
	v_mfma_f32_16x16x32_bf16 v[66:69], v[158:161], v[214:217], v[66:69]
	s_barrier
; #define PG8_STAGE(bufoff, gbase, voff) do { _Pragma("unroll") for (int _i = 0; _i < 2; ++_i) \
;         __builtin_amdgcn_global_load_lds((const unsigned*)((const char*)(gbase) + (voff)[_i]), (PG8_LAS unsigned*)(lds + (bufoff) + ldsw + _i * 8192), 16, 0, 0); } while (0)
; #define PG8_WAIT_V(n) asm volatile("s_waitcnt vmcnt(" #n ")" ::: "memory")
; #define PG8_WAIT_L(n) asm volatile("s_waitcnt lgkmcnt(" #n ")" ::: "memory")
; #define PG8_BAR __builtin_amdgcn_s_barrier()
; #define PG8_SCHED __builtin_amdgcn_sched_barrier(0)
; template <class Epi, class Sched, bool ALIGN_EPI = true, bool SP2 = true>
; __device__ __forceinline__ void gemm_phase(PG8_LAS unsigned char* lds, const int K  , const Sched& S, const Epi& E) {
;     ...
;             PG8_LDA(At, 1, 1); PG8_STAGE(PG8_SB(1, 0), b3, voffB); PG8_STAGE(PG8_SB(1, 1), b3 + hstep, voffB); PG8_STAGE(PG8_SA(1, 0), a3, voffA);
;             PG8_WAIT_V(8); PG8_WAIT_L(0); PG8_BAR; PG8_MMA(1, 0, At, B0); PG8_MMA(1, 1, At, B1); PG8_BAR; PG8_SCHED;
	s_setprio 0
	s_add_i32 s24, s55, s29
	v_lshl_add_u64 v[198:199], v[198:199], 0, s[6:7]
	s_mov_b32 m0, s24
	ds_read_b128 v[162:165], v205 offset:49152
	ds_read_b128 v[166:169], v205 offset:50176
	ds_read_b128 v[170:173], v205 offset:51200
	ds_read_b128 v[174:177], v205 offset:52224
	ds_read_b128 v[178:181], v205 offset:53248
	ds_read_b128 v[206:209], v205 offset:54272
	ds_read_b128 v[210:213], v205 offset:55296
	ds_read_b128 v[214:217], v205 offset:56320
	global_load_lds_dwordx4 v[198:199], off
	s_add_i32 m0, s24, 0x2000
	s_add_u32 s22, s22, 0x80080
	v_lshl_add_u64 v[198:199], v[218:219], 0, s[6:7]
	s_addc_u32 s23, s23, 0
	s_add_i32 s24, s56, s29
	global_load_lds_dwordx4 v[198:199], off
	v_lshl_add_u64 v[198:199], s[22:23], 0, v[184:185]
	s_mov_b32 m0, s24
	s_nop 0
	global_load_lds_dwordx4 v[198:199], off
	v_lshl_add_u64 v[198:199], s[22:23], 0, v[188:189]
	s_add_i32 m0, s24, 0x2000
	s_nop 0
	global_load_lds_dwordx4 v[198:199], off
	v_lshl_add_u64 v[198:199], v[220:221], 0, s[6:7]
	s_mov_b32 m0, s38
	s_nop 0
	global_load_lds_dwordx4 v[198:199], off
	v_lshl_add_u64 v[198:199], v[222:223], 0, s[6:7]
	s_mov_b32 m0, s39
	s_nop 0
	global_load_lds_dwordx4 v[198:199], off
	s_add_i32 s54, s54, 2
	s_add_u32 s20, s20, 0x100
	s_addc_u32 s21, s21, 0
	s_add_u32 s52, s52, 0x100
	s_addc_u32 s53, s53, 0
	s_cmp_gt_u32 s54, 29
	s_waitcnt vmcnt(8)
	s_waitcnt lgkmcnt(0)
	s_setprio 1
	s_barrier
	v_mfma_f32_16x16x32_bf16 v[62:65], v[130:133], v[162:165], v[62:65]
	v_mfma_f32_16x16x32_bf16 v[58:61], v[138:141], v[162:165], v[58:61]
	v_mfma_f32_16x16x32_bf16 v[50:53], v[130:133], v[170:173], v[50:53]
	v_mfma_f32_16x16x32_bf16 v[42:45], v[138:141], v[170:173], v[42:45]
	v_mfma_f32_16x16x32_bf16 v[34:37], v[130:133], v[178:181], v[34:37]
	v_mfma_f32_16x16x32_bf16 v[26:29], v[138:141], v[178:181], v[26:29]
	v_mfma_f32_16x16x32_bf16 v[18:21], v[130:133], v[210:213], v[18:21]
	v_mfma_f32_16x16x32_bf16 v[10:13], v[138:141], v[210:213], v[10:13]
	v_mfma_f32_16x16x32_bf16 v[62:65], v[134:137], v[166:169], v[62:65]
	v_mfma_f32_16x16x32_bf16 v[58:61], v[142:145], v[166:169], v[58:61]
	v_mfma_f32_16x16x32_bf16 v[50:53], v[134:137], v[174:177], v[50:53]
	v_mfma_f32_16x16x32_bf16 v[42:45], v[142:145], v[174:177], v[42:45]
	v_mfma_f32_16x16x32_bf16 v[34:37], v[134:137], v[206:209], v[34:37]
	v_mfma_f32_16x16x32_bf16 v[26:29], v[142:145], v[206:209], v[26:29]
	v_mfma_f32_16x16x32_bf16 v[18:21], v[134:137], v[214:217], v[18:21]
	v_mfma_f32_16x16x32_bf16 v[10:13], v[142:145], v[214:217], v[10:13]
	s_setprio 0
	s_setprio 1
	v_mfma_f32_16x16x32_bf16 v[54:57], v[146:149], v[162:165], v[54:57]
	v_mfma_f32_16x16x32_bf16 v[46:49], v[154:157], v[162:165], v[46:49]
	v_mfma_f32_16x16x32_bf16 v[38:41], v[146:149], v[170:173], v[38:41]
	v_mfma_f32_16x16x32_bf16 v[30:33], v[154:157], v[170:173], v[30:33]
	v_mfma_f32_16x16x32_bf16 v[22:25], v[146:149], v[178:181], v[22:25]
	v_mfma_f32_16x16x32_bf16 v[14:17], v[154:157], v[178:181], v[14:17]
	v_mfma_f32_16x16x32_bf16 v[6:9], v[146:149], v[210:213], v[6:9]
	v_mfma_f32_16x16x32_bf16 v[2:5], v[154:157], v[210:213], v[2:5]
	v_mfma_f32_16x16x32_bf16 v[54:57], v[150:153], v[166:169], v[54:57]
	v_mfma_f32_16x16x32_bf16 v[46:49], v[158:161], v[166:169], v[46:49]
	v_mfma_f32_16x16x32_bf16 v[38:41], v[150:153], v[174:177], v[38:41]
	v_mfma_f32_16x16x32_bf16 v[30:33], v[158:161], v[174:177], v[30:33]
	v_mfma_f32_16x16x32_bf16 v[22:25], v[150:153], v[206:209], v[22:25]
	v_mfma_f32_16x16x32_bf16 v[14:17], v[158:161], v[206:209], v[14:17]
	v_mfma_f32_16x16x32_bf16 v[6:9], v[150:153], v[214:217], v[6:9]
	v_mfma_f32_16x16x32_bf16 v[2:5], v[158:161], v[214:217], v[2:5]
	s_barrier
	s_setprio 0
	s_cbranch_scc0 .LBB0_2296
	s_and_b64 vcc, exec, s[8:9]
	s_cbranch_vccz .LBB0_2299
	s_barrier

; #define PG8_STAGE(bufoff, gbase, voff) do { _Pragma("unroll") for (int _i = 0; _i < 2; ++_i) \
;         __builtin_amdgcn_global_load_lds((const unsigned*)((const char*)(gbase) + (voff)[_i]), (PG8_LAS unsigned*)(lds + (bufoff) + ldsw + _i * 8192), 16, 0, 0); } while (0)
; #define PG8_WAIT_V(n) asm volatile("s_waitcnt vmcnt(" #n ")" ::: "memory")
; #define PG8_WAIT_L(n) asm volatile("s_waitcnt lgkmcnt(" #n ")" ::: "memory")
; #define PG8_BAR __builtin_amdgcn_s_barrier()
; #define PG8_SCHED __builtin_amdgcn_sched_barrier(0)
;     __device__ __forceinline__ int nt(const pg8::Unit& u) const { return u.kind == 0 ? ntiles : q_nt(u.kind - 1); }
; template <class Epi, class Sched, bool ALIGN_EPI = true, bool SP2 = true>
; __device__ __forceinline__ void gemm_phase(PG8_LAS unsigned char* lds, const int K  , const Sched& S, const Epi& E) {
;     ...
;             const bool last = (t == nt - 2);
;             const char* a1 = cA + (size_t)(t + 1) * kstep;
;             const char* a2 = last ? nA : cA + (size_t)(t + 2) * kstep; const char* b2 = last ? nB : cB + (size_t)(t + 2) * kstep;
;             const char* a3 = a2 + kstep; const char* b3 = b2 + kstep;
;             if constexpr (SP2) {
;             PG8_LDB(B0, 0, 0); PG8_LDB(B1, 0, 1); PG8_SCHED; PG8_LDA(At, 0, 0); PG8_STAGE(PG8_SA(1, 1), a1 + hstep, voffA);
;             PG8_WAIT_V(8); PG8_WAIT_L(0); PG8_BAR; PG8_MMA(0, 0, At, B0); PG8_MMA(0, 1, At, B1); PG8_BAR; PG8_SCHED;
;             PG8_LDA(At, 0, 1); PG8_STAGE(PG8_SB(0, 0), b2, voffB); PG8_STAGE(PG8_SB(0, 1), b2 + hstep, voffB); PG8_STAGE(PG8_SA(0, 0), a2, voffA);
;             PG8_WAIT_V(8); PG8_WAIT_L(0); PG8_BAR; PG8_MMA(1, 0, At, B0); PG8_MMA(1, 1, At, B1); PG8_BAR; PG8_SCHED;
.LBB0_2433:
	ds_read_b128 v[146:149], v152
	ds_read_b128 v[158:161], v152 offset:1024
	ds_read_b128 v[162:165], v152 offset:2048
	ds_read_b128 v[166:169], v152 offset:3072
	ds_read_b128 v[170:173], v153
	ds_read_b128 v[174:177], v153 offset:1024
	ds_read_b128 v[178:181], v153 offset:2048
	ds_read_b128 v[182:185], v153 offset:3072
	s_add_u32 s22, s20, 0xfff80080
	s_addc_u32 s23, s21, -1
	s_cmp_eq_u32 s48, 28
	s_cselect_b32 s25, s13, s23
	s_cselect_b32 s24, s44, s22
	s_cselect_b32 s23, s11, s47
	s_cselect_b32 s22, s45, s46
	v_lshl_add_u64 v[218:219], s[20:21], 0, v[138:139]
	s_add_i32 m0, s19, 0xc000
	ds_read_b128 v[186:189], v154
	ds_read_b128 v[190:193], v154 offset:1024
	ds_read_b128 v[194:197], v154 offset:2048
	ds_read_b128 v[198:201], v154 offset:3072
	ds_read_b128 v[202:205], v154 offset:4096
	ds_read_b128 v[206:209], v154 offset:5120
	ds_read_b128 v[210:213], v154 offset:6144
	ds_read_b128 v[214:217], v154 offset:7168
	global_load_lds_dwordx4 v[218:219], off
	v_lshl_add_u64 v[218:219], s[20:21], 0, v[140:141]
	s_add_i32 m0, s19, 0xe000
	s_nop 0
	global_load_lds_dwordx4 v[218:219], off
	s_waitcnt vmcnt(8)
	s_waitcnt lgkmcnt(0)
	s_setprio 1
	s_barrier
	v_mfma_f32_16x16x32_bf16 v[126:129], v[146:149], v[186:189], v[126:129]
	v_mfma_f32_16x16x32_bf16 v[118:121], v[162:165], v[186:189], v[118:121]
	v_mfma_f32_16x16x32_bf16 v[110:113], v[146:149], v[194:197], v[110:113]
	v_mfma_f32_16x16x32_bf16 v[102:105], v[162:165], v[194:197], v[102:105]
	v_mfma_f32_16x16x32_bf16 v[94:97], v[146:149], v[202:205], v[94:97]
	v_mfma_f32_16x16x32_bf16 v[86:89], v[162:165], v[202:205], v[86:89]
	v_mfma_f32_16x16x32_bf16 v[78:81], v[146:149], v[210:213], v[78:81]
	v_mfma_f32_16x16x32_bf16 v[70:73], v[162:165], v[210:213], v[70:73]
	v_mfma_f32_16x16x32_bf16 v[126:129], v[158:161], v[190:193], v[126:129]
	v_mfma_f32_16x16x32_bf16 v[118:121], v[166:169], v[190:193], v[118:121]
	v_mfma_f32_16x16x32_bf16 v[110:113], v[158:161], v[198:201], v[110:113]
	v_mfma_f32_16x16x32_bf16 v[102:105], v[166:169], v[198:201], v[102:105]
	v_mfma_f32_16x16x32_bf16 v[94:97], v[158:161], v[206:209], v[94:97]
	v_mfma_f32_16x16x32_bf16 v[86:89], v[166:169], v[206:209], v[86:89]
	v_mfma_f32_16x16x32_bf16 v[78:81], v[158:161], v[214:217], v[78:81]
	v_mfma_f32_16x16x32_bf16 v[70:73], v[166:169], v[214:217], v[70:73]
	s_setprio 0
	s_setprio 1
	v_mfma_f32_16x16x32_bf16 v[122:125], v[170:173], v[186:189], v[122:125]
	v_mfma_f32_16x16x32_bf16 v[114:117], v[178:181], v[186:189], v[114:117]
	v_mfma_f32_16x16x32_bf16 v[106:109], v[170:173], v[194:197], v[106:109]
	v_mfma_f32_16x16x32_bf16 v[98:101], v[178:181], v[194:197], v[98:101]
	v_mfma_f32_16x16x32_bf16 v[90:93], v[170:173], v[202:205], v[90:93]
	v_mfma_f32_16x16x32_bf16 v[82:85], v[178:181], v[202:205], v[82:85]
	v_mfma_f32_16x16x32_bf16 v[74:77], v[170:173], v[210:213], v[74:77]
	v_mfma_f32_16x16x32_bf16 v[66:69], v[178:181], v[210:213], v[66:69]
	v_mfma_f32_16x16x32_bf16 v[122:125], v[174:177], v[190:193], v[122:125]
	v_mfma_f32_16x16x32_bf16 v[114:117], v[182:185], v[190:193], v[114:117]
	v_mfma_f32_16x16x32_bf16 v[106:109], v[174:177], v[198:201], v[106:109]
	v_mfma_f32_16x16x32_bf16 v[98:101], v[182:185], v[198:201], v[98:101]
	v_mfma_f32_16x16x32_bf16 v[90:93], v[174:177], v[206:209], v[90:93]
	v_mfma_f32_16x16x32_bf16 v[82:85], v[182:185], v[206:209], v[82:85]
	v_mfma_f32_16x16x32_bf16 v[74:77], v[174:177], v[214:217], v[74:77]
	v_mfma_f32_16x16x32_bf16 v[66:69], v[182:185], v[214:217], v[66:69]
	s_barrier
	s_setprio 0
	s_add_i32 s49, s39, s28
	v_lshl_add_u64 v[218:219], s[22:23], 0, v[134:135]
	s_mov_b32 m0, s49
	ds_read_b128 v[186:189], v154 offset:16384
	ds_read_b128 v[190:193], v154 offset:17408
	ds_read_b128 v[194:197], v154 offset:18432
	ds_read_b128 v[198:201], v154 offset:19456
	ds_read_b128 v[202:205], v154 offset:20480
	ds_read_b128 v[206:209], v154 offset:21504
	ds_read_b128 v[210:213], v154 offset:22528
	ds_read_b128 v[214:217], v154 offset:23552
	global_load_lds_dwordx4 v[218:219], off
	s_add_i32 m0, s49, 0x2000
	s_add_u32 s50, s22, 0x80000
	v_lshl_add_u64 v[220:221], s[22:23], 0, v[130:131]
	s_addc_u32 s51, s23, 0
	s_add_i32 s49, s40, s28
	global_load_lds_dwordx4 v[220:221], off
	v_lshl_add_u64 v[222:223], s[50:51], 0, v[134:135]
	s_mov_b32 m0, s49
	v_lshl_add_u64 v[224:225], s[24:25], 0, v[132:133]
	global_load_lds_dwordx4 v[222:223], off
	v_lshl_add_u64 v[222:223], s[50:51], 0, v[130:131]
	s_add_i32 m0, s49, 0x2000
	s_nop 0
	global_load_lds_dwordx4 v[222:223], off
	v_lshl_add_u64 v[222:223], s[24:25], 0, v[136:137]
	s_mov_b32 m0, s19
	s_nop 0
	global_load_lds_dwordx4 v[222:223], off
	s_mov_b32 m0, s31
	s_nop 0
	global_load_lds_dwordx4 v[224:225], off
	s_waitcnt vmcnt(8)
	s_waitcnt lgkmcnt(0)
	s_setprio 1
	s_barrier
; #define PG8_STAGE(bufoff, gbase, voff) do { _Pragma("unroll") for (int _i = 0; _i < 2; ++_i) \
;         __builtin_amdgcn_global_load_lds((const unsigned*)((const char*)(gbase) + (voff)[_i]), (PG8_LAS unsigned*)(lds + (bufoff) + ldsw + _i * 8192), 16, 0, 0); } while (0)
; #define PG8_WAIT_V(n) asm volatile("s_waitcnt vmcnt(" #n ")" ::: "memory")
; #define PG8_WAIT_L(n) asm volatile("s_waitcnt lgkmcnt(" #n ")" ::: "memory")
; #define PG8_BAR __builtin_amdgcn_s_barrier()
; #define PG8_SCHED __builtin_amdgcn_sched_barrier(0)
; template <class Epi, class Sched, bool ALIGN_EPI = true, bool SP2 = true>
; __device__ __forceinline__ void gemm_phase(PG8_LAS unsigned char* lds, const int K  , const Sched& S, const Epi& E) {
;     ...
;             PG8_WAIT_V(8); PG8_WAIT_L(0); PG8_BAR; PG8_MMA(1, 0, At, B0); PG8_MMA(1, 1, At, B1); PG8_BAR; PG8_SCHED;
;             PG8_LDB(B0, 1, 0); PG8_LDB(B1, 1, 1); PG8_SCHED; PG8_LDA(At, 1, 0); PG8_STAGE(PG8_SA(0, 1), a2 + hstep, voffA);
;             PG8_WAIT_V(8); PG8_WAIT_L(0); PG8_BAR; PG8_MMA(0, 0, At, B0); PG8_MMA(0, 1, At, B1); PG8_BAR; PG8_SCHED;
	v_mfma_f32_16x16x32_bf16 v[62:65], v[146:149], v[186:189], v[62:65]
	v_mfma_f32_16x16x32_bf16 v[54:57], v[162:165], v[186:189], v[54:57]
	v_mfma_f32_16x16x32_bf16 v[46:49], v[146:149], v[194:197], v[46:49]
	v_mfma_f32_16x16x32_bf16 v[38:41], v[162:165], v[194:197], v[38:41]
	v_mfma_f32_16x16x32_bf16 v[30:33], v[146:149], v[202:205], v[30:33]
	v_mfma_f32_16x16x32_bf16 v[22:25], v[162:165], v[202:205], v[22:25]
	v_mfma_f32_16x16x32_bf16 v[14:17], v[146:149], v[210:213], v[14:17]
	v_mfma_f32_16x16x32_bf16 v[6:9], v[162:165], v[210:213], v[6:9]
	v_mfma_f32_16x16x32_bf16 v[62:65], v[158:161], v[190:193], v[62:65]
	v_mfma_f32_16x16x32_bf16 v[54:57], v[166:169], v[190:193], v[54:57]
	v_mfma_f32_16x16x32_bf16 v[46:49], v[158:161], v[198:201], v[46:49]
	v_mfma_f32_16x16x32_bf16 v[38:41], v[166:169], v[198:201], v[38:41]
	v_mfma_f32_16x16x32_bf16 v[30:33], v[158:161], v[206:209], v[30:33]
	v_mfma_f32_16x16x32_bf16 v[22:25], v[166:169], v[206:209], v[22:25]
	v_mfma_f32_16x16x32_bf16 v[14:17], v[158:161], v[214:217], v[14:17]
	v_mfma_f32_16x16x32_bf16 v[6:9], v[166:169], v[214:217], v[6:9]
	s_setprio 0
	s_setprio 1
	v_mfma_f32_16x16x32_bf16 v[58:61], v[170:173], v[186:189], v[58:61]
	v_mfma_f32_16x16x32_bf16 v[50:53], v[178:181], v[186:189], v[50:53]
	v_mfma_f32_16x16x32_bf16 v[42:45], v[170:173], v[194:197], v[42:45]
	v_mfma_f32_16x16x32_bf16 v[34:37], v[178:181], v[194:197], v[34:37]
	v_mfma_f32_16x16x32_bf16 v[26:29], v[170:173], v[202:205], v[26:29]
	v_mfma_f32_16x16x32_bf16 v[18:21], v[178:181], v[202:205], v[18:21]
	v_mfma_f32_16x16x32_bf16 v[10:13], v[170:173], v[210:213], v[10:13]
	v_mfma_f32_16x16x32_bf16 v[2:5], v[178:181], v[210:213], v[2:5]
	v_mfma_f32_16x16x32_bf16 v[58:61], v[174:177], v[190:193], v[58:61]
	v_mfma_f32_16x16x32_bf16 v[50:53], v[182:185], v[190:193], v[50:53]
	v_mfma_f32_16x16x32_bf16 v[42:45], v[174:177], v[198:201], v[42:45]
	v_mfma_f32_16x16x32_bf16 v[34:37], v[182:185], v[198:201], v[34:37]
	v_mfma_f32_16x16x32_bf16 v[26:29], v[174:177], v[206:209], v[26:29]
	v_mfma_f32_16x16x32_bf16 v[18:21], v[182:185], v[206:209], v[18:21]
	v_mfma_f32_16x16x32_bf16 v[10:13], v[174:177], v[214:217], v[10:13]
	v_mfma_f32_16x16x32_bf16 v[2:5], v[182:185], v[214:217], v[2:5]
	s_barrier
	s_setprio 0
	s_add_i32 s49, 0, 0x18000
	v_add_u32_e32 v157, s49, v150
	s_add_i32 s50, 0, 0x1c000
	ds_read_b128 v[146:149], v157
	ds_read_b128 v[158:161], v157 offset:1024
	ds_read_b128 v[162:165], v157 offset:2048
	ds_read_b128 v[166:169], v157 offset:3072
	v_add_u32_e32 v157, s50, v150
	ds_read_b128 v[170:173], v157
	ds_read_b128 v[174:177], v157 offset:1024
	ds_read_b128 v[178:181], v157 offset:2048
	ds_read_b128 v[182:185], v157 offset:3072
	s_add_u32 s24, s24, 0x80000
	s_addc_u32 s25, s25, 0
	s_mov_b32 m0, s33
	v_lshl_add_u64 v[226:227], s[24:25], 0, v[136:137]
	ds_read_b128 v[186:189], v154 offset:32768
	ds_read_b128 v[190:193], v154 offset:33792
	ds_read_b128 v[194:197], v154 offset:34816
	ds_read_b128 v[198:201], v154 offset:35840
	ds_read_b128 v[202:205], v154 offset:36864
	ds_read_b128 v[206:209], v154 offset:37888
	ds_read_b128 v[210:213], v154 offset:38912
	ds_read_b128 v[214:217], v154 offset:39936
	global_load_lds_dwordx4 v[226:227], off
	v_lshl_add_u64 v[226:227], s[24:25], 0, v[132:133]
	s_mov_b32 m0, s34
	s_nop 0
	global_load_lds_dwordx4 v[226:227], off
	s_waitcnt vmcnt(8)
	s_waitcnt lgkmcnt(0)
	s_setprio 1
	s_barrier
	v_mfma_f32_16x16x32_bf16 v[126:129], v[146:149], v[186:189], v[126:129]
	v_mfma_f32_16x16x32_bf16 v[118:121], v[162:165], v[186:189], v[118:121]
	v_mfma_f32_16x16x32_bf16 v[110:113], v[146:149], v[194:197], v[110:113]
	v_mfma_f32_16x16x32_bf16 v[102:105], v[162:165], v[194:197], v[102:105]
	v_mfma_f32_16x16x32_bf16 v[94:97], v[146:149], v[202:205], v[94:97]
	v_mfma_f32_16x16x32_bf16 v[86:89], v[162:165], v[202:205], v[86:89]
	v_mfma_f32_16x16x32_bf16 v[78:81], v[146:149], v[210:213], v[78:81]
	v_mfma_f32_16x16x32_bf16 v[70:73], v[162:165], v[210:213], v[70:73]
	v_mfma_f32_16x16x32_bf16 v[126:129], v[158:161], v[190:193], v[126:129]
	v_mfma_f32_16x16x32_bf16 v[118:121], v[166:169], v[190:193], v[118:121]
	v_mfma_f32_16x16x32_bf16 v[110:113], v[158:161], v[198:201], v[110:113]
	v_mfma_f32_16x16x32_bf16 v[102:105], v[166:169], v[198:201], v[102:105]
	v_mfma_f32_16x16x32_bf16 v[94:97], v[158:161], v[206:209], v[94:97]
	v_mfma_f32_16x16x32_bf16 v[86:89], v[166:169], v[206:209], v[86:89]
	v_mfma_f32_16x16x32_bf16 v[78:81], v[158:161], v[214:217], v[78:81]
	v_mfma_f32_16x16x32_bf16 v[70:73], v[166:169], v[214:217], v[70:73]
	s_setprio 0
	s_setprio 1
	v_mfma_f32_16x16x32_bf16 v[122:125], v[170:173], v[186:189], v[122:125]
	v_mfma_f32_16x16x32_bf16 v[114:117], v[178:181], v[186:189], v[114:117]
	v_mfma_f32_16x16x32_bf16 v[106:109], v[170:173], v[194:197], v[106:109]
	v_mfma_f32_16x16x32_bf16 v[98:101], v[178:181], v[194:197], v[98:101]
	v_mfma_f32_16x16x32_bf16 v[90:93], v[170:173], v[202:205], v[90:93]
	v_mfma_f32_16x16x32_bf16 v[82:85], v[178:181], v[202:205], v[82:85]
	v_mfma_f32_16x16x32_bf16 v[74:77], v[170:173], v[210:213], v[74:77]
	v_mfma_f32_16x16x32_bf16 v[66:69], v[178:181], v[210:213], v[66:69]
	v_mfma_f32_16x16x32_bf16 v[122:125], v[174:177], v[190:193], v[122:125]
	v_mfma_f32_16x16x32_bf16 v[114:117], v[182:185], v[190:193], v[114:117]
	v_mfma_f32_16x16x32_bf16 v[106:109], v[174:177], v[198:201], v[106:109]
	v_mfma_f32_16x16x32_bf16 v[98:101], v[182:185], v[198:201], v[98:101]
	v_mfma_f32_16x16x32_bf16 v[90:93], v[174:177], v[206:209], v[90:93]
	v_mfma_f32_16x16x32_bf16 v[82:85], v[182:185], v[206:209], v[82:85]
	v_mfma_f32_16x16x32_bf16 v[74:77], v[174:177], v[214:217], v[74:77]
	v_mfma_f32_16x16x32_bf16 v[66:69], v[182:185], v[214:217], v[66:69]
	s_barrier
; #define PG8_STAGE(bufoff, gbase, voff) do { _Pragma("unroll") for (int _i = 0; _i < 2; ++_i) \
;         __builtin_amdgcn_global_load_lds((const unsigned*)((const char*)(gbase) + (voff)[_i]), (PG8_LAS unsigned*)(lds + (bufoff) + ldsw + _i * 8192), 16, 0, 0); } while (0)
; #define PG8_WAIT_V(n) asm volatile("s_waitcnt vmcnt(" #n ")" ::: "memory")
; #define PG8_WAIT_L(n) asm volatile("s_waitcnt lgkmcnt(" #n ")" ::: "memory")
; #define PG8_BAR __builtin_amdgcn_s_barrier()
; #define PG8_SCHED __builtin_amdgcn_sched_barrier(0)
; template <class Epi, class Sched, bool ALIGN_EPI = true, bool SP2 = true>
; __device__ __forceinline__ void gemm_phase(PG8_LAS unsigned char* lds, const int K  , const Sched& S, const Epi& E) {
;     ...
;             PG8_LDA(At, 1, 1); PG8_STAGE(PG8_SB(1, 0), b3, voffB); PG8_STAGE(PG8_SB(1, 1), b3 + hstep, voffB); PG8_STAGE(PG8_SA(1, 0), a3, voffA);
;             PG8_WAIT_V(8); PG8_WAIT_L(0); PG8_BAR; PG8_MMA(1, 0, At, B0); PG8_MMA(1, 1, At, B1); PG8_BAR; PG8_SCHED;
	s_setprio 0
	s_add_i32 s24, s49, s28
	v_lshl_add_u64 v[218:219], v[218:219], 0, s[6:7]
	s_mov_b32 m0, s24
	ds_read_b128 v[186:189], v154 offset:49152
	ds_read_b128 v[190:193], v154 offset:50176
	ds_read_b128 v[194:197], v154 offset:51200
	ds_read_b128 v[198:201], v154 offset:52224
	ds_read_b128 v[202:205], v154 offset:53248
	ds_read_b128 v[206:209], v154 offset:54272
	ds_read_b128 v[210:213], v154 offset:55296
	ds_read_b128 v[214:217], v154 offset:56320
	global_load_lds_dwordx4 v[218:219], off
	s_add_i32 m0, s24, 0x2000
	s_add_u32 s22, s22, 0x80080
	v_lshl_add_u64 v[218:219], v[220:221], 0, s[6:7]
	s_addc_u32 s23, s23, 0
	s_add_i32 s24, s50, s28
	global_load_lds_dwordx4 v[218:219], off
	v_lshl_add_u64 v[218:219], s[22:23], 0, v[134:135]
	s_mov_b32 m0, s24
	s_nop 0
	global_load_lds_dwordx4 v[218:219], off
	v_lshl_add_u64 v[218:219], s[22:23], 0, v[130:131]
	s_add_i32 m0, s24, 0x2000
	s_nop 0
	global_load_lds_dwordx4 v[218:219], off
	v_lshl_add_u64 v[218:219], v[222:223], 0, s[6:7]
	s_mov_b32 m0, s36
	s_nop 0
	global_load_lds_dwordx4 v[218:219], off
	v_lshl_add_u64 v[218:219], v[224:225], 0, s[6:7]
	s_mov_b32 m0, s37
	s_nop 0
	global_load_lds_dwordx4 v[218:219], off
	s_add_i32 s48, s48, 2
	s_add_u32 s20, s20, 0x100
	s_addc_u32 s21, s21, 0
	s_add_u32 s46, s46, 0x100
	s_addc_u32 s47, s47, 0
	s_cmp_gt_u32 s48, 29
	s_waitcnt vmcnt(8)
	s_waitcnt lgkmcnt(0)
	s_setprio 1
	s_barrier
	v_mfma_f32_16x16x32_bf16 v[62:65], v[146:149], v[186:189], v[62:65]
	v_mfma_f32_16x16x32_bf16 v[54:57], v[162:165], v[186:189], v[54:57]
	v_mfma_f32_16x16x32_bf16 v[46:49], v[146:149], v[194:197], v[46:49]
	v_mfma_f32_16x16x32_bf16 v[38:41], v[162:165], v[194:197], v[38:41]
	v_mfma_f32_16x16x32_bf16 v[30:33], v[146:149], v[202:205], v[30:33]
	v_mfma_f32_16x16x32_bf16 v[22:25], v[162:165], v[202:205], v[22:25]
	v_mfma_f32_16x16x32_bf16 v[14:17], v[146:149], v[210:213], v[14:17]
	v_mfma_f32_16x16x32_bf16 v[6:9], v[162:165], v[210:213], v[6:9]
	v_mfma_f32_16x16x32_bf16 v[62:65], v[158:161], v[190:193], v[62:65]
	v_mfma_f32_16x16x32_bf16 v[54:57], v[166:169], v[190:193], v[54:57]
	v_mfma_f32_16x16x32_bf16 v[46:49], v[158:161], v[198:201], v[46:49]
	v_mfma_f32_16x16x32_bf16 v[38:41], v[166:169], v[198:201], v[38:41]
	v_mfma_f32_16x16x32_bf16 v[30:33], v[158:161], v[206:209], v[30:33]
	v_mfma_f32_16x16x32_bf16 v[22:25], v[166:169], v[206:209], v[22:25]
	v_mfma_f32_16x16x32_bf16 v[14:17], v[158:161], v[214:217], v[14:17]
	v_mfma_f32_16x16x32_bf16 v[6:9], v[166:169], v[214:217], v[6:9]
	s_setprio 0
	s_setprio 1
	v_mfma_f32_16x16x32_bf16 v[58:61], v[170:173], v[186:189], v[58:61]
	v_mfma_f32_16x16x32_bf16 v[50:53], v[178:181], v[186:189], v[50:53]
	v_mfma_f32_16x16x32_bf16 v[42:45], v[170:173], v[194:197], v[42:45]
	v_mfma_f32_16x16x32_bf16 v[34:37], v[178:181], v[194:197], v[34:37]
	v_mfma_f32_16x16x32_bf16 v[26:29], v[170:173], v[202:205], v[26:29]
	v_mfma_f32_16x16x32_bf16 v[18:21], v[178:181], v[202:205], v[18:21]
	v_mfma_f32_16x16x32_bf16 v[10:13], v[170:173], v[210:213], v[10:13]
	v_mfma_f32_16x16x32_bf16 v[2:5], v[178:181], v[210:213], v[2:5]
	v_mfma_f32_16x16x32_bf16 v[58:61], v[174:177], v[190:193], v[58:61]
	v_mfma_f32_16x16x32_bf16 v[50:53], v[182:185], v[190:193], v[50:53]
	v_mfma_f32_16x16x32_bf16 v[42:45], v[174:177], v[198:201], v[42:45]
	v_mfma_f32_16x16x32_bf16 v[34:37], v[182:185], v[198:201], v[34:37]
	v_mfma_f32_16x16x32_bf16 v[26:29], v[174:177], v[206:209], v[26:29]
	v_mfma_f32_16x16x32_bf16 v[18:21], v[182:185], v[206:209], v[18:21]
	v_mfma_f32_16x16x32_bf16 v[10:13], v[174:177], v[214:217], v[10:13]
	v_mfma_f32_16x16x32_bf16 v[2:5], v[182:185], v[214:217], v[2:5]
	s_barrier
	s_setprio 0
	s_cbranch_scc0 .LBB0_2433
	s_and_b64 vcc, exec, s[8:9]
	s_cbranch_vccz .LBB0_2436
	s_barrier

; #define PG8_STAGE(bufoff, gbase, voff) do { _Pragma("unroll") for (int _i = 0; _i < 2; ++_i) \
;         __builtin_amdgcn_global_load_lds((const unsigned*)((const char*)(gbase) + (voff)[_i]), (PG8_LAS unsigned*)(lds + (bufoff) + ldsw + _i * 8192), 16, 0, 0); } while (0)
; #define PG8_WAIT_V(n) asm volatile("s_waitcnt vmcnt(" #n ")" ::: "memory")
; #define PG8_WAIT_L(n) asm volatile("s_waitcnt lgkmcnt(" #n ")" ::: "memory")
; #define PG8_BAR __builtin_amdgcn_s_barrier()
; #define PG8_SCHED __builtin_amdgcn_sched_barrier(0)
; template <class Epi, class Sched, bool ALIGN_EPI = true, bool SP2 = true>
; __device__ __forceinline__ void gemm_phase(PG8_LAS unsigned char* lds, const int K  , const Sched& S, const Epi& E) {
;     ...
;             PG8_LDB(B0, 0, 0); PG8_LDB(B1, 0, 1); PG8_SCHED; PG8_LDA(At, 0, 0); PG8_STAGE(PG8_SA(1, 1), a1 + hstep, voffA);
;             PG8_WAIT_V(8); PG8_WAIT_L(0); PG8_BAR; PG8_MMA(0, 0, At, B0); PG8_MMA(0, 1, At, B1); PG8_BAR; PG8_SCHED;
;             PG8_LDA(At, 0, 1); PG8_STAGE(PG8_SB(0, 0), b2, voffB); PG8_STAGE(PG8_SB(0, 1), b2 + hstep, voffB); PG8_STAGE(PG8_SA(0, 0), a2, voffA);
;             PG8_WAIT_V(8); PG8_WAIT_L(0); PG8_BAR; PG8_MMA(1, 0, At, B0); PG8_MMA(1, 1, At, B1); PG8_BAR; PG8_SCHED;
.LBB0_2516:
	ds_read_b128 v[16:19], v206
	ds_read_b128 v[20:23], v206 offset:1024
	ds_read_b128 v[24:27], v206 offset:2048
	ds_read_b128 v[28:31], v206 offset:3072
	ds_read_b128 v[0:3], v207
	ds_read_b128 v[4:7], v207 offset:1024
	ds_read_b128 v[8:11], v207 offset:2048
	ds_read_b128 v[12:15], v207 offset:3072
	s_add_u32 s18, s16, 0xfff50080
	s_addc_u32 s19, s17, -1
	s_cmp_eq_u32 s57, 40
	s_cselect_b32 s21, s7, s19
	s_cselect_b32 s20, s6, s18
	s_cselect_b32 s19, s15, s56
	s_cselect_b32 s18, s14, s55
	v_lshl_add_u64 v[200:201], s[16:17], 0, v[176:177]
	s_add_i32 m0, s25, 0xc000
	ds_read_b128 v[160:163], v208
	ds_read_b128 v[164:167], v208 offset:1024
	ds_read_b128 v[184:187], v208 offset:2048
	ds_read_b128 v[188:191], v208 offset:3072
	ds_read_b128 v[192:195], v208 offset:4096
	ds_read_b128 v[196:199], v208 offset:5120
	ds_read_b128 v[210:213], v208 offset:6144
	ds_read_b128 v[214:217], v208 offset:7168
	global_load_lds_dwordx4 v[200:201], off
	v_lshl_add_u64 v[200:201], s[16:17], 0, v[178:179]
	s_add_i32 m0, s25, 0xe000
	s_nop 0
	global_load_lds_dwordx4 v[200:201], off
	s_waitcnt vmcnt(8)
	s_waitcnt lgkmcnt(0)
	s_setprio 1
	s_barrier
	v_mfma_scale_f32_16x16x128_f8f6f4 v[156:159], v[16:23], v[160:167], v[156:159], v202, v202 op_sel_hi:[0,0,0]
	v_mfma_scale_f32_16x16x128_f8f6f4 v[152:155], v[24:31], v[160:167], v[152:155], v202, v202 op_sel_hi:[0,0,0]
	v_mfma_scale_f32_16x16x128_f8f6f4 v[140:143], v[16:23], v[184:191], v[140:143], v202, v202 op_sel_hi:[0,0,0]
	v_mfma_scale_f32_16x16x128_f8f6f4 v[136:139], v[24:31], v[184:191], v[136:139], v202, v202 op_sel_hi:[0,0,0]
	v_mfma_scale_f32_16x16x128_f8f6f4 v[124:127], v[16:23], v[192:199], v[124:127], v202, v202 op_sel_hi:[0,0,0]
	v_mfma_scale_f32_16x16x128_f8f6f4 v[120:123], v[24:31], v[192:199], v[120:123], v202, v202 op_sel_hi:[0,0,0]
	v_mfma_scale_f32_16x16x128_f8f6f4 v[108:111], v[16:23], v[210:217], v[108:111], v202, v202 op_sel_hi:[0,0,0]
	v_mfma_scale_f32_16x16x128_f8f6f4 v[104:107], v[24:31], v[210:217], v[104:107], v202, v202 op_sel_hi:[0,0,0]
	s_setprio 0
	s_setprio 1
	v_mfma_scale_f32_16x16x128_f8f6f4 v[148:151], v[0:7], v[160:167], v[148:151], v202, v202 op_sel_hi:[0,0,0]
	v_mfma_scale_f32_16x16x128_f8f6f4 v[144:147], v[8:15], v[160:167], v[144:147], v202, v202 op_sel_hi:[0,0,0]
	v_mfma_scale_f32_16x16x128_f8f6f4 v[132:135], v[0:7], v[184:191], v[132:135], v202, v202 op_sel_hi:[0,0,0]
	v_mfma_scale_f32_16x16x128_f8f6f4 v[128:131], v[8:15], v[184:191], v[128:131], v202, v202 op_sel_hi:[0,0,0]
	v_mfma_scale_f32_16x16x128_f8f6f4 v[116:119], v[0:7], v[192:199], v[116:119], v202, v202 op_sel_hi:[0,0,0]
	v_mfma_scale_f32_16x16x128_f8f6f4 v[112:115], v[8:15], v[192:199], v[112:115], v202, v202 op_sel_hi:[0,0,0]
	v_mfma_scale_f32_16x16x128_f8f6f4 v[100:103], v[0:7], v[210:217], v[100:103], v202, v202 op_sel_hi:[0,0,0]
	v_mfma_scale_f32_16x16x128_f8f6f4 v[96:99], v[8:15], v[210:217], v[96:99], v202, v202 op_sel_hi:[0,0,0]
	s_barrier
	s_setprio 0
	s_add_i32 s58, s38, s24
	v_lshl_add_u64 v[160:161], s[18:19], 0, v[170:171]
	s_mov_b32 m0, s58
	ds_read_b128 v[184:187], v208 offset:16384
	ds_read_b128 v[188:191], v208 offset:17408
	ds_read_b128 v[192:195], v208 offset:18432
	ds_read_b128 v[196:199], v208 offset:19456
	ds_read_b128 v[210:213], v208 offset:20480
	ds_read_b128 v[214:217], v208 offset:21504
	ds_read_b128 v[218:221], v208 offset:22528
	ds_read_b128 v[222:225], v208 offset:23552
	global_load_lds_dwordx4 v[160:161], off
	s_add_i32 m0, s58, 0x2000
	s_add_u32 s58, s18, 0xb0000
	v_lshl_add_u64 v[162:163], s[18:19], 0, v[174:175]
	s_addc_u32 s59, s19, 0
	s_add_i32 s60, s39, s24
	global_load_lds_dwordx4 v[162:163], off
	v_lshl_add_u64 v[164:165], s[58:59], 0, v[170:171]
	s_mov_b32 m0, s60
	v_lshl_add_u64 v[166:167], s[20:21], 0, v[172:173]
	global_load_lds_dwordx4 v[164:165], off
	v_lshl_add_u64 v[164:165], s[58:59], 0, v[174:175]
	s_add_i32 m0, s60, 0x2000
	s_nop 0
	global_load_lds_dwordx4 v[164:165], off
	v_lshl_add_u64 v[164:165], s[20:21], 0, v[168:169]
	s_mov_b32 m0, s25
	s_nop 0
	global_load_lds_dwordx4 v[164:165], off
	s_mov_b32 m0, s26
	s_nop 0
	global_load_lds_dwordx4 v[166:167], off
	s_waitcnt vmcnt(8)
	s_waitcnt lgkmcnt(0)
	s_setprio 1
	s_barrier
	v_mfma_scale_f32_16x16x128_f8f6f4 v[92:95], v[16:23], v[184:191], v[92:95], v202, v202 op_sel_hi:[0,0,0]
	v_mfma_scale_f32_16x16x128_f8f6f4 v[88:91], v[24:31], v[184:191], v[88:91], v202, v202 op_sel_hi:[0,0,0]
	v_mfma_scale_f32_16x16x128_f8f6f4 v[76:79], v[16:23], v[192:199], v[76:79], v202, v202 op_sel_hi:[0,0,0]
	v_mfma_scale_f32_16x16x128_f8f6f4 v[72:75], v[24:31], v[192:199], v[72:75], v202, v202 op_sel_hi:[0,0,0]
	v_mfma_scale_f32_16x16x128_f8f6f4 v[60:63], v[16:23], v[210:217], v[60:63], v202, v202 op_sel_hi:[0,0,0]
	v_mfma_scale_f32_16x16x128_f8f6f4 v[56:59], v[24:31], v[210:217], v[56:59], v202, v202 op_sel_hi:[0,0,0]
	v_mfma_scale_f32_16x16x128_f8f6f4 v[44:47], v[16:23], v[218:225], v[44:47], v202, v202 op_sel_hi:[0,0,0]
	v_mfma_scale_f32_16x16x128_f8f6f4 v[40:43], v[24:31], v[218:225], v[40:43], v202, v202 op_sel_hi:[0,0,0]
	s_setprio 0
	s_setprio 1
	v_mfma_scale_f32_16x16x128_f8f6f4 v[84:87], v[0:7], v[184:191], v[84:87], v202, v202 op_sel_hi:[0,0,0]
	v_mfma_scale_f32_16x16x128_f8f6f4 v[80:83], v[8:15], v[184:191], v[80:83], v202, v202 op_sel_hi:[0,0,0]
	v_mfma_scale_f32_16x16x128_f8f6f4 v[68:71], v[0:7], v[192:199], v[68:71], v202, v202 op_sel_hi:[0,0,0]
	v_mfma_scale_f32_16x16x128_f8f6f4 v[64:67], v[8:15], v[192:199], v[64:67], v202, v202 op_sel_hi:[0,0,0]
	v_mfma_scale_f32_16x16x128_f8f6f4 v[52:55], v[0:7], v[210:217], v[52:55], v202, v202 op_sel_hi:[0,0,0]
	v_mfma_scale_f32_16x16x128_f8f6f4 v[48:51], v[8:15], v[210:217], v[48:51], v202, v202 op_sel_hi:[0,0,0]
	v_mfma_scale_f32_16x16x128_f8f6f4 v[36:39], v[0:7], v[218:225], v[36:39], v202, v202 op_sel_hi:[0,0,0]
	v_mfma_scale_f32_16x16x128_f8f6f4 v[32:35], v[8:15], v[218:225], v[32:35], v202, v202 op_sel_hi:[0,0,0]
	s_barrier
; #define PG8_STAGE(bufoff, gbase, voff) do { _Pragma("unroll") for (int _i = 0; _i < 2; ++_i) \
;         __builtin_amdgcn_global_load_lds((const unsigned*)((const char*)(gbase) + (voff)[_i]), (PG8_LAS unsigned*)(lds + (bufoff) + ldsw + _i * 8192), 16, 0, 0); } while (0)
; #define PG8_WAIT_V(n) asm volatile("s_waitcnt vmcnt(" #n ")" ::: "memory")
; #define PG8_WAIT_L(n) asm volatile("s_waitcnt lgkmcnt(" #n ")" ::: "memory")
; #define PG8_BAR __builtin_amdgcn_s_barrier()
; #define PG8_SCHED __builtin_amdgcn_sched_barrier(0)
; template <class Epi, class Sched, bool ALIGN_EPI = true, bool SP2 = true>
; __device__ __forceinline__ void gemm_phase(PG8_LAS unsigned char* lds, const int K  , const Sched& S, const Epi& E) {
;     ...
;             PG8_LDB(B0, 1, 0); PG8_LDB(B1, 1, 1); PG8_SCHED; PG8_LDA(At, 1, 0); PG8_STAGE(PG8_SA(0, 1), a2 + hstep, voffA);
;             PG8_WAIT_V(8); PG8_WAIT_L(0); PG8_BAR; PG8_MMA(0, 0, At, B0); PG8_MMA(0, 1, At, B1); PG8_BAR; PG8_SCHED;
;             PG8_LDA(At, 1, 1); PG8_STAGE(PG8_SB(1, 0), b3, voffB); PG8_STAGE(PG8_SB(1, 1), b3 + hstep, voffB); PG8_STAGE(PG8_SA(1, 0), a3, voffA);
;             PG8_WAIT_V(8); PG8_WAIT_L(0); PG8_BAR; PG8_MMA(1, 0, At, B0); PG8_MMA(1, 1, At, B1); PG8_BAR; PG8_SCHED;
;     ...
;         if constexpr (Epi::FP8) asm volatile("s_nop 15\n\ts_nop 15\n\ts_nop 15\n\ts_nop 15\n\ts_nop 15" ::: "memory");
	s_setprio 0
	s_add_i32 s58, 0, 0x18000
	s_add_i32 s59, 0, 0x1c000
	v_add_u32_e32 v12, s58, v204
	v_add_u32_e32 v28, s59, v204
	ds_read_b128 v[0:3], v12
	ds_read_b128 v[4:7], v12 offset:1024
	ds_read_b128 v[8:11], v12 offset:2048
	ds_read_b128 v[12:15], v12 offset:3072
	ds_read_b128 v[16:19], v28
	ds_read_b128 v[20:23], v28 offset:1024
	ds_read_b128 v[24:27], v28 offset:2048
	ds_read_b128 v[28:31], v28 offset:3072
	s_add_u32 s20, s20, 0xb0000
	s_addc_u32 s21, s21, 0
	s_mov_b32 m0, s27
	v_lshl_add_u64 v[200:201], s[20:21], 0, v[168:169]
	ds_read_b128 v[184:187], v208 offset:32768
	ds_read_b128 v[188:191], v208 offset:33792
	ds_read_b128 v[192:195], v208 offset:34816
	ds_read_b128 v[196:199], v208 offset:35840
	ds_read_b128 v[210:213], v208 offset:36864
	ds_read_b128 v[214:217], v208 offset:37888
	ds_read_b128 v[218:221], v208 offset:38912
	ds_read_b128 v[222:225], v208 offset:39936
	global_load_lds_dwordx4 v[200:201], off
	v_lshl_add_u64 v[200:201], s[20:21], 0, v[172:173]
	s_mov_b32 m0, s28
	s_nop 0
	global_load_lds_dwordx4 v[200:201], off
	s_waitcnt vmcnt(8)
	s_waitcnt lgkmcnt(0)
	s_setprio 1
	s_barrier
	v_mfma_scale_f32_16x16x128_f8f6f4 v[156:159], v[0:7], v[184:191], v[156:159], v202, v202 op_sel_hi:[0,0,0]
	v_mfma_scale_f32_16x16x128_f8f6f4 v[152:155], v[8:15], v[184:191], v[152:155], v202, v202 op_sel_hi:[0,0,0]
	v_mfma_scale_f32_16x16x128_f8f6f4 v[140:143], v[0:7], v[192:199], v[140:143], v202, v202 op_sel_hi:[0,0,0]
	v_mfma_scale_f32_16x16x128_f8f6f4 v[136:139], v[8:15], v[192:199], v[136:139], v202, v202 op_sel_hi:[0,0,0]
	v_mfma_scale_f32_16x16x128_f8f6f4 v[124:127], v[0:7], v[210:217], v[124:127], v202, v202 op_sel_hi:[0,0,0]
	v_mfma_scale_f32_16x16x128_f8f6f4 v[120:123], v[8:15], v[210:217], v[120:123], v202, v202 op_sel_hi:[0,0,0]
	v_mfma_scale_f32_16x16x128_f8f6f4 v[108:111], v[0:7], v[218:225], v[108:111], v202, v202 op_sel_hi:[0,0,0]
	v_mfma_scale_f32_16x16x128_f8f6f4 v[104:107], v[8:15], v[218:225], v[104:107], v202, v202 op_sel_hi:[0,0,0]
	s_setprio 0
	s_setprio 1
	v_mfma_scale_f32_16x16x128_f8f6f4 v[148:151], v[16:23], v[184:191], v[148:151], v202, v202 op_sel_hi:[0,0,0]
	v_mfma_scale_f32_16x16x128_f8f6f4 v[144:147], v[24:31], v[184:191], v[144:147], v202, v202 op_sel_hi:[0,0,0]
	v_mfma_scale_f32_16x16x128_f8f6f4 v[132:135], v[16:23], v[192:199], v[132:135], v202, v202 op_sel_hi:[0,0,0]
	v_mfma_scale_f32_16x16x128_f8f6f4 v[128:131], v[24:31], v[192:199], v[128:131], v202, v202 op_sel_hi:[0,0,0]
	v_mfma_scale_f32_16x16x128_f8f6f4 v[116:119], v[16:23], v[210:217], v[116:119], v202, v202 op_sel_hi:[0,0,0]
	v_mfma_scale_f32_16x16x128_f8f6f4 v[112:115], v[24:31], v[210:217], v[112:115], v202, v202 op_sel_hi:[0,0,0]
	v_mfma_scale_f32_16x16x128_f8f6f4 v[100:103], v[16:23], v[218:225], v[100:103], v202, v202 op_sel_hi:[0,0,0]
	v_mfma_scale_f32_16x16x128_f8f6f4 v[96:99], v[24:31], v[218:225], v[96:99], v202, v202 op_sel_hi:[0,0,0]
	s_barrier
	s_setprio 0
	s_add_i32 s20, s58, s24
	v_lshl_add_u64 v[160:161], v[160:161], 0, s[8:9]
	s_mov_b32 m0, s20
	ds_read_b128 v[184:187], v208 offset:49152
	ds_read_b128 v[188:191], v208 offset:50176
	ds_read_b128 v[192:195], v208 offset:51200
	ds_read_b128 v[196:199], v208 offset:52224
	ds_read_b128 v[210:213], v208 offset:53248
	ds_read_b128 v[214:217], v208 offset:54272
	ds_read_b128 v[218:221], v208 offset:55296
	ds_read_b128 v[222:225], v208 offset:56320
	global_load_lds_dwordx4 v[160:161], off
	s_add_i32 m0, s20, 0x2000
	s_add_u32 s18, s18, 0xb0080
	v_lshl_add_u64 v[160:161], v[162:163], 0, s[8:9]
	s_addc_u32 s19, s19, 0
	s_add_i32 s20, s59, s24
	global_load_lds_dwordx4 v[160:161], off
	v_lshl_add_u64 v[160:161], s[18:19], 0, v[170:171]
	s_mov_b32 m0, s20
	s_nop 0
	global_load_lds_dwordx4 v[160:161], off
	v_lshl_add_u64 v[160:161], s[18:19], 0, v[174:175]
	s_add_i32 m0, s20, 0x2000
	s_nop 0
	global_load_lds_dwordx4 v[160:161], off
	v_lshl_add_u64 v[160:161], v[164:165], 0, s[8:9]
	s_mov_b32 m0, s35
	s_nop 0
	global_load_lds_dwordx4 v[160:161], off
	v_lshl_add_u64 v[160:161], v[166:167], 0, s[8:9]
	s_mov_b32 m0, s36
	s_nop 0
	global_load_lds_dwordx4 v[160:161], off
	s_add_i32 s57, s57, 2
	s_add_u32 s16, s16, 0x100
	s_addc_u32 s17, s17, 0
	s_add_u32 s55, s55, 0x100
	s_addc_u32 s56, s56, 0
	s_cmp_gt_u32 s57, 41
	s_waitcnt vmcnt(8)
	s_waitcnt lgkmcnt(0)
	s_setprio 1
	s_barrier
	v_mfma_scale_f32_16x16x128_f8f6f4 v[92:95], v[0:7], v[184:191], v[92:95], v202, v202 op_sel_hi:[0,0,0]
	v_mfma_scale_f32_16x16x128_f8f6f4 v[88:91], v[8:15], v[184:191], v[88:91], v202, v202 op_sel_hi:[0,0,0]
	v_mfma_scale_f32_16x16x128_f8f6f4 v[76:79], v[0:7], v[192:199], v[76:79], v202, v202 op_sel_hi:[0,0,0]
	v_mfma_scale_f32_16x16x128_f8f6f4 v[72:75], v[8:15], v[192:199], v[72:75], v202, v202 op_sel_hi:[0,0,0]
	v_mfma_scale_f32_16x16x128_f8f6f4 v[60:63], v[0:7], v[210:217], v[60:63], v202, v202 op_sel_hi:[0,0,0]
	v_mfma_scale_f32_16x16x128_f8f6f4 v[56:59], v[8:15], v[210:217], v[56:59], v202, v202 op_sel_hi:[0,0,0]
	v_mfma_scale_f32_16x16x128_f8f6f4 v[44:47], v[0:7], v[218:225], v[44:47], v202, v202 op_sel_hi:[0,0,0]
	v_mfma_scale_f32_16x16x128_f8f6f4 v[40:43], v[8:15], v[218:225], v[40:43], v202, v202 op_sel_hi:[0,0,0]
	s_setprio 0
	s_setprio 1
	v_mfma_scale_f32_16x16x128_f8f6f4 v[84:87], v[16:23], v[184:191], v[84:87], v202, v202 op_sel_hi:[0,0,0]
	v_mfma_scale_f32_16x16x128_f8f6f4 v[80:83], v[24:31], v[184:191], v[80:83], v202, v202 op_sel_hi:[0,0,0]
	v_mfma_scale_f32_16x16x128_f8f6f4 v[68:71], v[16:23], v[192:199], v[68:71], v202, v202 op_sel_hi:[0,0,0]
	v_mfma_scale_f32_16x16x128_f8f6f4 v[64:67], v[24:31], v[192:199], v[64:67], v202, v202 op_sel_hi:[0,0,0]
	v_mfma_scale_f32_16x16x128_f8f6f4 v[52:55], v[16:23], v[210:217], v[52:55], v202, v202 op_sel_hi:[0,0,0]
	v_mfma_scale_f32_16x16x128_f8f6f4 v[48:51], v[24:31], v[210:217], v[48:51], v202, v202 op_sel_hi:[0,0,0]
	v_mfma_scale_f32_16x16x128_f8f6f4 v[36:39], v[16:23], v[218:225], v[36:39], v202, v202 op_sel_hi:[0,0,0]
	v_mfma_scale_f32_16x16x128_f8f6f4 v[32:35], v[24:31], v[218:225], v[32:35], v202, v202 op_sel_hi:[0,0,0]
	s_barrier
	s_setprio 0
	s_cbranch_scc0 .LBB0_2516
	s_nop 15
	s_nop 15
	s_nop 15
	s_nop 15
	s_nop 15
	s_and_b64 vcc, exec, s[10:11]
	s_cbranch_vccz .LBB0_2519
	s_barrier
